# all v_pk_fma_f32 split into two v_fma_f32 (bit-identical; packed fma issues slower than two scalar fmas)
# speedup vs baseline: 1.0040x; 1.0027x over previous
; __device__ __forceinline__ unsigned pk2(float lo, float hi) { return f2bf(lo) | (f2bf(hi) << 16); }
; __global__ void __launch_bounds__(NWAVES * 64, 2) mk_fwd(Args args) {
;     ...
;         for (int m = gw; m < MEMROWS; m += NGW) {
;             const f32x4* xr = (const f32x4*)(args.in[1] + (size_t)m * D) + lane; const f32x4* gr = (const f32x4*)(args.in[18]) + lane; float s = 0.f; f32x4 v[4];
; #pragma unroll
;             for (int j = 0; j < 4; ++j) { v[j] = xr[64 * j]; s += (v[j].x * v[j].x + v[j].y * v[j].y) + (v[j].z * v[j].z + v[j].w * v[j].w); }
;             s = wave_sum(s); const float rs = 1.0f / sqrtf(s * (1.0f / D) + 1e-6f);
;             v2u* o8 = (v2u*)(MEMN + (size_t)m * D) + lane;
; #pragma unroll
;             for (int j = 0; j < 4; ++j) { const f32x4 g = gr[64 * j]; v2u o; o.x = pk2(v[j].x * rs * g.x, v[j].y * rs * g.y); o.y = pk2(v[j].z * rs * g.z, v[j].w * rs * g.w); o8[64 * j] = o; }
.LBB0_107:
	global_load_dwordx4 v[22:25], v[10:11], off offset:-3072
	global_load_dwordx4 v[26:29], v[10:11], off offset:-2048
	global_load_dwordx4 v[2:5], v[10:11], off
	global_load_dwordx4 v[30:33], v[10:11], off offset:-1024
	global_load_dwordx4 v[34:37], v[6:7], off
	s_add_i32 s4, s4, s80
	v_lshl_add_u64 v[10:11], v[10:11], 0, s[10:11]
	s_cmpk_gt_i32 s4, 0x7ff
	s_waitcnt vmcnt(4)
	v_pk_mul_f32 v[38:39], v[24:25], v[24:25]
	v_pk_mul_f32 v[40:41], v[22:23], v[22:23]
	s_waitcnt vmcnt(3)
	v_pk_mul_f32 v[42:43], v[28:29], v[28:29]
	v_pk_mul_f32 v[44:45], v[26:27], v[26:27]
	v_mov_b32_e32 v50, v22
	s_waitcnt lgkmcnt(0)
	v_mov_b32_e32 v51, v24
	s_waitcnt vmcnt(0)
	v_mov_b32_e32 v52, v34
	v_mov_b32_e32 v53, v36
	v_mov_b32_e32 v24, v23
	v_mov_b32_e32 v36, v35
	v_pk_mov_b32 v[22:23], v[40:41], v[38:39] op_sel:[1,0]
	v_mov_b32_e32 v41, v39
	v_pk_mov_b32 v[34:35], v[44:45], v[42:43] op_sel:[1,0]
	v_mov_b32_e32 v45, v43
	v_mul_f32_e32 v47, v3, v3
	v_mul_f32_e32 v49, v4, v4
	v_mul_f32_e32 v46, v31, v31
	v_mul_f32_e32 v48, v33, v33
	v_pk_add_f32 v[22:23], v[22:23], v[40:41]
	v_pk_add_f32 v[34:35], v[34:35], v[44:45]
	v_mul_f32_e32 v21, v2, v2
	v_mul_f32_e32 v54, v5, v5
	v_fma_f32 v38, v30, v30, v46
	v_fma_f32 v39, v31, v31, v46
	v_fma_f32 v42, v32, v32, v48
	v_fma_f32 v43, v33, v33, v48
	v_pk_add_f32 v[22:23], v[22:23], v[22:23] op_sel:[0,1] op_sel_hi:[1,0]
	v_pk_add_f32 v[34:35], v[34:35], v[34:35] op_sel:[0,1] op_sel_hi:[1,0]
	v_mov_b32_e32 v39, v49
	v_mov_b32_e32 v43, v54
	v_mov_b32_e32 v23, v21
	v_mov_b32_e32 v35, v47
	v_pk_add_f32 v[38:39], v[38:39], v[42:43]
	v_pk_add_f32 v[22:23], v[22:23], v[34:35]
	s_nop 0
	v_pk_add_f32 v[22:23], v[22:23], v[38:39]
	s_nop 0
	v_add_f32_e32 v21, v22, v23
	ds_bpermute_b32 v22, v12, v21
	s_waitcnt lgkmcnt(0)
	v_add_f32_e32 v21, v21, v22
	ds_bpermute_b32 v22, v13, v21
	s_waitcnt lgkmcnt(0)
	v_add_f32_e32 v21, v21, v22
	ds_bpermute_b32 v22, v14, v21
	s_waitcnt lgkmcnt(0)
	v_add_f32_e32 v21, v21, v22
	ds_bpermute_b32 v22, v15, v21
	s_waitcnt lgkmcnt(0)
	v_add_f32_e32 v21, v21, v22
	ds_bpermute_b32 v22, v16, v21
	s_waitcnt lgkmcnt(0)
	v_add_f32_e32 v21, v21, v22
	ds_bpermute_b32 v22, v17, v21
	s_waitcnt lgkmcnt(0)
	v_add_f32_e32 v21, v21, v22
	v_fmamk_f32 v21, v21, 0x3a800000, v18
	v_mul_f32_e32 v22, 0x4f800000, v21
	v_cmp_gt_f32_e32 vcc, s3, v21
	s_nop 1
	v_cndmask_b32_e32 v21, v21, v22, vcc
	v_sqrt_f32_e32 v22, v21
	s_nop 0
	v_add_u32_e32 v23, -1, v22
	v_add_u32_e32 v34, 1, v22
	v_fma_f32 v35, -v23, v22, v21
	v_fma_f32 v38, -v34, v22, v21
	v_cmp_ge_f32_e64 s[0:1], 0, v35
	s_nop 1
	v_cndmask_b32_e64 v22, v22, v23, s[0:1]
	v_cmp_lt_f32_e64 s[0:1], 0, v38
	s_nop 1
	v_cndmask_b32_e64 v22, v22, v34, s[0:1]
	v_mul_f32_e32 v23, 0x37800000, v22
	v_cndmask_b32_e32 v22, v22, v23, vcc
	v_cmp_class_f32_e32 vcc, v21, v19
	s_nop 1
	v_cndmask_b32_e32 v21, v22, v21, vcc
	v_div_scale_f32 v22, s[0:1], v21, v21, 1.0
	v_rcp_f32_e32 v34, v22
	v_div_scale_f32 v23, vcc, 1.0, v21, 1.0
	v_fma_f32 v35, -v22, v34, 1.0
	v_fmac_f32_e32 v34, v35, v34
	v_mul_f32_e32 v35, v23, v34
	v_fma_f32 v38, -v22, v35, v23
	v_fmac_f32_e32 v35, v38, v34
	v_fma_f32 v22, -v22, v35, v23
	v_div_fmas_f32 v22, v22, v34, v35
	v_div_fixup_f32 v34, v22, v21, 1.0
	v_pk_mul_f32 v[22:23], v[34:35], v[50:51] op_sel_hi:[0,1]
	v_pk_mul_f32 v[24:25], v[34:35], v[24:25] op_sel_hi:[0,1]
	v_pk_mul_f32 v[22:23], v[22:23], v[52:53]
	v_pk_mul_f32 v[24:25], v[24:25], v[36:37]
	v_and_b32_sdwa v21, v23, v20 dst_sel:DWORD dst_unused:UNUSED_PAD src0_sel:WORD_1 src1_sel:DWORD
	v_and_b32_sdwa v36, v25, v20 dst_sel:DWORD dst_unused:UNUSED_PAD src0_sel:WORD_1 src1_sel:DWORD
	v_and_b32_sdwa v37, v24, v20 dst_sel:DWORD dst_unused:UNUSED_PAD src0_sel:WORD_1 src1_sel:DWORD
	v_and_b32_sdwa v35, v22, v20 dst_sel:DWORD dst_unused:UNUSED_PAD src0_sel:WORD_1 src1_sel:DWORD
	v_add3_u32 v21, v23, v21, s5
	v_add3_u32 v23, v25, v36, s5
	v_add3_u32 v24, v24, v37, s5
	v_add3_u32 v22, v22, v35, s5
	v_and_b32_e32 v23, 0xffff0000, v23
	v_and_b32_e32 v24, 0xffff0000, v24
	v_or_b32_sdwa v23, v23, v21 dst_sel:DWORD dst_unused:UNUSED_PAD src0_sel:DWORD src1_sel:WORD_1
	v_or_b32_sdwa v22, v24, v22 dst_sel:DWORD dst_unused:UNUSED_PAD src0_sel:DWORD src1_sel:WORD_1
	global_store_dwordx2 v[8:9], v[22:23], off
	global_load_dwordx4 v[22:25], v[6:7], off offset:1024
	v_mov_b32_e32 v36, v26
	v_mov_b32_e32 v37, v28
	v_mov_b32_e32 v28, v27
	v_pk_mul_f32 v[26:27], v[34:35], v[36:37] op_sel_hi:[0,1]
	v_pk_mul_f32 v[28:29], v[34:35], v[28:29] op_sel_hi:[0,1]
	s_waitcnt vmcnt(0)
; __device__ __forceinline__ unsigned pk2(float lo, float hi) { return f2bf(lo) | (f2bf(hi) << 16); }
; __global__ void __launch_bounds__(NWAVES * 64, 2) mk_fwd(Args args) {
;     ...
;             v2u* o8 = (v2u*)(MEMN + (size_t)m * D) + lane;
; #pragma unroll
;             for (int j = 0; j < 4; ++j) { const f32x4 g = gr[64 * j]; v2u o; o.x = pk2(v[j].x * rs * g.x, v[j].y * rs * g.y); o.y = pk2(v[j].z * rs * g.z, v[j].w * rs * g.w); o8[64 * j] = o; }
	v_mov_b32_e32 v36, v22
	v_mov_b32_e32 v37, v24
	v_mov_b32_e32 v24, v23
	v_pk_mul_f32 v[22:23], v[26:27], v[36:37]
	v_pk_mul_f32 v[24:25], v[28:29], v[24:25]
	v_and_b32_sdwa v21, v23, v20 dst_sel:DWORD dst_unused:UNUSED_PAD src0_sel:WORD_1 src1_sel:DWORD
	v_and_b32_sdwa v27, v25, v20 dst_sel:DWORD dst_unused:UNUSED_PAD src0_sel:WORD_1 src1_sel:DWORD
	v_and_b32_sdwa v28, v24, v20 dst_sel:DWORD dst_unused:UNUSED_PAD src0_sel:WORD_1 src1_sel:DWORD
	v_and_b32_sdwa v26, v22, v20 dst_sel:DWORD dst_unused:UNUSED_PAD src0_sel:WORD_1 src1_sel:DWORD
	v_add3_u32 v21, v23, v21, s5
	v_add3_u32 v23, v25, v27, s5
	v_add3_u32 v24, v24, v28, s5
	v_add3_u32 v22, v22, v26, s5
	v_and_b32_e32 v23, 0xffff0000, v23
	v_and_b32_e32 v24, 0xffff0000, v24
	v_or_b32_sdwa v23, v23, v21 dst_sel:DWORD dst_unused:UNUSED_PAD src0_sel:DWORD src1_sel:WORD_1
	v_or_b32_sdwa v22, v24, v22 dst_sel:DWORD dst_unused:UNUSED_PAD src0_sel:DWORD src1_sel:WORD_1
	global_store_dwordx2 v[8:9], v[22:23], off offset:512
	global_load_dwordx4 v[22:25], v[6:7], off offset:2048
	v_mov_b32_e32 v26, v30
	v_mov_b32_e32 v27, v32
	v_mov_b32_e32 v32, v31
	v_pk_mul_f32 v[26:27], v[34:35], v[26:27] op_sel_hi:[0,1]
	v_pk_mul_f32 v[28:29], v[34:35], v[32:33] op_sel_hi:[0,1]
	s_waitcnt vmcnt(0)
	v_mov_b32_e32 v30, v22
	v_mov_b32_e32 v31, v24
	v_mov_b32_e32 v24, v23
	v_pk_mul_f32 v[22:23], v[26:27], v[30:31]
	v_pk_mul_f32 v[24:25], v[28:29], v[24:25]
	v_and_b32_sdwa v21, v23, v20 dst_sel:DWORD dst_unused:UNUSED_PAD src0_sel:WORD_1 src1_sel:DWORD
	v_and_b32_sdwa v27, v25, v20 dst_sel:DWORD dst_unused:UNUSED_PAD src0_sel:WORD_1 src1_sel:DWORD
	v_and_b32_sdwa v28, v24, v20 dst_sel:DWORD dst_unused:UNUSED_PAD src0_sel:WORD_1 src1_sel:DWORD
	v_and_b32_sdwa v26, v22, v20 dst_sel:DWORD dst_unused:UNUSED_PAD src0_sel:WORD_1 src1_sel:DWORD
	v_add3_u32 v21, v23, v21, s5
	v_add3_u32 v23, v25, v27, s5
	v_add3_u32 v24, v24, v28, s5
	v_add3_u32 v22, v22, v26, s5
	v_and_b32_e32 v23, 0xffff0000, v23
	v_and_b32_e32 v24, 0xffff0000, v24
	v_or_b32_sdwa v23, v23, v21 dst_sel:DWORD dst_unused:UNUSED_PAD src0_sel:DWORD src1_sel:WORD_1
	v_or_b32_sdwa v22, v24, v22 dst_sel:DWORD dst_unused:UNUSED_PAD src0_sel:DWORD src1_sel:WORD_1
	global_store_dwordx2 v[8:9], v[22:23], off offset:1024
	global_load_dwordx4 v[22:25], v[6:7], off offset:3072
	v_mov_b32_e32 v26, v2
	v_mov_b32_e32 v27, v4
	v_mov_b32_e32 v4, v3
	v_pk_mul_f32 v[2:3], v[34:35], v[26:27] op_sel_hi:[0,1]
	v_pk_mul_f32 v[4:5], v[34:35], v[4:5] op_sel_hi:[0,1]
	s_waitcnt vmcnt(0)
	v_mov_b32_e32 v27, v24
	v_mov_b32_e32 v24, v23
	v_mov_b32_e32 v26, v22
	v_pk_mul_f32 v[4:5], v[4:5], v[24:25]
	v_pk_mul_f32 v[2:3], v[2:3], v[26:27]
	v_and_b32_sdwa v23, v5, v20 dst_sel:DWORD dst_unused:UNUSED_PAD src0_sel:WORD_1 src1_sel:DWORD
	v_and_b32_sdwa v24, v4, v20 dst_sel:DWORD dst_unused:UNUSED_PAD src0_sel:WORD_1 src1_sel:DWORD
	v_and_b32_sdwa v21, v3, v20 dst_sel:DWORD dst_unused:UNUSED_PAD src0_sel:WORD_1 src1_sel:DWORD
	v_and_b32_sdwa v22, v2, v20 dst_sel:DWORD dst_unused:UNUSED_PAD src0_sel:WORD_1 src1_sel:DWORD
	v_add3_u32 v5, v5, v23, s5
	v_add3_u32 v4, v4, v24, s5
	v_add3_u32 v2, v2, v22, s5
	v_add3_u32 v3, v3, v21, s5
	v_and_b32_e32 v5, 0xffff0000, v5
	v_and_b32_e32 v4, 0xffff0000, v4
	v_or_b32_sdwa v3, v5, v3 dst_sel:DWORD dst_unused:UNUSED_PAD src0_sel:DWORD src1_sel:WORD_1
	v_or_b32_sdwa v2, v4, v2 dst_sel:DWORD dst_unused:UNUSED_PAD src0_sel:DWORD src1_sel:WORD_1
	global_store_dwordx2 v[8:9], v[2:3], off offset:1536
	v_lshl_add_u64 v[8:9], v[8:9], 0, s[8:9]
	s_cbranch_scc0 .LBB0_107

; __device__ __forceinline__ unsigned cvtpk(float lo, float hi) { f32x2v_ v = {lo, hi}; bf16x2v_ b = __builtin_convertvector(v, bf16x2v_); return __builtin_bit_cast(unsigned, b); }
;     __device__ __forceinline__ void operator()(const f32x4 (&acc)[2][2][4][2], const Unit& u, int wr, int wc, int fr, int fq) const {
;     ...
;                     if (xin32) { const float* p = xin32 + off + bj * HALF; a0 = *(const f32x4*)p; a1 = *(const f32x4*)(p + 4); }
;                     else { const u32x4 w = *(const u32x4*)(xb + off + bj * HALF);
;                         a0 = (f32x4){__uint_as_float(w.x << 16), __uint_as_float(w.x & 0xffff0000u), __uint_as_float(w.y << 16), __uint_as_float(w.y & 0xffff0000u)};
;                         a1 = (f32x4){__uint_as_float(w.z << 16), __uint_as_float(w.z & 0xffff0000u), __uint_as_float(w.w << 16), __uint_as_float(w.w & 0xffff0000u)}; }
;                     const f32x4 v0 = a0 + acc[ai][bj][m][0] * alpha, v1 = a1 + acc[ai][bj][m][1] * alpha;
;                     u32x4 w; w.x = cvtpk(v0[0], v0[1]); w.y = cvtpk(v0[2], v0[3]); w.z = cvtpk(v1[0], v1[1]); w.w = cvtpk(v1[2], v1[3]);
;                     *(u32x4*)(xb + off + bj * HALF) = w;
.LBB0_275:
	s_waitcnt vmcnt(0)
	v_fma_f32 v130, v126, 0.5, v130
	v_fma_f32 v131, v127, 0.5, v131
	v_fma_f32 v160, v124, 0.5, v128
	v_fma_f32 v161, v125, 0.5, v129
	v_fma_f32 v128, v122, 0.5, v134
	v_fma_f32 v129, v123, 0.5, v135
	v_fma_f32 v132, v120, 0.5, v132
	v_fma_f32 v133, v121, 0.5, v133
	v_cvt_pk_bf16_f32 v120, v160, v161
	v_cvt_pk_bf16_f32 v121, v130, v131
	v_cvt_pk_bf16_f32 v122, v132, v133
	v_cvt_pk_bf16_f32 v123, v128, v129
	s_and_b64 vcc, exec, s[10:11]
	global_store_dwordx4 v[156:157], v[120:123], off
	s_cbranch_vccnz .LBB0_340
	global_load_dwordx4 v[124:127], v[158:159], off offset:528
	global_load_dwordx4 v[120:123], v[158:159], off offset:512
	s_cbranch_execnz .LBB0_278

; __device__ __forceinline__ unsigned cvtpk(float lo, float hi) { f32x2v_ v = {lo, hi}; bf16x2v_ b = __builtin_convertvector(v, bf16x2v_); return __builtin_bit_cast(unsigned, b); }
; __device__ __forceinline__ void fx_add(float* p, size_t idx, float s) { atomicAdd((unsigned long long*)p + idx, (unsigned long long)(long long)(s * 4294967296.0f)); }
;     __device__ __forceinline__ void operator()(const f32x4 (&acc)[2][2][4][2], const Unit& u, int wr, int wc, int fr, int fq) const {
;     ...
;                     const f32x4 v0 = a0 + acc[ai][bj][m][0] * alpha, v1 = a1 + acc[ai][bj][m][1] * alpha;
;                     u32x4 w; w.x = cvtpk(v0[0], v0[1]); w.y = cvtpk(v0[2], v0[3]); w.z = cvtpk(v1[0], v1[1]); w.w = cvtpk(v1[2], v1[3]);
;                     *(u32x4*)(xb + off + bj * HALF) = w;
;                     s += (v0[0] * v0[0] + v0[1] * v0[1]) + (v0[2] * v0[2] + v0[3] * v0[3]) + (v1[0] * v1[0] + v1[1] * v1[1]) + (v1[2] * v1[2] + v1[3] * v1[3]); }
;                 s += __shfl_xor(s, 16); s += __shfl_xor(s, 32);
;                 if (fq == 0) fx_add(ssout, row, s); }
.LBB0_278:
	v_mul_f32_e32 v134, v161, v161
	v_mul_f32_e32 v131, v131, v131
	v_fmac_f32_e32 v134, v160, v160
	v_fmac_f32_e32 v131, v130, v130
	s_waitcnt vmcnt(0)
	v_fma_f32 v118, v118, 0.5, v122
	v_fma_f32 v119, v119, 0.5, v123
	v_fma_f32 v116, v116, 0.5, v120
	v_fma_f32 v117, v117, 0.5, v121
	v_add_f32_e32 v130, v134, v131
	v_mul_f32_e32 v131, v133, v133
	v_fma_f32 v122, v112, 0.5, v124
	v_fma_f32 v123, v113, 0.5, v125
	v_mul_f32_e32 v112, v117, v117
	v_mul_f32_e32 v113, v119, v119
	v_fmac_f32_e32 v131, v132, v132
	v_mul_f32_e32 v129, v129, v129
	v_fmac_f32_e32 v112, v116, v116
	v_fmac_f32_e32 v113, v118, v118
	v_add_f32_e32 v130, v131, v130
	v_fmac_f32_e32 v129, v128, v128
	v_add_f32_e32 v112, v112, v113
	v_mul_f32_e32 v113, v123, v123
	v_add_f32_e32 v129, v129, v130
	v_and_b32_e32 v130, 64, v170
	v_fma_f32 v120, v114, 0.5, v126
	v_fma_f32 v121, v115, 0.5, v127
	v_fmac_f32_e32 v113, v122, v122
	v_xor_b32_e32 v128, 16, v170
	v_add_u32_e32 v130, 64, v130
	v_add_f32_e32 v112, v113, v112
	v_mul_f32_e32 v113, v121, v121
	v_cmp_lt_i32_e32 vcc, v128, v130
	v_fmac_f32_e32 v113, v120, v120
	v_add_f32_e32 v112, v113, v112
	v_cndmask_b32_e32 v128, v170, v128, vcc
	v_lshlrev_b32_e32 v128, 2, v128
	v_add_f32_e32 v112, v129, v112
	ds_bpermute_b32 v113, v128, v112
	v_xor_b32_e32 v131, 32, v170
	v_cmp_lt_i32_e32 vcc, v131, v130
	v_cvt_pk_bf16_f32 v115, v118, v119
	s_waitcnt lgkmcnt(0)
	v_add_f32_e32 v112, v112, v113
	v_cndmask_b32_e32 v114, v170, v131, vcc
	v_lshlrev_b32_e32 v129, 2, v114
	ds_bpermute_b32 v113, v129, v112
	v_cvt_pk_bf16_f32 v114, v116, v117
	v_cvt_pk_bf16_f32 v116, v122, v123
	v_cvt_pk_bf16_f32 v117, v120, v121
	global_store_dwordx4 v[156:157], v[114:117], off offset:256
	s_and_saveexec_b64 s[50:51], s[6:7]
	s_cbranch_execz .LBB0_280
	s_waitcnt lgkmcnt(0)
	v_add_f32_e32 v112, v112, v113
	v_mul_f32_e32 v112, 0x4f800000, v112
	v_trunc_f32_e32 v112, v112
	v_mul_f32_e64 v113, |v112|, s67
	v_floor_f32_e32 v113, v113
	v_fma_f32 v114, v113, s86, |v112|
	v_cvt_u32_f32_e32 v114, v114
	v_cvt_u32_f32_e32 v113, v113
	v_ashrrev_i32_e32 v115, 31, v112
	v_xor_b32_e32 v112, v114, v115
	v_xor_b32_e32 v113, v113, v115
	v_sub_co_u32_e32 v112, vcc, v112, v115
	s_nop 1
	v_subb_co_u32_e32 v113, vcc, v113, v115, vcc
	v_lshl_add_u64 v[114:115], v[154:155], 3, s[24:25]
	global_atomic_add_x2 v[114:115], v[112:113], off

; __device__ __forceinline__ unsigned cvtpk(float lo, float hi) { f32x2v_ v = {lo, hi}; bf16x2v_ b = __builtin_convertvector(v, bf16x2v_); return __builtin_bit_cast(unsigned, b); }
;     __device__ __forceinline__ void operator()(const f32x4 (&acc)[2][2][4][2], const Unit& u, int wr, int wc, int fr, int fq) const {
;     ...
;                     if (xin32) { const float* p = xin32 + off + bj * HALF; a0 = *(const f32x4*)p; a1 = *(const f32x4*)(p + 4); }
;                     else { const u32x4 w = *(const u32x4*)(xb + off + bj * HALF);
;                         a0 = (f32x4){__uint_as_float(w.x << 16), __uint_as_float(w.x & 0xffff0000u), __uint_as_float(w.y << 16), __uint_as_float(w.y & 0xffff0000u)};
;                         a1 = (f32x4){__uint_as_float(w.z << 16), __uint_as_float(w.z & 0xffff0000u), __uint_as_float(w.w << 16), __uint_as_float(w.w & 0xffff0000u)}; }
;                     const f32x4 v0 = a0 + acc[ai][bj][m][0] * alpha, v1 = a1 + acc[ai][bj][m][1] * alpha;
;                     u32x4 w; w.x = cvtpk(v0[0], v0[1]); w.y = cvtpk(v0[2], v0[3]); w.z = cvtpk(v1[0], v1[1]); w.w = cvtpk(v1[2], v1[3]);
;                     *(u32x4*)(xb + off + bj * HALF) = w;
.LBB0_283:
	s_waitcnt vmcnt(0)
	v_fma_f32 v114, v110, 0.5, v114
	v_fma_f32 v115, v111, 0.5, v115
	v_fma_f32 v126, v108, 0.5, v112
	v_fma_f32 v127, v109, 0.5, v113
	v_fma_f32 v112, v106, 0.5, v118
	v_fma_f32 v113, v107, 0.5, v119
	v_fma_f32 v116, v104, 0.5, v116
	v_fma_f32 v117, v105, 0.5, v117
	v_cvt_pk_bf16_f32 v104, v126, v127
	v_cvt_pk_bf16_f32 v105, v114, v115
	v_cvt_pk_bf16_f32 v106, v116, v117
	v_cvt_pk_bf16_f32 v107, v112, v113
	s_and_b64 vcc, exec, s[10:11]
	global_store_dwordx4 v[122:123], v[104:107], off
	s_cbranch_vccnz .LBB0_342
	global_load_dwordx4 v[108:111], v[124:125], off offset:528
	global_load_dwordx4 v[104:107], v[124:125], off offset:512
	s_cbranch_execnz .LBB0_286

; __device__ __forceinline__ void fx_add(float* p, size_t idx, float s) { atomicAdd((unsigned long long*)p + idx, (unsigned long long)(long long)(s * 4294967296.0f)); }
; __device__ __forceinline__ unsigned cvtpk(float lo, float hi) { f32x2v_ v = {lo, hi}; bf16x2v_ b = __builtin_convertvector(v, bf16x2v_); return __builtin_bit_cast(unsigned, b); }
;     __device__ __forceinline__ void operator()(const f32x4 (&acc)[2][2][4][2], const Unit& u, int wr, int wc, int fr, int fq) const {
;     ...
;             for (int m = 0; m < 4; ++m) { const int row = row0 + ai * HALF + m * 16; const size_t off = (size_t)row * 1024 + col0; float s = 0.f;
; #pragma unroll
;                 for (int bj = 0; bj < 2; ++bj) { f32x4 a0, a1;
;                     if (xin32) { const float* p = xin32 + off + bj * HALF; a0 = *(const f32x4*)p; a1 = *(const f32x4*)(p + 4); }
;                     else { const u32x4 w = *(const u32x4*)(xb + off + bj * HALF);
;                         a0 = (f32x4){__uint_as_float(w.x << 16), __uint_as_float(w.x & 0xffff0000u), __uint_as_float(w.y << 16), __uint_as_float(w.y & 0xffff0000u)};
;                         a1 = (f32x4){__uint_as_float(w.z << 16), __uint_as_float(w.z & 0xffff0000u), __uint_as_float(w.w << 16), __uint_as_float(w.w & 0xffff0000u)}; }
;                     const f32x4 v0 = a0 + acc[ai][bj][m][0] * alpha, v1 = a1 + acc[ai][bj][m][1] * alpha;
;                     u32x4 w; w.x = cvtpk(v0[0], v0[1]); w.y = cvtpk(v0[2], v0[3]); w.z = cvtpk(v1[0], v1[1]); w.w = cvtpk(v1[2], v1[3]);
;                     *(u32x4*)(xb + off + bj * HALF) = w;
;                     s += (v0[0] * v0[0] + v0[1] * v0[1]) + (v0[2] * v0[2] + v0[3] * v0[3]) + (v1[0] * v1[0] + v1[1] * v1[1]) + (v1[2] * v1[2] + v1[3] * v1[3]); }
;                 s += __shfl_xor(s, 16); s += __shfl_xor(s, 32);
;                 if (fq == 0) fx_add(ssout, row, s); }
.LBB0_286:
	s_waitcnt vmcnt(0)
	v_fma_f32 v102, v102, 0.5, v106
	v_fma_f32 v103, v103, 0.5, v107
	v_fma_f32 v100, v100, 0.5, v104
	v_fma_f32 v101, v101, 0.5, v105
	v_fma_f32 v106, v96, 0.5, v108
	v_fma_f32 v107, v97, 0.5, v109
	v_mul_f32_e32 v96, v101, v101
	v_mul_f32_e32 v97, v103, v103
	v_mul_f32_e32 v118, v127, v127
	v_mul_f32_e32 v115, v115, v115
	v_fmac_f32_e32 v96, v100, v100
	v_fmac_f32_e32 v97, v102, v102
	v_fmac_f32_e32 v118, v126, v126
	v_fmac_f32_e32 v115, v114, v114
	v_add_f32_e32 v96, v96, v97
	v_mul_f32_e32 v97, v107, v107
	v_add_f32_e32 v114, v118, v115
	v_mul_f32_e32 v115, v117, v117
	v_fma_f32 v104, v98, 0.5, v110
	v_fma_f32 v105, v99, 0.5, v111
	v_fmac_f32_e32 v97, v106, v106
	v_fmac_f32_e32 v115, v116, v116
	v_mul_f32_e32 v113, v113, v113
	v_add_f32_e32 v96, v97, v96
	v_mul_f32_e32 v97, v105, v105
	v_add_f32_e32 v114, v115, v114
	v_fmac_f32_e32 v113, v112, v112
	v_fmac_f32_e32 v97, v104, v104
	v_add_f32_e32 v112, v113, v114
	v_add_f32_e32 v96, v97, v96
	v_add_f32_e32 v96, v112, v96
	ds_bpermute_b32 v97, v128, v96
	v_cvt_pk_bf16_f32 v98, v100, v101
	v_cvt_pk_bf16_f32 v99, v102, v103
	v_cvt_pk_bf16_f32 v100, v106, v107
	v_cvt_pk_bf16_f32 v101, v104, v105
	s_waitcnt lgkmcnt(0)
	v_add_f32_e32 v96, v96, v97
	ds_bpermute_b32 v97, v129, v96
	global_store_dwordx4 v[122:123], v[98:101], off offset:256
	s_and_saveexec_b64 s[50:51], s[6:7]
	s_cbranch_execz .LBB0_288
	s_waitcnt lgkmcnt(0)
	v_add_f32_e32 v96, v96, v97
	v_mul_f32_e32 v96, 0x4f800000, v96
	v_trunc_f32_e32 v96, v96
	v_mul_f32_e64 v97, |v96|, s67
	v_floor_f32_e32 v97, v97
	v_fma_f32 v98, v97, s86, |v96|
	v_cvt_u32_f32_e32 v98, v98
	v_cvt_u32_f32_e32 v97, v97
	v_ashrrev_i32_e32 v99, 31, v96
	v_xor_b32_e32 v96, v98, v99
	v_xor_b32_e32 v97, v97, v99
	v_sub_co_u32_e32 v96, vcc, v96, v99
	s_nop 1
	v_subb_co_u32_e32 v97, vcc, v97, v99, vcc
	v_lshl_add_u64 v[98:99], v[120:121], 3, s[24:25]
	global_atomic_add_x2 v[98:99], v[96:97], off

; __device__ __forceinline__ void fx_add(float* p, size_t idx, float s) { atomicAdd((unsigned long long*)p + idx, (unsigned long long)(long long)(s * 4294967296.0f)); }
; __device__ __forceinline__ unsigned cvtpk(float lo, float hi) { f32x2v_ v = {lo, hi}; bf16x2v_ b = __builtin_convertvector(v, bf16x2v_); return __builtin_bit_cast(unsigned, b); }
;     __device__ __forceinline__ void operator()(const f32x4 (&acc)[2][2][4][2], const Unit& u, int wr, int wc, int fr, int fq) const {
;     ...
;             for (int m = 0; m < 4; ++m) { const int row = row0 + ai * HALF + m * 16; const size_t off = (size_t)row * 1024 + col0; float s = 0.f;
; #pragma unroll
;                 for (int bj = 0; bj < 2; ++bj) { f32x4 a0, a1;
;                     if (xin32) { const float* p = xin32 + off + bj * HALF; a0 = *(const f32x4*)p; a1 = *(const f32x4*)(p + 4); }
;                     else { const u32x4 w = *(const u32x4*)(xb + off + bj * HALF);
;                         a0 = (f32x4){__uint_as_float(w.x << 16), __uint_as_float(w.x & 0xffff0000u), __uint_as_float(w.y << 16), __uint_as_float(w.y & 0xffff0000u)};
;                         a1 = (f32x4){__uint_as_float(w.z << 16), __uint_as_float(w.z & 0xffff0000u), __uint_as_float(w.w << 16), __uint_as_float(w.w & 0xffff0000u)}; }
;                     const f32x4 v0 = a0 + acc[ai][bj][m][0] * alpha, v1 = a1 + acc[ai][bj][m][1] * alpha;
;                     u32x4 w; w.x = cvtpk(v0[0], v0[1]); w.y = cvtpk(v0[2], v0[3]); w.z = cvtpk(v1[0], v1[1]); w.w = cvtpk(v1[2], v1[3]);
;                     *(u32x4*)(xb + off + bj * HALF) = w;
;                     s += (v0[0] * v0[0] + v0[1] * v0[1]) + (v0[2] * v0[2] + v0[3] * v0[3]) + (v1[0] * v1[0] + v1[1] * v1[1]) + (v1[2] * v1[2] + v1[3] * v1[3]); }
;                 s += __shfl_xor(s, 16); s += __shfl_xor(s, 32);
;                 if (fq == 0) fx_add(ssout, row, s); }
.LBB0_291:
	s_waitcnt vmcnt(0)
	v_fma_f32 v98, v94, 0.5, v98
	v_fma_f32 v99, v95, 0.5, v99
	v_fma_f32 v110, v92, 0.5, v96
	v_fma_f32 v111, v93, 0.5, v97
	v_fma_f32 v96, v90, 0.5, v102
	v_fma_f32 v97, v91, 0.5, v103
	v_fma_f32 v100, v88, 0.5, v100
	v_fma_f32 v101, v89, 0.5, v101
	v_cvt_pk_bf16_f32 v88, v110, v111
	v_cvt_pk_bf16_f32 v89, v98, v99
	v_cvt_pk_bf16_f32 v90, v100, v101
	v_cvt_pk_bf16_f32 v91, v96, v97
	s_and_b64 vcc, exec, s[10:11]
	global_store_dwordx4 v[106:107], v[88:91], off
	s_cbranch_vccnz .LBB0_344
	global_load_dwordx4 v[92:95], v[108:109], off offset:528
	global_load_dwordx4 v[88:91], v[108:109], off offset:512
	s_cbranch_execnz .LBB0_294

; __device__ __forceinline__ void fx_add(float* p, size_t idx, float s) { atomicAdd((unsigned long long*)p + idx, (unsigned long long)(long long)(s * 4294967296.0f)); }
; __device__ __forceinline__ unsigned cvtpk(float lo, float hi) { f32x2v_ v = {lo, hi}; bf16x2v_ b = __builtin_convertvector(v, bf16x2v_); return __builtin_bit_cast(unsigned, b); }
;     __device__ __forceinline__ void operator()(const f32x4 (&acc)[2][2][4][2], const Unit& u, int wr, int wc, int fr, int fq) const {
;     ...
;             for (int m = 0; m < 4; ++m) { const int row = row0 + ai * HALF + m * 16; const size_t off = (size_t)row * 1024 + col0; float s = 0.f;
; #pragma unroll
;                 for (int bj = 0; bj < 2; ++bj) { f32x4 a0, a1;
;                     if (xin32) { const float* p = xin32 + off + bj * HALF; a0 = *(const f32x4*)p; a1 = *(const f32x4*)(p + 4); }
;                     else { const u32x4 w = *(const u32x4*)(xb + off + bj * HALF);
;                         a0 = (f32x4){__uint_as_float(w.x << 16), __uint_as_float(w.x & 0xffff0000u), __uint_as_float(w.y << 16), __uint_as_float(w.y & 0xffff0000u)};
;                         a1 = (f32x4){__uint_as_float(w.z << 16), __uint_as_float(w.z & 0xffff0000u), __uint_as_float(w.w << 16), __uint_as_float(w.w & 0xffff0000u)}; }
;                     const f32x4 v0 = a0 + acc[ai][bj][m][0] * alpha, v1 = a1 + acc[ai][bj][m][1] * alpha;
;                     u32x4 w; w.x = cvtpk(v0[0], v0[1]); w.y = cvtpk(v0[2], v0[3]); w.z = cvtpk(v1[0], v1[1]); w.w = cvtpk(v1[2], v1[3]);
;                     *(u32x4*)(xb + off + bj * HALF) = w;
;                     s += (v0[0] * v0[0] + v0[1] * v0[1]) + (v0[2] * v0[2] + v0[3] * v0[3]) + (v1[0] * v1[0] + v1[1] * v1[1]) + (v1[2] * v1[2] + v1[3] * v1[3]); }
;                 s += __shfl_xor(s, 16); s += __shfl_xor(s, 32);
;                 if (fq == 0) fx_add(ssout, row, s); }
.LBB0_294:
	s_waitcnt vmcnt(0)
	v_fma_f32 v86, v86, 0.5, v90
	v_fma_f32 v87, v87, 0.5, v91
	v_fma_f32 v84, v84, 0.5, v88
	v_fma_f32 v85, v85, 0.5, v89
	v_fma_f32 v90, v80, 0.5, v92
	v_fma_f32 v91, v81, 0.5, v93
	v_mul_f32_e32 v80, v85, v85
	v_mul_f32_e32 v81, v87, v87
	v_mul_f32_e32 v102, v111, v111
	v_mul_f32_e32 v99, v99, v99
	v_fmac_f32_e32 v80, v84, v84
	v_fmac_f32_e32 v81, v86, v86
	v_fmac_f32_e32 v102, v110, v110
	v_fmac_f32_e32 v99, v98, v98
	v_add_f32_e32 v80, v80, v81
	v_mul_f32_e32 v81, v91, v91
	v_add_f32_e32 v98, v102, v99
	v_mul_f32_e32 v99, v101, v101
	v_fma_f32 v88, v82, 0.5, v94
	v_fma_f32 v89, v83, 0.5, v95
	v_fmac_f32_e32 v81, v90, v90
	v_fmac_f32_e32 v99, v100, v100
	v_mul_f32_e32 v97, v97, v97
	v_add_f32_e32 v80, v81, v80
	v_mul_f32_e32 v81, v89, v89
	v_add_f32_e32 v98, v99, v98
	v_fmac_f32_e32 v97, v96, v96
	v_fmac_f32_e32 v81, v88, v88
	v_add_f32_e32 v96, v97, v98
	v_add_f32_e32 v80, v81, v80
	v_add_f32_e32 v80, v96, v80
	ds_bpermute_b32 v81, v128, v80
	v_cvt_pk_bf16_f32 v82, v84, v85
	v_cvt_pk_bf16_f32 v83, v86, v87
	v_cvt_pk_bf16_f32 v84, v90, v91
	v_cvt_pk_bf16_f32 v85, v88, v89
	s_waitcnt lgkmcnt(0)
	v_add_f32_e32 v80, v80, v81
	ds_bpermute_b32 v81, v129, v80
	global_store_dwordx4 v[106:107], v[82:85], off offset:256
	s_and_saveexec_b64 s[50:51], s[6:7]
	s_cbranch_execz .LBB0_296
	s_waitcnt lgkmcnt(0)
	v_add_f32_e32 v80, v80, v81
	v_mul_f32_e32 v80, 0x4f800000, v80
	v_trunc_f32_e32 v80, v80
	v_mul_f32_e64 v81, |v80|, s67
	v_floor_f32_e32 v81, v81
	v_fma_f32 v82, v81, s86, |v80|
	v_cvt_u32_f32_e32 v82, v82
	v_cvt_u32_f32_e32 v81, v81
	v_ashrrev_i32_e32 v83, 31, v80
	v_xor_b32_e32 v80, v82, v83
	v_xor_b32_e32 v81, v81, v83
	v_sub_co_u32_e32 v80, vcc, v80, v83
	s_nop 1
	v_subb_co_u32_e32 v81, vcc, v81, v83, vcc
	v_lshl_add_u64 v[82:83], v[104:105], 3, s[24:25]
	global_atomic_add_x2 v[82:83], v[80:81], off

; __device__ __forceinline__ void fx_add(float* p, size_t idx, float s) { atomicAdd((unsigned long long*)p + idx, (unsigned long long)(long long)(s * 4294967296.0f)); }
; __device__ __forceinline__ unsigned cvtpk(float lo, float hi) { f32x2v_ v = {lo, hi}; bf16x2v_ b = __builtin_convertvector(v, bf16x2v_); return __builtin_bit_cast(unsigned, b); }
;     __device__ __forceinline__ void operator()(const f32x4 (&acc)[2][2][4][2], const Unit& u, int wr, int wc, int fr, int fq) const {
;     ...
;             for (int m = 0; m < 4; ++m) { const int row = row0 + ai * HALF + m * 16; const size_t off = (size_t)row * 1024 + col0; float s = 0.f;
; #pragma unroll
;                 for (int bj = 0; bj < 2; ++bj) { f32x4 a0, a1;
;                     if (xin32) { const float* p = xin32 + off + bj * HALF; a0 = *(const f32x4*)p; a1 = *(const f32x4*)(p + 4); }
;                     else { const u32x4 w = *(const u32x4*)(xb + off + bj * HALF);
;                         a0 = (f32x4){__uint_as_float(w.x << 16), __uint_as_float(w.x & 0xffff0000u), __uint_as_float(w.y << 16), __uint_as_float(w.y & 0xffff0000u)};
;                         a1 = (f32x4){__uint_as_float(w.z << 16), __uint_as_float(w.z & 0xffff0000u), __uint_as_float(w.w << 16), __uint_as_float(w.w & 0xffff0000u)}; }
;                     const f32x4 v0 = a0 + acc[ai][bj][m][0] * alpha, v1 = a1 + acc[ai][bj][m][1] * alpha;
;                     u32x4 w; w.x = cvtpk(v0[0], v0[1]); w.y = cvtpk(v0[2], v0[3]); w.z = cvtpk(v1[0], v1[1]); w.w = cvtpk(v1[2], v1[3]);
;                     *(u32x4*)(xb + off + bj * HALF) = w;
;                     s += (v0[0] * v0[0] + v0[1] * v0[1]) + (v0[2] * v0[2] + v0[3] * v0[3]) + (v1[0] * v1[0] + v1[1] * v1[1]) + (v1[2] * v1[2] + v1[3] * v1[3]); }
;                 s += __shfl_xor(s, 16); s += __shfl_xor(s, 32);
;                 if (fq == 0) fx_add(ssout, row, s); }
.LBB0_299:
	s_waitcnt vmcnt(0)
	v_fma_f32 v82, v78, 0.5, v82
	v_fma_f32 v83, v79, 0.5, v83
	v_fma_f32 v94, v76, 0.5, v80
	v_fma_f32 v95, v77, 0.5, v81
	v_fma_f32 v80, v74, 0.5, v86
	v_fma_f32 v81, v75, 0.5, v87
	v_fma_f32 v84, v72, 0.5, v84
	v_fma_f32 v85, v73, 0.5, v85
	v_cvt_pk_bf16_f32 v72, v94, v95
	v_cvt_pk_bf16_f32 v73, v82, v83
	v_cvt_pk_bf16_f32 v74, v84, v85
	v_cvt_pk_bf16_f32 v75, v80, v81
	s_and_b64 vcc, exec, s[10:11]
	global_store_dwordx4 v[90:91], v[72:75], off
	s_cbranch_vccnz .LBB0_346
	global_load_dwordx4 v[76:79], v[92:93], off offset:528
	global_load_dwordx4 v[72:75], v[92:93], off offset:512
	s_cbranch_execnz .LBB0_302

; __device__ __forceinline__ void fx_add(float* p, size_t idx, float s) { atomicAdd((unsigned long long*)p + idx, (unsigned long long)(long long)(s * 4294967296.0f)); }
; __device__ __forceinline__ unsigned cvtpk(float lo, float hi) { f32x2v_ v = {lo, hi}; bf16x2v_ b = __builtin_convertvector(v, bf16x2v_); return __builtin_bit_cast(unsigned, b); }
;     __device__ __forceinline__ void operator()(const f32x4 (&acc)[2][2][4][2], const Unit& u, int wr, int wc, int fr, int fq) const {
;     ...
;             for (int m = 0; m < 4; ++m) { const int row = row0 + ai * HALF + m * 16; const size_t off = (size_t)row * 1024 + col0; float s = 0.f;
; #pragma unroll
;                 for (int bj = 0; bj < 2; ++bj) { f32x4 a0, a1;
;                     if (xin32) { const float* p = xin32 + off + bj * HALF; a0 = *(const f32x4*)p; a1 = *(const f32x4*)(p + 4); }
;                     else { const u32x4 w = *(const u32x4*)(xb + off + bj * HALF);
;                         a0 = (f32x4){__uint_as_float(w.x << 16), __uint_as_float(w.x & 0xffff0000u), __uint_as_float(w.y << 16), __uint_as_float(w.y & 0xffff0000u)};
;                         a1 = (f32x4){__uint_as_float(w.z << 16), __uint_as_float(w.z & 0xffff0000u), __uint_as_float(w.w << 16), __uint_as_float(w.w & 0xffff0000u)}; }
;                     const f32x4 v0 = a0 + acc[ai][bj][m][0] * alpha, v1 = a1 + acc[ai][bj][m][1] * alpha;
;                     u32x4 w; w.x = cvtpk(v0[0], v0[1]); w.y = cvtpk(v0[2], v0[3]); w.z = cvtpk(v1[0], v1[1]); w.w = cvtpk(v1[2], v1[3]);
;                     *(u32x4*)(xb + off + bj * HALF) = w;
;                     s += (v0[0] * v0[0] + v0[1] * v0[1]) + (v0[2] * v0[2] + v0[3] * v0[3]) + (v1[0] * v1[0] + v1[1] * v1[1]) + (v1[2] * v1[2] + v1[3] * v1[3]); }
;                 s += __shfl_xor(s, 16); s += __shfl_xor(s, 32);
;                 if (fq == 0) fx_add(ssout, row, s); }
.LBB0_302:
	s_waitcnt vmcnt(0)
	v_fma_f32 v70, v70, 0.5, v74
	v_fma_f32 v71, v71, 0.5, v75
	v_fma_f32 v68, v68, 0.5, v72
	v_fma_f32 v69, v69, 0.5, v73
	v_fma_f32 v74, v64, 0.5, v76
	v_fma_f32 v75, v65, 0.5, v77
	v_mul_f32_e32 v64, v69, v69
	v_mul_f32_e32 v65, v71, v71
	v_mul_f32_e32 v86, v95, v95
	v_mul_f32_e32 v83, v83, v83
	v_fmac_f32_e32 v64, v68, v68
	v_fmac_f32_e32 v65, v70, v70
	v_fmac_f32_e32 v86, v94, v94
	v_fmac_f32_e32 v83, v82, v82
	v_add_f32_e32 v64, v64, v65
	v_mul_f32_e32 v65, v75, v75
	v_add_f32_e32 v82, v86, v83
	v_mul_f32_e32 v83, v85, v85
	v_fma_f32 v72, v66, 0.5, v78
	v_fma_f32 v73, v67, 0.5, v79
	v_fmac_f32_e32 v65, v74, v74
	v_fmac_f32_e32 v83, v84, v84
	v_mul_f32_e32 v81, v81, v81
	v_add_f32_e32 v64, v65, v64
	v_mul_f32_e32 v65, v73, v73
	v_add_f32_e32 v82, v83, v82
	v_fmac_f32_e32 v81, v80, v80
	v_fmac_f32_e32 v65, v72, v72
	v_add_f32_e32 v80, v81, v82
	v_add_f32_e32 v64, v65, v64
	v_add_f32_e32 v64, v80, v64
	ds_bpermute_b32 v65, v128, v64
	v_cvt_pk_bf16_f32 v66, v68, v69
	v_cvt_pk_bf16_f32 v67, v70, v71
	v_cvt_pk_bf16_f32 v68, v74, v75
	v_cvt_pk_bf16_f32 v69, v72, v73
	s_waitcnt lgkmcnt(0)
	v_add_f32_e32 v64, v64, v65
	ds_bpermute_b32 v65, v129, v64
	global_store_dwordx4 v[90:91], v[66:69], off offset:256
	s_and_saveexec_b64 s[50:51], s[6:7]
	s_cbranch_execz .LBB0_304
	s_waitcnt lgkmcnt(0)
	v_add_f32_e32 v64, v64, v65
	v_mul_f32_e32 v64, 0x4f800000, v64
	v_trunc_f32_e32 v64, v64
	v_mul_f32_e64 v65, |v64|, s67
	v_floor_f32_e32 v65, v65
	v_fma_f32 v66, v65, s86, |v64|
	v_cvt_u32_f32_e32 v66, v66
	v_cvt_u32_f32_e32 v65, v65
	v_ashrrev_i32_e32 v67, 31, v64
	v_xor_b32_e32 v64, v66, v67
	v_xor_b32_e32 v65, v65, v67
	v_sub_co_u32_e32 v64, vcc, v64, v67
	s_nop 1
	v_subb_co_u32_e32 v65, vcc, v65, v67, vcc
	v_lshl_add_u64 v[66:67], v[88:89], 3, s[24:25]
	global_atomic_add_x2 v[66:67], v[64:65], off

; __device__ __forceinline__ void fx_add(float* p, size_t idx, float s) { atomicAdd((unsigned long long*)p + idx, (unsigned long long)(long long)(s * 4294967296.0f)); }
; __device__ __forceinline__ unsigned cvtpk(float lo, float hi) { f32x2v_ v = {lo, hi}; bf16x2v_ b = __builtin_convertvector(v, bf16x2v_); return __builtin_bit_cast(unsigned, b); }
;     __device__ __forceinline__ void operator()(const f32x4 (&acc)[2][2][4][2], const Unit& u, int wr, int wc, int fr, int fq) const {
;     ...
;             for (int m = 0; m < 4; ++m) { const int row = row0 + ai * HALF + m * 16; const size_t off = (size_t)row * 1024 + col0; float s = 0.f;
; #pragma unroll
;                 for (int bj = 0; bj < 2; ++bj) { f32x4 a0, a1;
;                     if (xin32) { const float* p = xin32 + off + bj * HALF; a0 = *(const f32x4*)p; a1 = *(const f32x4*)(p + 4); }
;                     else { const u32x4 w = *(const u32x4*)(xb + off + bj * HALF);
;                         a0 = (f32x4){__uint_as_float(w.x << 16), __uint_as_float(w.x & 0xffff0000u), __uint_as_float(w.y << 16), __uint_as_float(w.y & 0xffff0000u)};
;                         a1 = (f32x4){__uint_as_float(w.z << 16), __uint_as_float(w.z & 0xffff0000u), __uint_as_float(w.w << 16), __uint_as_float(w.w & 0xffff0000u)}; }
;                     const f32x4 v0 = a0 + acc[ai][bj][m][0] * alpha, v1 = a1 + acc[ai][bj][m][1] * alpha;
;                     u32x4 w; w.x = cvtpk(v0[0], v0[1]); w.y = cvtpk(v0[2], v0[3]); w.z = cvtpk(v1[0], v1[1]); w.w = cvtpk(v1[2], v1[3]);
;                     *(u32x4*)(xb + off + bj * HALF) = w;
;                     s += (v0[0] * v0[0] + v0[1] * v0[1]) + (v0[2] * v0[2] + v0[3] * v0[3]) + (v1[0] * v1[0] + v1[1] * v1[1]) + (v1[2] * v1[2] + v1[3] * v1[3]); }
;                 s += __shfl_xor(s, 16); s += __shfl_xor(s, 32);
;                 if (fq == 0) fx_add(ssout, row, s); }
.LBB0_307:
	s_waitcnt vmcnt(0)
	v_fma_f32 v66, v62, 0.5, v66
	v_fma_f32 v67, v63, 0.5, v67
	v_fma_f32 v78, v60, 0.5, v64
	v_fma_f32 v79, v61, 0.5, v65
	v_fma_f32 v64, v58, 0.5, v70
	v_fma_f32 v65, v59, 0.5, v71
	v_fma_f32 v68, v56, 0.5, v68
	v_fma_f32 v69, v57, 0.5, v69
	v_cvt_pk_bf16_f32 v56, v78, v79
	v_cvt_pk_bf16_f32 v57, v66, v67
	v_cvt_pk_bf16_f32 v58, v68, v69
	v_cvt_pk_bf16_f32 v59, v64, v65
	s_and_b64 vcc, exec, s[10:11]
	global_store_dwordx4 v[74:75], v[56:59], off
	s_cbranch_vccnz .LBB0_348
	global_load_dwordx4 v[60:63], v[76:77], off offset:528
	global_load_dwordx4 v[56:59], v[76:77], off offset:512
	s_cbranch_execnz .LBB0_310

; __device__ __forceinline__ void fx_add(float* p, size_t idx, float s) { atomicAdd((unsigned long long*)p + idx, (unsigned long long)(long long)(s * 4294967296.0f)); }
; __device__ __forceinline__ unsigned cvtpk(float lo, float hi) { f32x2v_ v = {lo, hi}; bf16x2v_ b = __builtin_convertvector(v, bf16x2v_); return __builtin_bit_cast(unsigned, b); }
;     __device__ __forceinline__ void operator()(const f32x4 (&acc)[2][2][4][2], const Unit& u, int wr, int wc, int fr, int fq) const {
;     ...
;             for (int m = 0; m < 4; ++m) { const int row = row0 + ai * HALF + m * 16; const size_t off = (size_t)row * 1024 + col0; float s = 0.f;
; #pragma unroll
;                 for (int bj = 0; bj < 2; ++bj) { f32x4 a0, a1;
;                     if (xin32) { const float* p = xin32 + off + bj * HALF; a0 = *(const f32x4*)p; a1 = *(const f32x4*)(p + 4); }
;                     else { const u32x4 w = *(const u32x4*)(xb + off + bj * HALF);
;                         a0 = (f32x4){__uint_as_float(w.x << 16), __uint_as_float(w.x & 0xffff0000u), __uint_as_float(w.y << 16), __uint_as_float(w.y & 0xffff0000u)};
;                         a1 = (f32x4){__uint_as_float(w.z << 16), __uint_as_float(w.z & 0xffff0000u), __uint_as_float(w.w << 16), __uint_as_float(w.w & 0xffff0000u)}; }
;                     const f32x4 v0 = a0 + acc[ai][bj][m][0] * alpha, v1 = a1 + acc[ai][bj][m][1] * alpha;
;                     u32x4 w; w.x = cvtpk(v0[0], v0[1]); w.y = cvtpk(v0[2], v0[3]); w.z = cvtpk(v1[0], v1[1]); w.w = cvtpk(v1[2], v1[3]);
;                     *(u32x4*)(xb + off + bj * HALF) = w;
;                     s += (v0[0] * v0[0] + v0[1] * v0[1]) + (v0[2] * v0[2] + v0[3] * v0[3]) + (v1[0] * v1[0] + v1[1] * v1[1]) + (v1[2] * v1[2] + v1[3] * v1[3]); }
;                 s += __shfl_xor(s, 16); s += __shfl_xor(s, 32);
;                 if (fq == 0) fx_add(ssout, row, s); }
.LBB0_310:
	s_waitcnt vmcnt(0)
	v_fma_f32 v54, v54, 0.5, v58
	v_fma_f32 v55, v55, 0.5, v59
	v_fma_f32 v52, v52, 0.5, v56
	v_fma_f32 v53, v53, 0.5, v57
	v_fma_f32 v58, v48, 0.5, v60
	v_fma_f32 v59, v49, 0.5, v61
	v_mul_f32_e32 v48, v53, v53
	v_mul_f32_e32 v49, v55, v55
	v_mul_f32_e32 v70, v79, v79
	v_mul_f32_e32 v67, v67, v67
	v_fmac_f32_e32 v48, v52, v52
	v_fmac_f32_e32 v49, v54, v54
	v_fmac_f32_e32 v70, v78, v78
	v_fmac_f32_e32 v67, v66, v66
	v_add_f32_e32 v48, v48, v49
	v_mul_f32_e32 v49, v59, v59
	v_add_f32_e32 v66, v70, v67
	v_mul_f32_e32 v67, v69, v69
	v_fma_f32 v56, v50, 0.5, v62
	v_fma_f32 v57, v51, 0.5, v63
	v_fmac_f32_e32 v49, v58, v58
	v_fmac_f32_e32 v67, v68, v68
	v_mul_f32_e32 v65, v65, v65
	v_add_f32_e32 v48, v49, v48
	v_mul_f32_e32 v49, v57, v57
	v_add_f32_e32 v66, v67, v66
	v_fmac_f32_e32 v65, v64, v64
	v_fmac_f32_e32 v49, v56, v56
	v_add_f32_e32 v64, v65, v66
	v_add_f32_e32 v48, v49, v48
	v_add_f32_e32 v48, v64, v48
	ds_bpermute_b32 v49, v128, v48
	v_cvt_pk_bf16_f32 v50, v52, v53
	v_cvt_pk_bf16_f32 v51, v54, v55
	v_cvt_pk_bf16_f32 v52, v58, v59
	v_cvt_pk_bf16_f32 v53, v56, v57
	s_waitcnt lgkmcnt(0)
	v_add_f32_e32 v48, v48, v49
	ds_bpermute_b32 v49, v129, v48
	global_store_dwordx4 v[74:75], v[50:53], off offset:256
	s_and_saveexec_b64 s[50:51], s[6:7]
	s_cbranch_execz .LBB0_312
	s_waitcnt lgkmcnt(0)
	v_add_f32_e32 v48, v48, v49
	v_mul_f32_e32 v48, 0x4f800000, v48
	v_trunc_f32_e32 v48, v48
	v_mul_f32_e64 v49, |v48|, s67
	v_floor_f32_e32 v49, v49
	v_fma_f32 v50, v49, s86, |v48|
	v_cvt_u32_f32_e32 v50, v50
	v_cvt_u32_f32_e32 v49, v49
	v_ashrrev_i32_e32 v51, 31, v48
	v_xor_b32_e32 v48, v50, v51
	v_xor_b32_e32 v49, v49, v51
	v_sub_co_u32_e32 v48, vcc, v48, v51
	s_nop 1
	v_subb_co_u32_e32 v49, vcc, v49, v51, vcc
	v_lshl_add_u64 v[50:51], v[72:73], 3, s[24:25]
	global_atomic_add_x2 v[50:51], v[48:49], off

; __device__ __forceinline__ void fx_add(float* p, size_t idx, float s) { atomicAdd((unsigned long long*)p + idx, (unsigned long long)(long long)(s * 4294967296.0f)); }
; __device__ __forceinline__ unsigned cvtpk(float lo, float hi) { f32x2v_ v = {lo, hi}; bf16x2v_ b = __builtin_convertvector(v, bf16x2v_); return __builtin_bit_cast(unsigned, b); }
;     __device__ __forceinline__ void operator()(const f32x4 (&acc)[2][2][4][2], const Unit& u, int wr, int wc, int fr, int fq) const {
;     ...
;             for (int m = 0; m < 4; ++m) { const int row = row0 + ai * HALF + m * 16; const size_t off = (size_t)row * 1024 + col0; float s = 0.f;
; #pragma unroll
;                 for (int bj = 0; bj < 2; ++bj) { f32x4 a0, a1;
;                     if (xin32) { const float* p = xin32 + off + bj * HALF; a0 = *(const f32x4*)p; a1 = *(const f32x4*)(p + 4); }
;                     else { const u32x4 w = *(const u32x4*)(xb + off + bj * HALF);
;                         a0 = (f32x4){__uint_as_float(w.x << 16), __uint_as_float(w.x & 0xffff0000u), __uint_as_float(w.y << 16), __uint_as_float(w.y & 0xffff0000u)};
;                         a1 = (f32x4){__uint_as_float(w.z << 16), __uint_as_float(w.z & 0xffff0000u), __uint_as_float(w.w << 16), __uint_as_float(w.w & 0xffff0000u)}; }
;                     const f32x4 v0 = a0 + acc[ai][bj][m][0] * alpha, v1 = a1 + acc[ai][bj][m][1] * alpha;
;                     u32x4 w; w.x = cvtpk(v0[0], v0[1]); w.y = cvtpk(v0[2], v0[3]); w.z = cvtpk(v1[0], v1[1]); w.w = cvtpk(v1[2], v1[3]);
;                     *(u32x4*)(xb + off + bj * HALF) = w;
;                     s += (v0[0] * v0[0] + v0[1] * v0[1]) + (v0[2] * v0[2] + v0[3] * v0[3]) + (v1[0] * v1[0] + v1[1] * v1[1]) + (v1[2] * v1[2] + v1[3] * v1[3]); }
;                 s += __shfl_xor(s, 16); s += __shfl_xor(s, 32);
;                 if (fq == 0) fx_add(ssout, row, s); }
.LBB0_315:
	s_waitcnt vmcnt(0)
	v_fma_f32 v50, v46, 0.5, v50
	v_fma_f32 v51, v47, 0.5, v51
	v_fma_f32 v62, v44, 0.5, v48
	v_fma_f32 v63, v45, 0.5, v49
	v_fma_f32 v48, v42, 0.5, v54
	v_fma_f32 v49, v43, 0.5, v55
	v_fma_f32 v52, v40, 0.5, v52
	v_fma_f32 v53, v41, 0.5, v53
	v_cvt_pk_bf16_f32 v40, v62, v63
	v_cvt_pk_bf16_f32 v41, v50, v51
	v_cvt_pk_bf16_f32 v42, v52, v53
	v_cvt_pk_bf16_f32 v43, v48, v49
	s_and_b64 vcc, exec, s[10:11]
	global_store_dwordx4 v[58:59], v[40:43], off
	s_cbranch_vccnz .LBB0_350
	global_load_dwordx4 v[44:47], v[60:61], off offset:528
	global_load_dwordx4 v[40:43], v[60:61], off offset:512
	s_cbranch_execnz .LBB0_318

; __device__ __forceinline__ void fx_add(float* p, size_t idx, float s) { atomicAdd((unsigned long long*)p + idx, (unsigned long long)(long long)(s * 4294967296.0f)); }
; __device__ __forceinline__ unsigned cvtpk(float lo, float hi) { f32x2v_ v = {lo, hi}; bf16x2v_ b = __builtin_convertvector(v, bf16x2v_); return __builtin_bit_cast(unsigned, b); }
;     __device__ __forceinline__ void operator()(const f32x4 (&acc)[2][2][4][2], const Unit& u, int wr, int wc, int fr, int fq) const {
;     ...
;             for (int m = 0; m < 4; ++m) { const int row = row0 + ai * HALF + m * 16; const size_t off = (size_t)row * 1024 + col0; float s = 0.f;
; #pragma unroll
;                 for (int bj = 0; bj < 2; ++bj) { f32x4 a0, a1;
;                     if (xin32) { const float* p = xin32 + off + bj * HALF; a0 = *(const f32x4*)p; a1 = *(const f32x4*)(p + 4); }
;                     else { const u32x4 w = *(const u32x4*)(xb + off + bj * HALF);
;                         a0 = (f32x4){__uint_as_float(w.x << 16), __uint_as_float(w.x & 0xffff0000u), __uint_as_float(w.y << 16), __uint_as_float(w.y & 0xffff0000u)};
;                         a1 = (f32x4){__uint_as_float(w.z << 16), __uint_as_float(w.z & 0xffff0000u), __uint_as_float(w.w << 16), __uint_as_float(w.w & 0xffff0000u)}; }
;                     const f32x4 v0 = a0 + acc[ai][bj][m][0] * alpha, v1 = a1 + acc[ai][bj][m][1] * alpha;
;                     u32x4 w; w.x = cvtpk(v0[0], v0[1]); w.y = cvtpk(v0[2], v0[3]); w.z = cvtpk(v1[0], v1[1]); w.w = cvtpk(v1[2], v1[3]);
;                     *(u32x4*)(xb + off + bj * HALF) = w;
;                     s += (v0[0] * v0[0] + v0[1] * v0[1]) + (v0[2] * v0[2] + v0[3] * v0[3]) + (v1[0] * v1[0] + v1[1] * v1[1]) + (v1[2] * v1[2] + v1[3] * v1[3]); }
;                 s += __shfl_xor(s, 16); s += __shfl_xor(s, 32);
;                 if (fq == 0) fx_add(ssout, row, s); }
.LBB0_318:
	s_waitcnt vmcnt(0)
	v_fma_f32 v38, v38, 0.5, v42
	v_fma_f32 v39, v39, 0.5, v43
	v_fma_f32 v36, v36, 0.5, v40
	v_fma_f32 v37, v37, 0.5, v41
	v_fma_f32 v42, v32, 0.5, v44
	v_fma_f32 v43, v33, 0.5, v45
	v_mul_f32_e32 v32, v37, v37
	v_mul_f32_e32 v33, v39, v39
	v_mul_f32_e32 v54, v63, v63
	v_mul_f32_e32 v51, v51, v51
	v_fmac_f32_e32 v32, v36, v36
	v_fmac_f32_e32 v33, v38, v38
	v_fmac_f32_e32 v54, v62, v62
	v_fmac_f32_e32 v51, v50, v50
	v_add_f32_e32 v32, v32, v33
	v_mul_f32_e32 v33, v43, v43
	v_add_f32_e32 v50, v54, v51
	v_mul_f32_e32 v51, v53, v53
	v_fma_f32 v40, v34, 0.5, v46
	v_fma_f32 v41, v35, 0.5, v47
	v_fmac_f32_e32 v33, v42, v42
	v_fmac_f32_e32 v51, v52, v52
	v_mul_f32_e32 v49, v49, v49
	v_add_f32_e32 v32, v33, v32
	v_mul_f32_e32 v33, v41, v41
	v_add_f32_e32 v50, v51, v50
	v_fmac_f32_e32 v49, v48, v48
	v_fmac_f32_e32 v33, v40, v40
	v_add_f32_e32 v48, v49, v50
	v_add_f32_e32 v32, v33, v32
	v_add_f32_e32 v32, v48, v32
	ds_bpermute_b32 v33, v128, v32
	v_cvt_pk_bf16_f32 v34, v36, v37
	v_cvt_pk_bf16_f32 v35, v38, v39
	v_cvt_pk_bf16_f32 v36, v42, v43
	v_cvt_pk_bf16_f32 v37, v40, v41
	s_waitcnt lgkmcnt(0)
	v_add_f32_e32 v32, v32, v33
	ds_bpermute_b32 v33, v129, v32
	global_store_dwordx4 v[58:59], v[34:37], off offset:256
	s_and_saveexec_b64 s[50:51], s[6:7]
	s_cbranch_execz .LBB0_320
	s_waitcnt lgkmcnt(0)
	v_add_f32_e32 v32, v32, v33
	v_mul_f32_e32 v32, 0x4f800000, v32
	v_trunc_f32_e32 v32, v32
	v_mul_f32_e64 v33, |v32|, s67
	v_floor_f32_e32 v33, v33
	v_fma_f32 v34, v33, s86, |v32|
	v_cvt_u32_f32_e32 v34, v34
	v_cvt_u32_f32_e32 v33, v33
	v_ashrrev_i32_e32 v35, 31, v32
	v_xor_b32_e32 v32, v34, v35
	v_xor_b32_e32 v33, v33, v35
	v_sub_co_u32_e32 v32, vcc, v32, v35
	s_nop 1
	v_subb_co_u32_e32 v33, vcc, v33, v35, vcc
	v_lshl_add_u64 v[34:35], v[56:57], 3, s[24:25]
	global_atomic_add_x2 v[34:35], v[32:33], off

; __device__ __forceinline__ void fx_add(float* p, size_t idx, float s) { atomicAdd((unsigned long long*)p + idx, (unsigned long long)(long long)(s * 4294967296.0f)); }
; __device__ __forceinline__ unsigned cvtpk(float lo, float hi) { f32x2v_ v = {lo, hi}; bf16x2v_ b = __builtin_convertvector(v, bf16x2v_); return __builtin_bit_cast(unsigned, b); }
;     __device__ __forceinline__ void operator()(const f32x4 (&acc)[2][2][4][2], const Unit& u, int wr, int wc, int fr, int fq) const {
;     ...
;             for (int m = 0; m < 4; ++m) { const int row = row0 + ai * HALF + m * 16; const size_t off = (size_t)row * 1024 + col0; float s = 0.f;
; #pragma unroll
;                 for (int bj = 0; bj < 2; ++bj) { f32x4 a0, a1;
;                     if (xin32) { const float* p = xin32 + off + bj * HALF; a0 = *(const f32x4*)p; a1 = *(const f32x4*)(p + 4); }
;                     else { const u32x4 w = *(const u32x4*)(xb + off + bj * HALF);
;                         a0 = (f32x4){__uint_as_float(w.x << 16), __uint_as_float(w.x & 0xffff0000u), __uint_as_float(w.y << 16), __uint_as_float(w.y & 0xffff0000u)};
;                         a1 = (f32x4){__uint_as_float(w.z << 16), __uint_as_float(w.z & 0xffff0000u), __uint_as_float(w.w << 16), __uint_as_float(w.w & 0xffff0000u)}; }
;                     const f32x4 v0 = a0 + acc[ai][bj][m][0] * alpha, v1 = a1 + acc[ai][bj][m][1] * alpha;
;                     u32x4 w; w.x = cvtpk(v0[0], v0[1]); w.y = cvtpk(v0[2], v0[3]); w.z = cvtpk(v1[0], v1[1]); w.w = cvtpk(v1[2], v1[3]);
;                     *(u32x4*)(xb + off + bj * HALF) = w;
;                     s += (v0[0] * v0[0] + v0[1] * v0[1]) + (v0[2] * v0[2] + v0[3] * v0[3]) + (v1[0] * v1[0] + v1[1] * v1[1]) + (v1[2] * v1[2] + v1[3] * v1[3]); }
;                 s += __shfl_xor(s, 16); s += __shfl_xor(s, 32);
;                 if (fq == 0) fx_add(ssout, row, s); }
.LBB0_323:
	s_waitcnt vmcnt(0)
	v_fma_f32 v34, v30, 0.5, v34
	v_fma_f32 v35, v31, 0.5, v35
	v_fma_f32 v46, v28, 0.5, v32
	v_fma_f32 v47, v29, 0.5, v33
	v_fma_f32 v32, v26, 0.5, v38
	v_fma_f32 v33, v27, 0.5, v39
	v_fma_f32 v36, v24, 0.5, v36
	v_fma_f32 v37, v25, 0.5, v37
	v_cvt_pk_bf16_f32 v24, v46, v47
	v_cvt_pk_bf16_f32 v25, v34, v35
	v_cvt_pk_bf16_f32 v26, v36, v37
	v_cvt_pk_bf16_f32 v27, v32, v33
	s_and_b64 vcc, exec, s[10:11]
	global_store_dwordx4 v[42:43], v[24:27], off
	s_cbranch_vccnz .LBB0_352
	global_load_dwordx4 v[28:31], v[44:45], off offset:528
	global_load_dwordx4 v[24:27], v[44:45], off offset:512
	s_cbranch_execnz .LBB0_326

; __device__ __forceinline__ void fx_add(float* p, size_t idx, float s) { atomicAdd((unsigned long long*)p + idx, (unsigned long long)(long long)(s * 4294967296.0f)); }
; __device__ __forceinline__ unsigned cvtpk(float lo, float hi) { f32x2v_ v = {lo, hi}; bf16x2v_ b = __builtin_convertvector(v, bf16x2v_); return __builtin_bit_cast(unsigned, b); }
;     __device__ __forceinline__ void operator()(const f32x4 (&acc)[2][2][4][2], const Unit& u, int wr, int wc, int fr, int fq) const {
;     ...
;             for (int m = 0; m < 4; ++m) { const int row = row0 + ai * HALF + m * 16; const size_t off = (size_t)row * 1024 + col0; float s = 0.f;
; #pragma unroll
;                 for (int bj = 0; bj < 2; ++bj) { f32x4 a0, a1;
;                     if (xin32) { const float* p = xin32 + off + bj * HALF; a0 = *(const f32x4*)p; a1 = *(const f32x4*)(p + 4); }
;                     else { const u32x4 w = *(const u32x4*)(xb + off + bj * HALF);
;                         a0 = (f32x4){__uint_as_float(w.x << 16), __uint_as_float(w.x & 0xffff0000u), __uint_as_float(w.y << 16), __uint_as_float(w.y & 0xffff0000u)};
;                         a1 = (f32x4){__uint_as_float(w.z << 16), __uint_as_float(w.z & 0xffff0000u), __uint_as_float(w.w << 16), __uint_as_float(w.w & 0xffff0000u)}; }
;                     const f32x4 v0 = a0 + acc[ai][bj][m][0] * alpha, v1 = a1 + acc[ai][bj][m][1] * alpha;
;                     u32x4 w; w.x = cvtpk(v0[0], v0[1]); w.y = cvtpk(v0[2], v0[3]); w.z = cvtpk(v1[0], v1[1]); w.w = cvtpk(v1[2], v1[3]);
;                     *(u32x4*)(xb + off + bj * HALF) = w;
;                     s += (v0[0] * v0[0] + v0[1] * v0[1]) + (v0[2] * v0[2] + v0[3] * v0[3]) + (v1[0] * v1[0] + v1[1] * v1[1]) + (v1[2] * v1[2] + v1[3] * v1[3]); }
;                 s += __shfl_xor(s, 16); s += __shfl_xor(s, 32);
;                 if (fq == 0) fx_add(ssout, row, s); }
.LBB0_326:
	s_waitcnt vmcnt(0)
	v_fma_f32 v22, v22, 0.5, v26
	v_fma_f32 v23, v23, 0.5, v27
	v_fma_f32 v20, v20, 0.5, v24
	v_fma_f32 v21, v21, 0.5, v25
	v_fma_f32 v26, v16, 0.5, v28
	v_fma_f32 v27, v17, 0.5, v29
	v_mul_f32_e32 v16, v21, v21
	v_mul_f32_e32 v17, v23, v23
	v_mul_f32_e32 v38, v47, v47
	v_mul_f32_e32 v35, v35, v35
	v_fmac_f32_e32 v16, v20, v20
	v_fmac_f32_e32 v17, v22, v22
	v_fmac_f32_e32 v38, v46, v46
	v_fmac_f32_e32 v35, v34, v34
	v_add_f32_e32 v16, v16, v17
	v_mul_f32_e32 v17, v27, v27
	v_add_f32_e32 v34, v38, v35
	v_mul_f32_e32 v35, v37, v37
	v_fma_f32 v24, v18, 0.5, v30
	v_fma_f32 v25, v19, 0.5, v31
	v_fmac_f32_e32 v17, v26, v26
	v_fmac_f32_e32 v35, v36, v36
	v_mul_f32_e32 v33, v33, v33
	v_add_f32_e32 v16, v17, v16
	v_mul_f32_e32 v17, v25, v25
	v_add_f32_e32 v34, v35, v34
	v_fmac_f32_e32 v33, v32, v32
	v_fmac_f32_e32 v17, v24, v24
	v_add_f32_e32 v32, v33, v34
	v_add_f32_e32 v16, v17, v16
	v_add_f32_e32 v16, v32, v16
	ds_bpermute_b32 v17, v128, v16
	v_cvt_pk_bf16_f32 v18, v20, v21
	v_cvt_pk_bf16_f32 v19, v22, v23
	v_cvt_pk_bf16_f32 v20, v26, v27
	v_cvt_pk_bf16_f32 v21, v24, v25
	s_waitcnt lgkmcnt(0)
	v_add_f32_e32 v16, v16, v17
	ds_bpermute_b32 v17, v129, v16
	global_store_dwordx4 v[42:43], v[18:21], off offset:256
	s_and_saveexec_b64 s[50:51], s[6:7]
	s_cbranch_execz .LBB0_328
	s_waitcnt lgkmcnt(0)
	v_add_f32_e32 v16, v16, v17
	v_mul_f32_e32 v16, 0x4f800000, v16
	v_trunc_f32_e32 v16, v16
	v_mul_f32_e64 v17, |v16|, s67
	v_floor_f32_e32 v17, v17
	v_fma_f32 v18, v17, s86, |v16|
	v_cvt_u32_f32_e32 v18, v18
	v_cvt_u32_f32_e32 v17, v17
	v_ashrrev_i32_e32 v19, 31, v16
	v_xor_b32_e32 v16, v18, v19
	v_xor_b32_e32 v17, v17, v19
	v_sub_co_u32_e32 v16, vcc, v16, v19
	s_nop 1
	v_subb_co_u32_e32 v17, vcc, v17, v19, vcc
	v_lshl_add_u64 v[18:19], v[40:41], 3, s[24:25]
	global_atomic_add_x2 v[18:19], v[16:17], off

; __device__ __forceinline__ void fx_add(float* p, size_t idx, float s) { atomicAdd((unsigned long long*)p + idx, (unsigned long long)(long long)(s * 4294967296.0f)); }
; __device__ __forceinline__ unsigned cvtpk(float lo, float hi) { f32x2v_ v = {lo, hi}; bf16x2v_ b = __builtin_convertvector(v, bf16x2v_); return __builtin_bit_cast(unsigned, b); }
;     __device__ __forceinline__ void operator()(const f32x4 (&acc)[2][2][4][2], const Unit& u, int wr, int wc, int fr, int fq) const {
;     ...
;             for (int m = 0; m < 4; ++m) { const int row = row0 + ai * HALF + m * 16; const size_t off = (size_t)row * 1024 + col0; float s = 0.f;
; #pragma unroll
;                 for (int bj = 0; bj < 2; ++bj) { f32x4 a0, a1;
;                     if (xin32) { const float* p = xin32 + off + bj * HALF; a0 = *(const f32x4*)p; a1 = *(const f32x4*)(p + 4); }
;                     else { const u32x4 w = *(const u32x4*)(xb + off + bj * HALF);
;                         a0 = (f32x4){__uint_as_float(w.x << 16), __uint_as_float(w.x & 0xffff0000u), __uint_as_float(w.y << 16), __uint_as_float(w.y & 0xffff0000u)};
;                         a1 = (f32x4){__uint_as_float(w.z << 16), __uint_as_float(w.z & 0xffff0000u), __uint_as_float(w.w << 16), __uint_as_float(w.w & 0xffff0000u)}; }
;                     const f32x4 v0 = a0 + acc[ai][bj][m][0] * alpha, v1 = a1 + acc[ai][bj][m][1] * alpha;
;                     u32x4 w; w.x = cvtpk(v0[0], v0[1]); w.y = cvtpk(v0[2], v0[3]); w.z = cvtpk(v1[0], v1[1]); w.w = cvtpk(v1[2], v1[3]);
;                     *(u32x4*)(xb + off + bj * HALF) = w;
;                     s += (v0[0] * v0[0] + v0[1] * v0[1]) + (v0[2] * v0[2] + v0[3] * v0[3]) + (v1[0] * v1[0] + v1[1] * v1[1]) + (v1[2] * v1[2] + v1[3] * v1[3]); }
;                 s += __shfl_xor(s, 16); s += __shfl_xor(s, 32);
;                 if (fq == 0) fx_add(ssout, row, s); }
.LBB0_331:
	s_waitcnt vmcnt(0)
	v_fma_f32 v18, v14, 0.5, v18
	v_fma_f32 v19, v15, 0.5, v19
	v_fma_f32 v30, v12, 0.5, v16
	v_fma_f32 v31, v13, 0.5, v17
	v_fma_f32 v16, v10, 0.5, v22
	v_fma_f32 v17, v11, 0.5, v23
	v_fma_f32 v20, v8, 0.5, v20
	v_fma_f32 v21, v9, 0.5, v21
	v_cvt_pk_bf16_f32 v8, v30, v31
	v_cvt_pk_bf16_f32 v9, v18, v19
	v_cvt_pk_bf16_f32 v10, v20, v21
	v_cvt_pk_bf16_f32 v11, v16, v17
	s_and_b64 vcc, exec, s[10:11]
	global_store_dwordx4 v[26:27], v[8:11], off
	s_cbranch_vccnz .LBB0_354
	global_load_dwordx4 v[12:15], v[28:29], off offset:528
	global_load_dwordx4 v[8:11], v[28:29], off offset:512
	s_cbranch_execnz .LBB0_334

; __device__ __forceinline__ void fx_add(float* p, size_t idx, float s) { atomicAdd((unsigned long long*)p + idx, (unsigned long long)(long long)(s * 4294967296.0f)); }
; __device__ __forceinline__ unsigned cvtpk(float lo, float hi) { f32x2v_ v = {lo, hi}; bf16x2v_ b = __builtin_convertvector(v, bf16x2v_); return __builtin_bit_cast(unsigned, b); }
;     __device__ __forceinline__ void operator()(const f32x4 (&acc)[2][2][4][2], const Unit& u, int wr, int wc, int fr, int fq) const {
;     ...
;             for (int m = 0; m < 4; ++m) { const int row = row0 + ai * HALF + m * 16; const size_t off = (size_t)row * 1024 + col0; float s = 0.f;
; #pragma unroll
;                 for (int bj = 0; bj < 2; ++bj) { f32x4 a0, a1;
;                     if (xin32) { const float* p = xin32 + off + bj * HALF; a0 = *(const f32x4*)p; a1 = *(const f32x4*)(p + 4); }
;                     else { const u32x4 w = *(const u32x4*)(xb + off + bj * HALF);
;                         a0 = (f32x4){__uint_as_float(w.x << 16), __uint_as_float(w.x & 0xffff0000u), __uint_as_float(w.y << 16), __uint_as_float(w.y & 0xffff0000u)};
;                         a1 = (f32x4){__uint_as_float(w.z << 16), __uint_as_float(w.z & 0xffff0000u), __uint_as_float(w.w << 16), __uint_as_float(w.w & 0xffff0000u)}; }
;                     const f32x4 v0 = a0 + acc[ai][bj][m][0] * alpha, v1 = a1 + acc[ai][bj][m][1] * alpha;
;                     u32x4 w; w.x = cvtpk(v0[0], v0[1]); w.y = cvtpk(v0[2], v0[3]); w.z = cvtpk(v1[0], v1[1]); w.w = cvtpk(v1[2], v1[3]);
;                     *(u32x4*)(xb + off + bj * HALF) = w;
;                     s += (v0[0] * v0[0] + v0[1] * v0[1]) + (v0[2] * v0[2] + v0[3] * v0[3]) + (v1[0] * v1[0] + v1[1] * v1[1]) + (v1[2] * v1[2] + v1[3] * v1[3]); }
;                 s += __shfl_xor(s, 16); s += __shfl_xor(s, 32);
;                 if (fq == 0) fx_add(ssout, row, s); }
.LBB0_334:
	s_waitcnt vmcnt(0)
	v_fma_f32 v6, v6, 0.5, v10
	v_fma_f32 v7, v7, 0.5, v11
	v_fma_f32 v4, v4, 0.5, v8
	v_fma_f32 v5, v5, 0.5, v9
	v_fma_f32 v10, v0, 0.5, v12
	v_fma_f32 v11, v1, 0.5, v13
	v_mul_f32_e32 v0, v5, v5
	v_mul_f32_e32 v1, v7, v7
	v_mul_f32_e32 v22, v31, v31
	v_mul_f32_e32 v19, v19, v19
	v_fmac_f32_e32 v0, v4, v4
	v_fmac_f32_e32 v1, v6, v6
	v_fmac_f32_e32 v22, v30, v30
	v_fmac_f32_e32 v19, v18, v18
	v_add_f32_e32 v0, v0, v1
	v_mul_f32_e32 v1, v11, v11
	v_add_f32_e32 v18, v22, v19
	v_mul_f32_e32 v19, v21, v21
	v_fma_f32 v8, v2, 0.5, v14
	v_fma_f32 v9, v3, 0.5, v15
	v_fmac_f32_e32 v1, v10, v10
	v_fmac_f32_e32 v19, v20, v20
	v_mul_f32_e32 v17, v17, v17
	v_add_f32_e32 v0, v1, v0
	v_mul_f32_e32 v1, v9, v9
	v_add_f32_e32 v18, v19, v18
	v_fmac_f32_e32 v17, v16, v16
	v_fmac_f32_e32 v1, v8, v8
	v_add_f32_e32 v16, v17, v18
	v_add_f32_e32 v0, v1, v0
	v_add_f32_e32 v0, v16, v0
	ds_bpermute_b32 v1, v128, v0
	v_cvt_pk_bf16_f32 v2, v4, v5
	v_cvt_pk_bf16_f32 v3, v6, v7
	v_cvt_pk_bf16_f32 v4, v10, v11
	v_cvt_pk_bf16_f32 v5, v8, v9
	s_waitcnt lgkmcnt(0)
	v_add_f32_e32 v0, v0, v1
	ds_bpermute_b32 v1, v129, v0
	global_store_dwordx4 v[26:27], v[2:5], off offset:256
	s_and_saveexec_b64 s[10:11], s[6:7]
	s_cbranch_execz .LBB0_336
	s_waitcnt lgkmcnt(0)
	v_add_f32_e32 v0, v0, v1
	v_mul_f32_e32 v0, 0x4f800000, v0
	v_trunc_f32_e32 v0, v0
	v_mul_f32_e64 v1, |v0|, s67
	v_floor_f32_e32 v1, v1
	v_fma_f32 v2, v1, s86, |v0|
	v_cvt_u32_f32_e32 v2, v2
	v_cvt_u32_f32_e32 v1, v1
	v_ashrrev_i32_e32 v3, 31, v0
	v_xor_b32_e32 v0, v2, v3
	v_xor_b32_e32 v1, v1, v3
	v_sub_co_u32_e32 v0, vcc, v0, v3
	s_nop 1
	v_subb_co_u32_e32 v1, vcc, v1, v3, vcc
	v_lshl_add_u64 v[2:3], v[24:25], 3, s[24:25]
	global_atomic_add_x2 v[2:3], v[0:1], off

; template <int l> __device__ __forceinline__ void layer_body(const Args& args, LAS unsigned char* lds, const XcdBarrier& bar) {
;     ...
;                   for (int i = 0; i < 16; i += 2) { v4u bg[2], c0[2], u0[2], c1[2], u1[2], c2[2], u2[2];
; #pragma unroll
;                     for (int q_ = 0; q_ < 2; ++q_) { const int t = w * 128 + (tid >> 6) + 8 * (i + q_), pos = t & (SEQ - 1); const bf16* zr = Z + (size_t)t * EV_IN + c;
;                         bg[q_] = *(const v4u*)zr; c0[q_] = *(const v4u*)(zr + 512); u0[q_] = *(const v4u*)(zr + 1024);
;                         c1[q_] = (v4u){0, 0, 0, 0}; u1[q_] = (v4u){0, 0, 0, 0}; c2[q_] = (v4u){0, 0, 0, 0}; u2[q_] = (v4u){0, 0, 0, 0};
;                         if (pos >= 1) { c1[q_] = *(const v4u*)(zr + 512 - EV_IN); u1[q_] = *(const v4u*)(zr + 1024 - EV_IN); }
;                         if (pos >= 2) { c2[q_] = *(const v4u*)(zr + 512 - 2 * EV_IN); u2[q_] = *(const v4u*)(zr + 1024 - 2 * EV_IN); } }
; #pragma unroll
;                     for (int q_ = 0; q_ < 2; ++q_) { const int t = w * 128 + (tid >> 6) + 8 * (i + q_); v4u o;
;                         o.x = CONV2(0, wa0[0], wa0[1], wb0[0], wb0[1], wc0[0], wc0[1]); o.y = CONV2(1, wa0[2], wa0[3], wb0[2], wb0[3], wc0[2], wc0[3]);
;                         o.z = CONV2(2, wa1[0], wa1[1], wb1[0], wb1[1], wc1[0], wc1[1]); o.w = CONV2(3, wa1[2], wa1[3], wb1[2], wb1[3], wc1[2], wc1[3]);
;                         *(v4u*)(Y + (size_t)t * D + c) = o; } }
.LBB0_568:
	s_or_b64 exec, exec, s[48:49]
	s_waitcnt vmcnt(4)
	v_lshlrev_b32_e32 v94, 16, v74
	v_and_b32_e32 v95, 0xffff0000, v74
	v_lshlrev_b32_e32 v74, 16, v75
	v_and_b32_e32 v75, 0xffff0000, v75
	v_lshlrev_b32_e32 v90, 16, v66
	v_and_b32_e32 v91, 0xffff0000, v66
	s_waitcnt vmcnt(3)
	v_lshlrev_b32_e32 v96, 16, v62
	v_and_b32_e32 v97, 0xffff0000, v62
	v_lshlrev_b32_e32 v66, 16, v67
	v_and_b32_e32 v67, 0xffff0000, v67
	v_pk_mul_f32 v[74:75], v[12:13], v[74:75]
	v_lshlrev_b32_e32 v62, 16, v63
	v_and_b32_e32 v63, 0xffff0000, v63
	v_lshlrev_b32_e32 v92, 16, v54
	v_and_b32_e32 v93, 0xffff0000, v54
	v_pk_mul_f32 v[66:67], v[20:21], v[66:67]
	v_lshlrev_b32_e32 v54, 16, v55
	v_and_b32_e32 v55, 0xffff0000, v55
	v_pk_mul_f32 v[62:63], v[74:75], v[62:63]
	v_lshlrev_b32_e32 v88, 16, v70
	v_fma_f32 v54, v66, v54, v62
	v_fma_f32 v55, v67, v55, v63
	v_lshlrev_b32_e32 v62, 16, v79
	v_and_b32_e32 v63, 0xffff0000, v79
	v_pk_mul_f32 v[62:63], v[4:5], v[62:63]
	v_lshlrev_b32_e32 v66, 16, v51
	v_and_b32_e32 v67, 0xffff0000, v51
	v_and_b32_e32 v89, 0xffff0000, v70
	v_lshlrev_b32_e32 v70, 16, v71
	v_and_b32_e32 v71, 0xffff0000, v71
	v_fma_f32 v54, v62, v66, v54
	v_fma_f32 v55, v63, v67, v55
	v_lshlrev_b32_e32 v62, 16, v68
	v_pk_mul_f32 v[54:55], v[54:55], v[70:71]
	v_lshlrev_b32_e32 v70, 16, v76
	v_and_b32_e32 v71, 0xffff0000, v76
	v_and_b32_e32 v63, 0xffff0000, v68
	v_pk_mul_f32 v[70:71], v[14:15], v[70:71]
	v_lshlrev_b32_e32 v74, 16, v64
	v_and_b32_e32 v75, 0xffff0000, v64
	v_pk_mul_f32 v[62:63], v[22:23], v[62:63]
	v_lshlrev_b32_e32 v66, 16, v56
	v_and_b32_e32 v67, 0xffff0000, v56
	v_pk_mul_f32 v[70:71], v[70:71], v[74:75]
	v_cvt_pk_bf16_f32 v51, v54, v55
	v_fma_f32 v62, v62, v66, v70
	v_fma_f32 v63, v63, v67, v71
	v_lshlrev_b32_e32 v66, 16, v80
	v_and_b32_e32 v67, 0xffff0000, v80
	v_pk_mul_f32 v[66:67], v[6:7], v[66:67]
	v_lshlrev_b32_e32 v70, 16, v52
	v_and_b32_e32 v71, 0xffff0000, v52
	v_lshlrev_b32_e32 v54, 16, v72
	v_and_b32_e32 v55, 0xffff0000, v72
	v_fma_f32 v62, v66, v70, v62
	v_fma_f32 v63, v67, v71, v63
	v_lshlrev_b32_e32 v66, 16, v77
	v_and_b32_e32 v67, 0xffff0000, v77
	v_pk_mul_f32 v[94:95], v[10:11], v[94:95]
	v_pk_mul_f32 v[54:55], v[62:63], v[54:55]
	v_lshlrev_b32_e32 v62, 16, v69
	v_and_b32_e32 v63, 0xffff0000, v69
	v_pk_mul_f32 v[66:67], v[16:17], v[66:67]
	v_lshlrev_b32_e32 v64, 16, v65
	v_and_b32_e32 v65, 0xffff0000, v65
	v_pk_mul_f32 v[90:91], v[18:19], v[90:91]
	v_pk_mul_f32 v[94:95], v[94:95], v[96:97]
	v_pk_mul_f32 v[62:63], v[24:25], v[62:63]
	v_lshlrev_b32_e32 v56, 16, v57
	v_and_b32_e32 v57, 0xffff0000, v57
	v_pk_mul_f32 v[64:65], v[66:67], v[64:65]
	v_fma_f32 v90, v90, v92, v94
	v_fma_f32 v91, v91, v93, v95
	v_lshlrev_b32_e32 v92, 16, v78
	v_and_b32_e32 v93, 0xffff0000, v78
	v_fma_f32 v56, v62, v56, v64
	v_fma_f32 v57, v63, v57, v65
	v_lshlrev_b32_e32 v62, 16, v81
	v_and_b32_e32 v63, 0xffff0000, v81
	v_pk_mul_f32 v[92:93], v[2:3], v[92:93]
	v_lshlrev_b32_e32 v94, 16, v50
	v_and_b32_e32 v95, 0xffff0000, v50
	v_pk_mul_f32 v[62:63], v[8:9], v[62:63]
	v_lshlrev_b32_e32 v64, 16, v53
	v_and_b32_e32 v65, 0xffff0000, v53
	v_fma_f32 v90, v92, v94, v90
	v_fma_f32 v91, v93, v95, v91
	v_cvt_pk_bf16_f32 v52, v54, v55
	v_lshlrev_b32_e32 v54, 16, v73
	v_and_b32_e32 v55, 0xffff0000, v73
	v_fma_f32 v56, v62, v64, v56
	v_fma_f32 v57, v63, v65, v57
	v_pk_mul_f32 v[88:89], v[90:91], v[88:89]
	v_pk_mul_f32 v[54:55], v[56:57], v[54:55]
	v_cvt_pk_bf16_f32 v50, v88, v89
	v_cvt_pk_bf16_f32 v53, v54, v55
	v_lshl_add_u64 v[54:55], v[82:83], 0, v[102:103]
	s_waitcnt vmcnt(1)
	v_lshlrev_b32_e32 v56, 16, v42
	v_and_b32_e32 v57, 0xffff0000, v42
	v_lshlrev_b32_e32 v42, 16, v43
	v_and_b32_e32 v43, 0xffff0000, v43
	global_store_dwordx4 v[54:55], v[50:53], off
	s_waitcnt vmcnt(1)
; template <int l> __device__ __forceinline__ void layer_body(const Args& args, LAS unsigned char* lds, const XcdBarrier& bar) {
;     ...
;                   for (int i = 0; i < 16; i += 2) { v4u bg[2], c0[2], u0[2], c1[2], u1[2], c2[2], u2[2];
; #pragma unroll
;                     for (int q_ = 0; q_ < 2; ++q_) { const int t = w * 128 + (tid >> 6) + 8 * (i + q_), pos = t & (SEQ - 1); const bf16* zr = Z + (size_t)t * EV_IN + c;
;                         bg[q_] = *(const v4u*)zr; c0[q_] = *(const v4u*)(zr + 512); u0[q_] = *(const v4u*)(zr + 1024);
;                         c1[q_] = (v4u){0, 0, 0, 0}; u1[q_] = (v4u){0, 0, 0, 0}; c2[q_] = (v4u){0, 0, 0, 0}; u2[q_] = (v4u){0, 0, 0, 0};
;                         if (pos >= 1) { c1[q_] = *(const v4u*)(zr + 512 - EV_IN); u1[q_] = *(const v4u*)(zr + 1024 - EV_IN); }
;                         if (pos >= 2) { c2[q_] = *(const v4u*)(zr + 512 - 2 * EV_IN); u2[q_] = *(const v4u*)(zr + 1024 - 2 * EV_IN); } }
; #pragma unroll
;                     for (int q_ = 0; q_ < 2; ++q_) { const int t = w * 128 + (tid >> 6) + 8 * (i + q_); v4u o;
;                         o.x = CONV2(0, wa0[0], wa0[1], wb0[0], wb0[1], wc0[0], wc0[1]); o.y = CONV2(1, wa0[2], wa0[3], wb0[2], wb0[3], wc0[2], wc0[3]);
;                         o.z = CONV2(2, wa1[0], wa1[1], wb1[0], wb1[1], wc1[0], wc1[1]); o.w = CONV2(3, wa1[2], wa1[3], wb1[2], wb1[3], wc1[2], wc1[3]);
;                         *(v4u*)(Y + (size_t)t * D + c) = o; } }
	v_lshlrev_b32_e32 v62, 16, v30
	v_and_b32_e32 v63, 0xffff0000, v30
	v_lshlrev_b32_e32 v52, 16, v38
	v_and_b32_e32 v53, 0xffff0000, v38
	v_lshlrev_b32_e32 v38, 16, v39
	v_and_b32_e32 v39, 0xffff0000, v39
	v_pk_mul_f32 v[42:43], v[12:13], v[42:43]
	v_lshlrev_b32_e32 v30, 16, v31
	v_and_b32_e32 v31, 0xffff0000, v31
	v_lshlrev_b32_e32 v54, 16, v34
	v_and_b32_e32 v55, 0xffff0000, v34
	v_pk_mul_f32 v[38:39], v[20:21], v[38:39]
	v_lshlrev_b32_e32 v34, 16, v35
	v_and_b32_e32 v35, 0xffff0000, v35
	v_pk_mul_f32 v[30:31], v[42:43], v[30:31]
	v_lshlrev_b32_e32 v50, 16, v46
	v_fma_f32 v30, v38, v34, v30
	v_fma_f32 v31, v39, v35, v31
	v_lshlrev_b32_e32 v34, 16, v59
	v_and_b32_e32 v35, 0xffff0000, v59
	v_pk_mul_f32 v[34:35], v[4:5], v[34:35]
	v_lshlrev_b32_e32 v38, 16, v27
	v_and_b32_e32 v39, 0xffff0000, v27
	v_and_b32_e32 v51, 0xffff0000, v46
	v_lshlrev_b32_e32 v46, 16, v47
	v_and_b32_e32 v47, 0xffff0000, v47
	v_fma_f32 v30, v34, v38, v30
	v_fma_f32 v31, v35, v39, v31
	v_lshlrev_b32_e32 v42, 16, v44
	v_and_b32_e32 v43, 0xffff0000, v44
	v_pk_mul_f32 v[30:31], v[30:31], v[46:47]
	v_lshlrev_b32_e32 v34, 16, v40
	v_and_b32_e32 v35, 0xffff0000, v40
	v_pk_mul_f32 v[42:43], v[14:15], v[42:43]
	v_lshlrev_b32_e32 v46, 16, v32
	v_and_b32_e32 v47, 0xffff0000, v32
	v_pk_mul_f32 v[34:35], v[22:23], v[34:35]
	v_lshlrev_b32_e32 v38, 16, v36
	v_and_b32_e32 v39, 0xffff0000, v36
	v_pk_mul_f32 v[42:43], v[42:43], v[46:47]
	v_cvt_pk_bf16_f32 v27, v30, v31
	v_fma_f32 v34, v34, v38, v42
	v_fma_f32 v35, v35, v39, v43
	v_lshlrev_b32_e32 v38, 16, v60
	v_and_b32_e32 v39, 0xffff0000, v60
	v_pk_mul_f32 v[38:39], v[6:7], v[38:39]
	v_lshlrev_b32_e32 v42, 16, v28
	v_and_b32_e32 v43, 0xffff0000, v28
	v_lshlrev_b32_e32 v30, 16, v48
	v_and_b32_e32 v31, 0xffff0000, v48
	v_fma_f32 v34, v38, v42, v34
	v_fma_f32 v35, v39, v43, v35
	v_lshlrev_b32_e32 v38, 16, v45
	v_and_b32_e32 v39, 0xffff0000, v45
	v_pk_mul_f32 v[30:31], v[34:35], v[30:31]
	v_lshlrev_b32_e32 v34, 16, v41
	v_and_b32_e32 v35, 0xffff0000, v41
	v_pk_mul_f32 v[38:39], v[16:17], v[38:39]
	v_lshlrev_b32_e32 v32, 16, v33
	v_and_b32_e32 v33, 0xffff0000, v33
	v_pk_mul_f32 v[56:57], v[10:11], v[56:57]
	v_pk_mul_f32 v[34:35], v[24:25], v[34:35]
	v_lshlrev_b32_e32 v36, 16, v37
	v_and_b32_e32 v37, 0xffff0000, v37
	v_pk_mul_f32 v[32:33], v[38:39], v[32:33]
	v_pk_mul_f32 v[52:53], v[18:19], v[52:53]
	v_pk_mul_f32 v[56:57], v[56:57], v[62:63]
	v_fma_f32 v32, v34, v36, v32
	v_fma_f32 v33, v35, v37, v33
	v_lshlrev_b32_e32 v34, 16, v61
	v_and_b32_e32 v35, 0xffff0000, v61
	v_fma_f32 v52, v52, v54, v56
	v_fma_f32 v53, v53, v55, v57
	v_lshlrev_b32_e32 v54, 16, v58
	v_and_b32_e32 v55, 0xffff0000, v58
	v_pk_mul_f32 v[34:35], v[8:9], v[34:35]
	v_lshlrev_b32_e32 v36, 16, v29
	v_and_b32_e32 v37, 0xffff0000, v29
	v_pk_mul_f32 v[54:55], v[2:3], v[54:55]
	v_lshlrev_b32_e32 v56, 16, v26
	v_and_b32_e32 v57, 0xffff0000, v26
	v_cvt_pk_bf16_f32 v28, v30, v31
	v_lshlrev_b32_e32 v30, 16, v49
	v_and_b32_e32 v31, 0xffff0000, v49
	v_fma_f32 v32, v34, v36, v32
	v_fma_f32 v33, v35, v37, v33
	v_ashrrev_i32_e32 v87, 31, v86
	v_fma_f32 v52, v54, v56, v52
	v_fma_f32 v53, v55, v57, v53
	v_pk_mul_f32 v[30:31], v[32:33], v[30:31]
	v_pk_mul_f32 v[50:51], v[52:53], v[50:51]
	v_cvt_pk_bf16_f32 v29, v30, v31
	v_lshlrev_b64 v[30:31], 11, v[86:87]
	s_add_i32 s10, s10, 2
	v_cvt_pk_bf16_f32 v26, v50, v51
	v_lshl_add_u64 v[30:31], v[106:107], 0, v[30:31]
	v_add_u32_e32 v1, 16, v1
	v_lshl_add_u64 v[82:83], v[82:83], 0, s[36:37]
	s_cmp_gt_u32 s10, 13
	v_lshl_add_u64 v[84:85], v[84:85], 0, s[38:39]
	global_store_dwordx4 v[30:31], v[26:29], off
	s_cbranch_scc1 .LBB0_577

; #define LAS __attribute__((address_space(3)))
; #define MFMA32(a, b, c) __builtin_amdgcn_mfma_f32_32x32x16_bf16((a), (b), (c), 0, 0, 0)
; template <int DH, class LF>
; __device__ __forceinline__ void attn_run(const bf16* kb, const bf16* vb, int t0, int t1, const bf16x8 (&qf)[DH / 16], f32x16 (&o)[DH / 32], float& m_run, float& l_run, LF&& lf) {
;     ...
;     for (int t = t0; t <= t1; ++t) {
;         bf16x8 vf[2][ND];
; #pragma unroll
;         for (int s2 = 0; s2 < 2; ++s2)
; #pragma unroll
;             for (int dg = 0; dg < ND; ++dg) vf[s2][dg] = *(const bf16x8*)(vb + s2 * (2 * DH * 8) + dg * 256);
;         f32x16 st;
; #pragma unroll
;         for (int i = 0; i < 16; ++i) st[i] = 0.f;
; #pragma unroll
;         for (int s = 0; s < KS; ++s) st = MFMA32(kf[s], qf[s], st);
;         if (t < t1) kb += TS;
;         vb += TS;
; #pragma unroll
;         for (int s = 0; s < KS; ++s) kf[s] = *(const bf16x8*)(kb + s * 512);
;         lf(t, st);
;         float tmax = fmaxf(fmaxf(st[0], st[1]), st[2]);
; #pragma unroll
;         for (int i = 3; i < 15; i += 2) tmax = fmaxf(fmaxf(tmax, st[i]), st[i + 1]);
;         tmax = fmaxf(tmax, st[15]);
;         { auto rr_ = __builtin_amdgcn_permlane32_swap(__float_as_uint(tmax), __float_as_uint(tmax), false, false); tmax = fmaxf(__uint_as_float(rr_[0]), __uint_as_float(rr_[1])); }
;         if (__any(tmax > m_run + 8.0f)) {
;             const float mn = fmaxf(m_run, tmax), corr = __builtin_amdgcn_exp2f(m_run - mn); m_run = mn; l_run *= corr;
; #pragma unroll
;             for (int dg = 0; dg < ND; ++dg) o[dg] = o[dg] * corr;
;         }
; template <int l> __device__ __forceinline__ void layer_body(const Args& args, LAS unsigned char* lds, const XcdBarrier& bar) {
;     ...
;                         const LAS float* bp = tb + (TPAD - 23) + (qpos - t * 32 - 8 * hh);
; #pragma unroll
;                         for (int i = 0; i < 16; ++i) st[i] = __builtin_fmaf(st[i], 0.125f * LOG2E, bp[23 - kofs(i)]); });
.LBB0_581:
	s_waitcnt vmcnt(3)
	v_mfma_f32_32x32x16_bf16 v[34:49], v[74:77], v[50:53], 0
	s_cmp_ge_u32 s57, s56
	s_cselect_b64 s[50:51], -1, 0
	s_cmp_lt_u32 s57, s56
	s_waitcnt vmcnt(0)
	v_mov_b64_e32 v[138:139], v[72:73]
	global_load_dwordx4 v[94:97], v[132:133], off
	global_load_dwordx4 v[86:89], v[132:133], off offset:512
	global_load_dwordx4 v[90:93], v[132:133], off offset:2048
	global_load_dwordx4 v[82:85], v[132:133], off offset:2560
	s_cselect_b32 s10, 0x1000, 0
	v_mov_b64_e32 v[136:137], v[70:71]
	v_mfma_f32_32x32x16_bf16 v[34:49], v[66:69], v[54:57], v[34:49]
	v_lshl_add_u64 v[70:71], v[126:127], 0, s[10:11]
	global_load_dwordx4 v[74:77], v[70:71], off offset:-2048
	global_load_dwordx4 v[66:69], v[70:71], off offset:-1024
	v_mfma_f32_32x32x16_bf16 v[34:49], v[78:81], v[58:61], v[34:49]
	global_load_dwordx4 v[78:81], v[70:71], off
	s_nop 0
	global_load_dwordx4 v[70:73], v[70:71], off offset:1024
	ds_read2_b32 v[140:141], v131 offset0:22 offset1:23
	ds_read2_b32 v[142:143], v131 offset0:20 offset1:21
	ds_read2_b32 v[144:145], v131 offset0:18 offset1:19
	v_mfma_f32_32x32x16_bf16 v[34:49], v[136:139], v[62:65], v[34:49]
	ds_read2_b32 v[136:137], v131 offset0:16 offset1:17
	s_waitcnt lgkmcnt(3)
	s_nop 9
	v_fma_f32 v34, v34, s44, v141
	v_fma_f32 v35, v35, s44, v140
	s_waitcnt lgkmcnt(2)
	v_fma_f32 v36, v36, s44, v143
	v_fma_f32 v37, v37, s44, v142
	v_max_f32_e32 v1, v34, v35
	s_waitcnt lgkmcnt(1)
	v_fma_f32 v38, v38, s44, v145
	v_fma_f32 v39, v39, s44, v144
	ds_read2_b32 v[138:139], v131 offset0:6 offset1:7
	ds_read2_b32 v[140:141], v131 offset0:4 offset1:5
	ds_read2_b32 v[142:143], v131 offset0:2 offset1:3
	ds_read2_b32 v[144:145], v131 offset1:1
	v_max3_f32 v1, v1, v36, v37
	s_waitcnt lgkmcnt(4)
	v_fma_f32 v40, v40, s44, v137
	v_fma_f32 v41, v41, s44, v136
	v_max3_f32 v1, v1, v38, v39
	s_waitcnt lgkmcnt(3)
	v_fma_f32 v42, v42, s44, v139
	v_fma_f32 v43, v43, s44, v138
	v_max3_f32 v1, v1, v40, v41
	s_waitcnt lgkmcnt(2)
	v_fma_f32 v44, v44, s44, v141
	v_fma_f32 v45, v45, s44, v140
	v_max3_f32 v1, v1, v42, v43
	s_waitcnt lgkmcnt(1)
	v_fma_f32 v46, v46, s44, v143
	v_fma_f32 v47, v47, s44, v142
	v_max3_f32 v1, v1, v44, v45
	s_waitcnt lgkmcnt(0)
	v_fma_f32 v48, v48, s44, v145
	v_fma_f32 v49, v49, s44, v144
	v_max3_f32 v1, v1, v46, v47
	v_max3_f32 v1, v1, v48, v49
	v_mov_b32_e32 v136, v1
	s_nop 1
	v_permlane32_swap_b32_e32 v1, v136
	v_max_f32_e32 v136, v136, v136
	v_max_f32_e32 v1, v1, v1
	v_max_f32_e32 v1, v1, v136
	v_add_f32_e32 v136, 0x41000000, v135
	v_cmp_gt_f32_e32 vcc, v1, v136
	s_cbranch_vccz .LBB0_580
	v_max_f32_e32 v1, v1, v1
	v_max_f32_e32 v136, v135, v135
	v_max_f32_e32 v1, v136, v1
	v_sub_f32_e32 v135, v135, v1
	v_exp_f32_e32 v136, v135
	v_mov_b32_e32 v135, v1
	v_mul_f32_e32 v134, v134, v136
	v_pk_mul_f32 v[32:33], v[32:33], v[136:137] op_sel_hi:[1,0]
	v_pk_mul_f32 v[30:31], v[30:31], v[136:137] op_sel_hi:[1,0]
	v_pk_mul_f32 v[28:29], v[28:29], v[136:137] op_sel_hi:[1,0]
	v_pk_mul_f32 v[26:27], v[26:27], v[136:137] op_sel_hi:[1,0]
	v_pk_mul_f32 v[24:25], v[24:25], v[136:137] op_sel_hi:[1,0]
	v_pk_mul_f32 v[22:23], v[22:23], v[136:137] op_sel_hi:[1,0]
	v_pk_mul_f32 v[20:21], v[20:21], v[136:137] op_sel_hi:[1,0]
	v_pk_mul_f32 v[18:19], v[18:19], v[136:137] op_sel_hi:[1,0]
	v_pk_mul_f32 v[16:17], v[16:17], v[136:137] op_sel_hi:[1,0]
	v_pk_mul_f32 v[14:15], v[14:15], v[136:137] op_sel_hi:[1,0]
	v_pk_mul_f32 v[12:13], v[12:13], v[136:137] op_sel_hi:[1,0]
	v_pk_mul_f32 v[10:11], v[10:11], v[136:137] op_sel_hi:[1,0]
	v_pk_mul_f32 v[8:9], v[8:9], v[136:137] op_sel_hi:[1,0]
	v_pk_mul_f32 v[6:7], v[6:7], v[136:137] op_sel_hi:[1,0]
	v_pk_mul_f32 v[4:5], v[4:5], v[136:137] op_sel_hi:[1,0]
	v_pk_mul_f32 v[2:3], v[2:3], v[136:137] op_sel_hi:[1,0]
	s_branch .LBB0_580

; __device__ __forceinline__ void fx_add(float* p, size_t idx, float s) { atomicAdd((unsigned long long*)p + idx, (unsigned long long)(long long)(s * 4294967296.0f)); }
; __device__ __forceinline__ unsigned cvtpk(float lo, float hi) { f32x2v_ v = {lo, hi}; bf16x2v_ b = __builtin_convertvector(v, bf16x2v_); return __builtin_bit_cast(unsigned, b); }
;     __device__ __forceinline__ void operator()(const f32x4 (&acc)[2][2][4][2], const Unit& u, int wr, int wc, int fr, int fq) const {
;     ...
;             for (int m = 0; m < 4; ++m) { const int row = row0 + ai * HALF + m * 16; const size_t off = (size_t)row * 1024 + col0; float s = 0.f;
; #pragma unroll
;                 for (int bj = 0; bj < 2; ++bj) { f32x4 a0, a1;
;                     if (xin32) { const float* p = xin32 + off + bj * HALF; a0 = *(const f32x4*)p; a1 = *(const f32x4*)(p + 4); }
;                     else { const u32x4 w = *(const u32x4*)(xb + off + bj * HALF);
;                         a0 = (f32x4){__uint_as_float(w.x << 16), __uint_as_float(w.x & 0xffff0000u), __uint_as_float(w.y << 16), __uint_as_float(w.y & 0xffff0000u)};
;                         a1 = (f32x4){__uint_as_float(w.z << 16), __uint_as_float(w.z & 0xffff0000u), __uint_as_float(w.w << 16), __uint_as_float(w.w & 0xffff0000u)}; }
;                     const f32x4 v0 = a0 + acc[ai][bj][m][0] * alpha, v1 = a1 + acc[ai][bj][m][1] * alpha;
;                     u32x4 w; w.x = cvtpk(v0[0], v0[1]); w.y = cvtpk(v0[2], v0[3]); w.z = cvtpk(v1[0], v1[1]); w.w = cvtpk(v1[2], v1[3]);
;                     *(u32x4*)(xb + off + bj * HALF) = w;
;                     s += (v0[0] * v0[0] + v0[1] * v0[1]) + (v0[2] * v0[2] + v0[3] * v0[3]) + (v1[0] * v1[0] + v1[1] * v1[1]) + (v1[2] * v1[2] + v1[3] * v1[3]); }
;                 s += __shfl_xor(s, 16); s += __shfl_xor(s, 32);
;                 if (fq == 0) fx_add(ssout, row, s); }
.LBB0_1038:
	v_lshl_add_u32 v146, s74, 8, v148
	v_ashrrev_i32_e32 v147, 31, v146
	v_lshl_or_b32 v144, s67, 8, v150
	v_lshlrev_b64 v[156:157], 11, v[146:147]
	v_ashrrev_i32_e32 v145, 31, v144
	v_lshl_add_u64 v[156:157], s[22:23], 0, v[156:157]
	v_lshl_add_u64 v[166:167], v[144:145], 1, v[156:157]
	global_load_dwordx4 v[158:161], v[166:167], off
	global_load_dwordx4 v[162:165], v[166:167], off offset:256
	v_and_b32_e32 v156, 64, v154
	v_xor_b32_e32 v155, 16, v154
	v_add_u32_e32 v156, 64, v156
	v_xor_b32_e32 v157, 32, v154
	v_cmp_lt_i32_e32 vcc, v155, v156
	s_waitcnt vmcnt(0)
	v_lshlrev_b32_e32 v168, 16, v158
	v_cndmask_b32_e32 v155, v154, v155, vcc
	v_cmp_lt_i32_e32 vcc, v157, v156
	v_and_b32_e32 v169, 0xffff0000, v158
	v_lshlrev_b32_e32 v158, 16, v159
	v_and_b32_e32 v159, 0xffff0000, v159
	v_lshlrev_b32_e32 v172, 16, v162
	v_and_b32_e32 v173, 0xffff0000, v162
	v_lshlrev_b32_e32 v162, 16, v163
	v_and_b32_e32 v163, 0xffff0000, v163
	v_cndmask_b32_e32 v157, v154, v157, vcc
	v_lshlrev_b32_e32 v170, 16, v160
	v_and_b32_e32 v171, 0xffff0000, v160
	v_lshlrev_b32_e32 v160, 16, v161
	v_and_b32_e32 v161, 0xffff0000, v161
	v_lshlrev_b32_e32 v174, 16, v164
	v_and_b32_e32 v175, 0xffff0000, v164
	v_lshlrev_b32_e32 v164, 16, v165
	v_and_b32_e32 v165, 0xffff0000, v165
	v_fma_f32 v126, v126, 0.5, v158
	v_fma_f32 v127, v127, 0.5, v159
	v_fma_f32 v124, v124, 0.5, v168
	v_fma_f32 v125, v125, 0.5, v169
	v_fma_f32 v118, v118, 0.5, v162
	v_fma_f32 v119, v119, 0.5, v163
	v_fma_f32 v116, v116, 0.5, v172
	v_fma_f32 v117, v117, 0.5, v173
	v_lshlrev_b32_e32 v156, 2, v155
	v_lshlrev_b32_e32 v155, 2, v157
	v_fma_f32 v122, v122, 0.5, v160
	v_fma_f32 v123, v123, 0.5, v161
	v_fma_f32 v120, v120, 0.5, v170
	v_fma_f32 v121, v121, 0.5, v171
	v_fma_f32 v158, v114, 0.5, v164
	v_fma_f32 v159, v115, 0.5, v165
	v_fma_f32 v160, v112, 0.5, v174
	v_fma_f32 v161, v113, 0.5, v175
	v_mul_f32_e32 v114, v125, v125
	v_mul_f32_e32 v115, v127, v127
	v_mul_f32_e32 v157, v117, v117
	v_mul_f32_e32 v162, v119, v119
	v_cvt_pk_bf16_f32 v112, v124, v125
	v_mul_f32_e32 v125, v121, v121
	v_mul_f32_e32 v163, v161, v161
	v_fmac_f32_e32 v114, v124, v124
	v_fmac_f32_e32 v115, v126, v126
	v_fmac_f32_e32 v157, v116, v116
	v_fmac_f32_e32 v162, v118, v118
	v_cvt_pk_bf16_f32 v113, v126, v127
	v_mul_f32_e32 v127, v123, v123
	v_mul_f32_e32 v164, v159, v159
	v_fmac_f32_e32 v125, v120, v120
	v_fmac_f32_e32 v163, v160, v160
	v_add_f32_e32 v114, v114, v115
	v_add_f32_e32 v115, v157, v162
	v_fmac_f32_e32 v127, v122, v122
	v_fmac_f32_e32 v164, v158, v158
	v_add_f32_e32 v114, v125, v114
	v_add_f32_e32 v115, v163, v115
	v_add_f32_e32 v114, v127, v114
	v_add_f32_e32 v115, v164, v115
	v_add_f32_e32 v124, v114, v115
	ds_bpermute_b32 v125, v156, v124
	v_cvt_pk_bf16_f32 v114, v120, v121
	v_cvt_pk_bf16_f32 v115, v122, v123
	global_store_dwordx4 v[166:167], v[112:115], off
	s_waitcnt lgkmcnt(0)
	s_nop 0
	v_add_f32_e32 v112, v124, v125
	ds_bpermute_b32 v113, v155, v112
	v_cvt_pk_bf16_f32 v114, v116, v117
	v_cvt_pk_bf16_f32 v115, v118, v119
	v_cvt_pk_bf16_f32 v116, v160, v161
	v_cvt_pk_bf16_f32 v117, v158, v159
	global_store_dwordx4 v[166:167], v[114:117], off offset:256
	s_and_saveexec_b64 s[50:51], s[10:11]
	s_cbranch_execz .LBB0_1040
	s_waitcnt lgkmcnt(0)
	v_add_f32_e32 v112, v112, v113
	v_mul_f32_e32 v112, 0x4f800000, v112
	v_trunc_f32_e32 v112, v112
	v_mul_f32_e64 v113, |v112|, s63
	v_floor_f32_e32 v113, v113
	v_fma_f32 v114, v113, s64, |v112|
	v_cvt_u32_f32_e32 v114, v114
	v_cvt_u32_f32_e32 v113, v113
	v_ashrrev_i32_e32 v115, 31, v112
	v_xor_b32_e32 v112, v114, v115
	v_xor_b32_e32 v113, v113, v115
	v_sub_co_u32_e32 v112, vcc, v112, v115
	s_nop 1
	v_subb_co_u32_e32 v113, vcc, v113, v115, vcc
	v_lshl_add_u64 v[114:115], v[146:147], 3, s[36:37]
	global_atomic_add_x2 v[114:115], v[112:113], off
.LBB0_1040:
	s_or_b64 exec, exec, s[50:51]
	v_or_b32_e32 v112, 16, v146
	s_waitcnt lgkmcnt(0)
	v_ashrrev_i32_e32 v113, 31, v112
	v_lshlrev_b64 v[114:115], 11, v[112:113]
	v_lshl_add_u64 v[114:115], s[22:23], 0, v[114:115]
	v_lshl_add_u64 v[122:123], v[144:145], 1, v[114:115]
	global_load_dwordx4 v[114:117], v[122:123], off
	global_load_dwordx4 v[118:121], v[122:123], off offset:256
	s_waitcnt vmcnt(1)
	v_lshlrev_b32_e32 v124, 16, v114
	v_and_b32_e32 v125, 0xffff0000, v114
	v_lshlrev_b32_e32 v114, 16, v115
	v_and_b32_e32 v115, 0xffff0000, v115
	s_waitcnt vmcnt(0)
	v_lshlrev_b32_e32 v158, 16, v118
	v_and_b32_e32 v159, 0xffff0000, v118
	v_lshlrev_b32_e32 v118, 16, v119
	v_and_b32_e32 v119, 0xffff0000, v119
	v_lshlrev_b32_e32 v126, 16, v116
	v_and_b32_e32 v127, 0xffff0000, v116
	v_lshlrev_b32_e32 v116, 16, v117
	v_and_b32_e32 v117, 0xffff0000, v117
	v_lshlrev_b32_e32 v160, 16, v120
	v_and_b32_e32 v161, 0xffff0000, v120
	v_lshlrev_b32_e32 v120, 16, v121
	v_and_b32_e32 v121, 0xffff0000, v121
	v_fma_f32 v110, v110, 0.5, v114
	v_fma_f32 v111, v111, 0.5, v115
	v_fma_f32 v108, v108, 0.5, v124
	v_fma_f32 v109, v109, 0.5, v125
	v_fma_f32 v102, v102, 0.5, v118
	v_fma_f32 v103, v103, 0.5, v119
	v_fma_f32 v100, v100, 0.5, v158
	v_fma_f32 v101, v101, 0.5, v159
	v_fma_f32 v106, v106, 0.5, v116
	v_fma_f32 v107, v107, 0.5, v117
	v_fma_f32 v104, v104, 0.5, v126
	v_fma_f32 v105, v105, 0.5, v127
	v_fma_f32 v114, v98, 0.5, v120
	v_fma_f32 v115, v99, 0.5, v121
	v_fma_f32 v116, v96, 0.5, v160
	v_fma_f32 v117, v97, 0.5, v161
	v_mul_f32_e32 v98, v109, v109
	v_mul_f32_e32 v99, v111, v111
	v_mul_f32_e32 v118, v101, v101
	v_mul_f32_e32 v119, v103, v103
	v_cvt_pk_bf16_f32 v96, v108, v109
	v_mul_f32_e32 v109, v105, v105
	v_mul_f32_e32 v120, v117, v117
	v_fmac_f32_e32 v98, v108, v108
	v_fmac_f32_e32 v99, v110, v110
	v_fmac_f32_e32 v118, v100, v100
	v_fmac_f32_e32 v119, v102, v102
	v_cvt_pk_bf16_f32 v97, v110, v111
	v_mul_f32_e32 v111, v107, v107
	v_mul_f32_e32 v121, v115, v115
	v_fmac_f32_e32 v109, v104, v104
	v_fmac_f32_e32 v120, v116, v116
	v_add_f32_e32 v98, v98, v99
	v_add_f32_e32 v99, v118, v119
	v_fmac_f32_e32 v111, v106, v106
	v_fmac_f32_e32 v121, v114, v114
	v_add_f32_e32 v98, v109, v98
	v_add_f32_e32 v99, v120, v99
	v_add_f32_e32 v98, v111, v98
	v_add_f32_e32 v99, v121, v99
	v_add_f32_e32 v108, v98, v99
	ds_bpermute_b32 v109, v156, v108
	v_cvt_pk_bf16_f32 v98, v104, v105
	v_cvt_pk_bf16_f32 v99, v106, v107
	global_store_dwordx4 v[122:123], v[96:99], off
	s_waitcnt lgkmcnt(0)
	s_nop 0
	v_add_f32_e32 v96, v108, v109
	ds_bpermute_b32 v97, v155, v96
	v_cvt_pk_bf16_f32 v98, v100, v101
	v_cvt_pk_bf16_f32 v99, v102, v103
	v_cvt_pk_bf16_f32 v100, v116, v117
	v_cvt_pk_bf16_f32 v101, v114, v115
	global_store_dwordx4 v[122:123], v[98:101], off offset:256
	s_and_saveexec_b64 s[50:51], s[10:11]
	s_cbranch_execz .LBB0_1042
; __device__ __forceinline__ void fx_add(float* p, size_t idx, float s) { atomicAdd((unsigned long long*)p + idx, (unsigned long long)(long long)(s * 4294967296.0f)); }
; __device__ __forceinline__ unsigned cvtpk(float lo, float hi) { f32x2v_ v = {lo, hi}; bf16x2v_ b = __builtin_convertvector(v, bf16x2v_); return __builtin_bit_cast(unsigned, b); }
;     __device__ __forceinline__ void operator()(const f32x4 (&acc)[2][2][4][2], const Unit& u, int wr, int wc, int fr, int fq) const {
;     ...
;             for (int m = 0; m < 4; ++m) { const int row = row0 + ai * HALF + m * 16; const size_t off = (size_t)row * 1024 + col0; float s = 0.f;
; #pragma unroll
;                 for (int bj = 0; bj < 2; ++bj) { f32x4 a0, a1;
;                     if (xin32) { const float* p = xin32 + off + bj * HALF; a0 = *(const f32x4*)p; a1 = *(const f32x4*)(p + 4); }
;                     else { const u32x4 w = *(const u32x4*)(xb + off + bj * HALF);
;                         a0 = (f32x4){__uint_as_float(w.x << 16), __uint_as_float(w.x & 0xffff0000u), __uint_as_float(w.y << 16), __uint_as_float(w.y & 0xffff0000u)};
;                         a1 = (f32x4){__uint_as_float(w.z << 16), __uint_as_float(w.z & 0xffff0000u), __uint_as_float(w.w << 16), __uint_as_float(w.w & 0xffff0000u)}; }
;                     const f32x4 v0 = a0 + acc[ai][bj][m][0] * alpha, v1 = a1 + acc[ai][bj][m][1] * alpha;
;                     u32x4 w; w.x = cvtpk(v0[0], v0[1]); w.y = cvtpk(v0[2], v0[3]); w.z = cvtpk(v1[0], v1[1]); w.w = cvtpk(v1[2], v1[3]);
;                     *(u32x4*)(xb + off + bj * HALF) = w;
;                     s += (v0[0] * v0[0] + v0[1] * v0[1]) + (v0[2] * v0[2] + v0[3] * v0[3]) + (v1[0] * v1[0] + v1[1] * v1[1]) + (v1[2] * v1[2] + v1[3] * v1[3]); }
;                 s += __shfl_xor(s, 16); s += __shfl_xor(s, 32);
;                 if (fq == 0) fx_add(ssout, row, s); }
	s_waitcnt lgkmcnt(0)
	v_add_f32_e32 v96, v96, v97
	v_mul_f32_e32 v96, 0x4f800000, v96
	v_trunc_f32_e32 v96, v96
	v_mul_f32_e64 v97, |v96|, s63
	v_floor_f32_e32 v97, v97
	v_fma_f32 v98, v97, s64, |v96|
	v_cvt_u32_f32_e32 v98, v98
	v_cvt_u32_f32_e32 v97, v97
	v_ashrrev_i32_e32 v99, 31, v96
	v_xor_b32_e32 v96, v98, v99
	v_xor_b32_e32 v97, v97, v99
	v_sub_co_u32_e32 v96, vcc, v96, v99
	s_nop 1
	v_subb_co_u32_e32 v97, vcc, v97, v99, vcc
	v_lshl_add_u64 v[98:99], v[112:113], 3, s[36:37]
	global_atomic_add_x2 v[98:99], v[96:97], off
.LBB0_1042:
	s_or_b64 exec, exec, s[50:51]
	v_or_b32_e32 v96, 32, v146
	s_waitcnt lgkmcnt(0)
	v_ashrrev_i32_e32 v97, 31, v96
	v_lshlrev_b64 v[98:99], 11, v[96:97]
	v_lshl_add_u64 v[98:99], s[22:23], 0, v[98:99]
	v_lshl_add_u64 v[106:107], v[144:145], 1, v[98:99]
	global_load_dwordx4 v[98:101], v[106:107], off
	global_load_dwordx4 v[102:105], v[106:107], off offset:256
	s_waitcnt vmcnt(1)
	v_lshlrev_b32_e32 v108, 16, v98
	v_and_b32_e32 v109, 0xffff0000, v98
	v_lshlrev_b32_e32 v98, 16, v99
	v_and_b32_e32 v99, 0xffff0000, v99
	s_waitcnt vmcnt(0)
	v_lshlrev_b32_e32 v112, 16, v102
	v_and_b32_e32 v113, 0xffff0000, v102
	v_lshlrev_b32_e32 v102, 16, v103
	v_and_b32_e32 v103, 0xffff0000, v103
	v_lshlrev_b32_e32 v110, 16, v100
	v_and_b32_e32 v111, 0xffff0000, v100
	v_lshlrev_b32_e32 v100, 16, v101
	v_and_b32_e32 v101, 0xffff0000, v101
	v_lshlrev_b32_e32 v114, 16, v104
	v_and_b32_e32 v115, 0xffff0000, v104
	v_lshlrev_b32_e32 v104, 16, v105
	v_and_b32_e32 v105, 0xffff0000, v105
	v_fma_f32 v94, v94, 0.5, v98
	v_fma_f32 v95, v95, 0.5, v99
	v_fma_f32 v92, v92, 0.5, v108
	v_fma_f32 v93, v93, 0.5, v109
	v_fma_f32 v86, v86, 0.5, v102
	v_fma_f32 v87, v87, 0.5, v103
	v_fma_f32 v84, v84, 0.5, v112
	v_fma_f32 v85, v85, 0.5, v113
	v_fma_f32 v90, v90, 0.5, v100
	v_fma_f32 v91, v91, 0.5, v101
	v_fma_f32 v88, v88, 0.5, v110
	v_fma_f32 v89, v89, 0.5, v111
	v_fma_f32 v98, v82, 0.5, v104
	v_fma_f32 v99, v83, 0.5, v105
	v_fma_f32 v100, v80, 0.5, v114
	v_fma_f32 v101, v81, 0.5, v115
	v_mul_f32_e32 v82, v93, v93
	v_mul_f32_e32 v83, v95, v95
	v_mul_f32_e32 v102, v85, v85
	v_mul_f32_e32 v103, v87, v87
	v_cvt_pk_bf16_f32 v80, v92, v93
	v_mul_f32_e32 v93, v89, v89
	v_mul_f32_e32 v104, v101, v101
	v_fmac_f32_e32 v82, v92, v92
	v_fmac_f32_e32 v83, v94, v94
	v_fmac_f32_e32 v102, v84, v84
	v_fmac_f32_e32 v103, v86, v86
	v_cvt_pk_bf16_f32 v81, v94, v95
	v_mul_f32_e32 v95, v91, v91
	v_mul_f32_e32 v105, v99, v99
	v_fmac_f32_e32 v93, v88, v88
	v_fmac_f32_e32 v104, v100, v100
	v_add_f32_e32 v82, v82, v83
	v_add_f32_e32 v83, v102, v103
	v_fmac_f32_e32 v95, v90, v90
	v_fmac_f32_e32 v105, v98, v98
	v_add_f32_e32 v82, v93, v82
	v_add_f32_e32 v83, v104, v83
	v_add_f32_e32 v82, v95, v82
	v_add_f32_e32 v83, v105, v83
	v_add_f32_e32 v92, v82, v83
	ds_bpermute_b32 v93, v156, v92
	v_cvt_pk_bf16_f32 v82, v88, v89
	v_cvt_pk_bf16_f32 v83, v90, v91
	global_store_dwordx4 v[106:107], v[80:83], off
	s_waitcnt lgkmcnt(0)
	s_nop 0
	v_add_f32_e32 v80, v92, v93
	ds_bpermute_b32 v81, v155, v80
	v_cvt_pk_bf16_f32 v82, v84, v85
	v_cvt_pk_bf16_f32 v83, v86, v87
	v_cvt_pk_bf16_f32 v84, v100, v101
	v_cvt_pk_bf16_f32 v85, v98, v99
	global_store_dwordx4 v[106:107], v[82:85], off offset:256
	s_and_saveexec_b64 s[50:51], s[10:11]
	s_cbranch_execz .LBB0_1044
	s_waitcnt lgkmcnt(0)
	v_add_f32_e32 v80, v80, v81
	v_mul_f32_e32 v80, 0x4f800000, v80
	v_trunc_f32_e32 v80, v80
	v_mul_f32_e64 v81, |v80|, s63
	v_floor_f32_e32 v81, v81
	v_fma_f32 v82, v81, s64, |v80|
	v_cvt_u32_f32_e32 v82, v82
	v_cvt_u32_f32_e32 v81, v81
	v_ashrrev_i32_e32 v83, 31, v80
	v_xor_b32_e32 v80, v82, v83
	v_xor_b32_e32 v81, v81, v83
	v_sub_co_u32_e32 v80, vcc, v80, v83
	s_nop 1
	v_subb_co_u32_e32 v81, vcc, v81, v83, vcc
	v_lshl_add_u64 v[82:83], v[96:97], 3, s[36:37]
	global_atomic_add_x2 v[82:83], v[80:81], off
.LBB0_1044:
	s_or_b64 exec, exec, s[50:51]
	v_or_b32_e32 v80, 48, v146
	s_waitcnt lgkmcnt(0)
	v_ashrrev_i32_e32 v81, 31, v80
	v_lshlrev_b64 v[82:83], 11, v[80:81]
	v_lshl_add_u64 v[82:83], s[22:23], 0, v[82:83]
	v_lshl_add_u64 v[90:91], v[144:145], 1, v[82:83]
	global_load_dwordx4 v[82:85], v[90:91], off
	global_load_dwordx4 v[86:89], v[90:91], off offset:256
	s_waitcnt vmcnt(1)
	v_lshlrev_b32_e32 v92, 16, v82
	v_and_b32_e32 v93, 0xffff0000, v82
	v_lshlrev_b32_e32 v82, 16, v83
	v_and_b32_e32 v83, 0xffff0000, v83
	s_waitcnt vmcnt(0)
	v_lshlrev_b32_e32 v96, 16, v86
	v_and_b32_e32 v97, 0xffff0000, v86
	v_lshlrev_b32_e32 v86, 16, v87
	v_and_b32_e32 v87, 0xffff0000, v87
	v_lshlrev_b32_e32 v94, 16, v84
	v_and_b32_e32 v95, 0xffff0000, v84
	v_lshlrev_b32_e32 v84, 16, v85
	v_and_b32_e32 v85, 0xffff0000, v85
	v_lshlrev_b32_e32 v98, 16, v88
	v_and_b32_e32 v99, 0xffff0000, v88
	v_lshlrev_b32_e32 v88, 16, v89
	v_and_b32_e32 v89, 0xffff0000, v89
	v_fma_f32 v78, v78, 0.5, v82
	v_fma_f32 v79, v79, 0.5, v83
	v_fma_f32 v76, v76, 0.5, v92
	v_fma_f32 v77, v77, 0.5, v93
	v_fma_f32 v70, v70, 0.5, v86
	v_fma_f32 v71, v71, 0.5, v87
	v_fma_f32 v68, v68, 0.5, v96
	v_fma_f32 v69, v69, 0.5, v97
	v_fma_f32 v74, v74, 0.5, v84
	v_fma_f32 v75, v75, 0.5, v85
	v_fma_f32 v72, v72, 0.5, v94
	v_fma_f32 v73, v73, 0.5, v95
	v_fma_f32 v82, v66, 0.5, v88
	v_fma_f32 v83, v67, 0.5, v89
	v_fma_f32 v84, v64, 0.5, v98
	v_fma_f32 v85, v65, 0.5, v99
	v_mul_f32_e32 v66, v77, v77
	v_mul_f32_e32 v67, v79, v79
	v_mul_f32_e32 v86, v69, v69
	v_mul_f32_e32 v87, v71, v71
	v_cvt_pk_bf16_f32 v64, v76, v77
	v_mul_f32_e32 v77, v73, v73
	v_mul_f32_e32 v88, v85, v85
	v_fmac_f32_e32 v66, v76, v76
	v_fmac_f32_e32 v67, v78, v78
	v_fmac_f32_e32 v86, v68, v68
	v_fmac_f32_e32 v87, v70, v70
	v_cvt_pk_bf16_f32 v65, v78, v79
	v_mul_f32_e32 v79, v75, v75
	v_mul_f32_e32 v89, v83, v83
	v_fmac_f32_e32 v77, v72, v72
	v_fmac_f32_e32 v88, v84, v84
	v_add_f32_e32 v66, v66, v67
	v_add_f32_e32 v67, v86, v87
	v_fmac_f32_e32 v79, v74, v74
	v_fmac_f32_e32 v89, v82, v82
	v_add_f32_e32 v66, v77, v66
	v_add_f32_e32 v67, v88, v67
	v_add_f32_e32 v66, v79, v66
	v_add_f32_e32 v67, v89, v67
	v_add_f32_e32 v76, v66, v67
	ds_bpermute_b32 v77, v156, v76
	v_cvt_pk_bf16_f32 v66, v72, v73
	v_cvt_pk_bf16_f32 v67, v74, v75
	global_store_dwordx4 v[90:91], v[64:67], off
	s_waitcnt lgkmcnt(0)
	s_nop 0
	v_add_f32_e32 v64, v76, v77
	ds_bpermute_b32 v65, v155, v64
	v_cvt_pk_bf16_f32 v66, v68, v69
	v_cvt_pk_bf16_f32 v67, v70, v71
	v_cvt_pk_bf16_f32 v68, v84, v85
	v_cvt_pk_bf16_f32 v69, v82, v83
	global_store_dwordx4 v[90:91], v[66:69], off offset:256
	s_and_saveexec_b64 s[50:51], s[10:11]
	s_cbranch_execz .LBB0_1046
	s_waitcnt lgkmcnt(0)
	v_add_f32_e32 v64, v64, v65
	v_mul_f32_e32 v64, 0x4f800000, v64
	v_trunc_f32_e32 v64, v64
	v_mul_f32_e64 v65, |v64|, s63
	v_floor_f32_e32 v65, v65
	v_fma_f32 v66, v65, s64, |v64|
	v_cvt_u32_f32_e32 v66, v66
	v_cvt_u32_f32_e32 v65, v65
	v_ashrrev_i32_e32 v67, 31, v64
	v_xor_b32_e32 v64, v66, v67
	v_xor_b32_e32 v65, v65, v67
	v_sub_co_u32_e32 v64, vcc, v64, v67
	s_nop 1
	v_subb_co_u32_e32 v65, vcc, v65, v67, vcc
	v_lshl_add_u64 v[66:67], v[80:81], 3, s[36:37]
	global_atomic_add_x2 v[66:67], v[64:65], off
; __device__ __forceinline__ void fx_add(float* p, size_t idx, float s) { atomicAdd((unsigned long long*)p + idx, (unsigned long long)(long long)(s * 4294967296.0f)); }
; __device__ __forceinline__ unsigned cvtpk(float lo, float hi) { f32x2v_ v = {lo, hi}; bf16x2v_ b = __builtin_convertvector(v, bf16x2v_); return __builtin_bit_cast(unsigned, b); }
;     __device__ __forceinline__ void operator()(const f32x4 (&acc)[2][2][4][2], const Unit& u, int wr, int wc, int fr, int fq) const {
;     ...
;             for (int m = 0; m < 4; ++m) { const int row = row0 + ai * HALF + m * 16; const size_t off = (size_t)row * 1024 + col0; float s = 0.f;
; #pragma unroll
;                 for (int bj = 0; bj < 2; ++bj) { f32x4 a0, a1;
;                     if (xin32) { const float* p = xin32 + off + bj * HALF; a0 = *(const f32x4*)p; a1 = *(const f32x4*)(p + 4); }
;                     else { const u32x4 w = *(const u32x4*)(xb + off + bj * HALF);
;                         a0 = (f32x4){__uint_as_float(w.x << 16), __uint_as_float(w.x & 0xffff0000u), __uint_as_float(w.y << 16), __uint_as_float(w.y & 0xffff0000u)};
;                         a1 = (f32x4){__uint_as_float(w.z << 16), __uint_as_float(w.z & 0xffff0000u), __uint_as_float(w.w << 16), __uint_as_float(w.w & 0xffff0000u)}; }
;                     const f32x4 v0 = a0 + acc[ai][bj][m][0] * alpha, v1 = a1 + acc[ai][bj][m][1] * alpha;
;                     u32x4 w; w.x = cvtpk(v0[0], v0[1]); w.y = cvtpk(v0[2], v0[3]); w.z = cvtpk(v1[0], v1[1]); w.w = cvtpk(v1[2], v1[3]);
;                     *(u32x4*)(xb + off + bj * HALF) = w;
;                     s += (v0[0] * v0[0] + v0[1] * v0[1]) + (v0[2] * v0[2] + v0[3] * v0[3]) + (v1[0] * v1[0] + v1[1] * v1[1]) + (v1[2] * v1[2] + v1[3] * v1[3]); }
;                 s += __shfl_xor(s, 16); s += __shfl_xor(s, 32);
;                 if (fq == 0) fx_add(ssout, row, s); }
.LBB0_1046:
	s_or_b64 exec, exec, s[50:51]
	v_add_u32_e32 v64, 0x80, v146
	s_waitcnt lgkmcnt(0)
	v_ashrrev_i32_e32 v65, 31, v64
	v_lshlrev_b64 v[66:67], 11, v[64:65]
	v_lshl_add_u64 v[66:67], s[22:23], 0, v[66:67]
	v_lshl_add_u64 v[74:75], v[144:145], 1, v[66:67]
	global_load_dwordx4 v[66:69], v[74:75], off
	global_load_dwordx4 v[70:73], v[74:75], off offset:256
	s_waitcnt vmcnt(1)
	v_lshlrev_b32_e32 v76, 16, v66
	v_and_b32_e32 v77, 0xffff0000, v66
	v_lshlrev_b32_e32 v66, 16, v67
	v_and_b32_e32 v67, 0xffff0000, v67
	s_waitcnt vmcnt(0)
	v_lshlrev_b32_e32 v80, 16, v70
	v_and_b32_e32 v81, 0xffff0000, v70
	v_lshlrev_b32_e32 v70, 16, v71
	v_and_b32_e32 v71, 0xffff0000, v71
	v_lshlrev_b32_e32 v78, 16, v68
	v_and_b32_e32 v79, 0xffff0000, v68
	v_lshlrev_b32_e32 v68, 16, v69
	v_and_b32_e32 v69, 0xffff0000, v69
	v_lshlrev_b32_e32 v82, 16, v72
	v_and_b32_e32 v83, 0xffff0000, v72
	v_lshlrev_b32_e32 v72, 16, v73
	v_and_b32_e32 v73, 0xffff0000, v73
	v_fma_f32 v62, v62, 0.5, v66
	v_fma_f32 v63, v63, 0.5, v67
	v_fma_f32 v60, v60, 0.5, v76
	v_fma_f32 v61, v61, 0.5, v77
	v_fma_f32 v54, v54, 0.5, v70
	v_fma_f32 v55, v55, 0.5, v71
	v_fma_f32 v52, v52, 0.5, v80
	v_fma_f32 v53, v53, 0.5, v81
	v_fma_f32 v58, v58, 0.5, v68
	v_fma_f32 v59, v59, 0.5, v69
	v_fma_f32 v56, v56, 0.5, v78
	v_fma_f32 v57, v57, 0.5, v79
	v_fma_f32 v66, v50, 0.5, v72
	v_fma_f32 v67, v51, 0.5, v73
	v_fma_f32 v68, v48, 0.5, v82
	v_fma_f32 v69, v49, 0.5, v83
	v_mul_f32_e32 v50, v61, v61
	v_mul_f32_e32 v51, v63, v63
	v_mul_f32_e32 v70, v53, v53
	v_mul_f32_e32 v71, v55, v55
	v_cvt_pk_bf16_f32 v48, v60, v61
	v_mul_f32_e32 v61, v57, v57
	v_mul_f32_e32 v72, v69, v69
	v_fmac_f32_e32 v50, v60, v60
	v_fmac_f32_e32 v51, v62, v62
	v_fmac_f32_e32 v70, v52, v52
	v_fmac_f32_e32 v71, v54, v54
	v_cvt_pk_bf16_f32 v49, v62, v63
	v_mul_f32_e32 v63, v59, v59
	v_mul_f32_e32 v73, v67, v67
	v_fmac_f32_e32 v61, v56, v56
	v_fmac_f32_e32 v72, v68, v68
	v_add_f32_e32 v50, v50, v51
	v_add_f32_e32 v51, v70, v71
	v_fmac_f32_e32 v63, v58, v58
	v_fmac_f32_e32 v73, v66, v66
	v_add_f32_e32 v50, v61, v50
	v_add_f32_e32 v51, v72, v51
	v_add_f32_e32 v50, v63, v50
	v_add_f32_e32 v51, v73, v51
	v_add_f32_e32 v60, v50, v51
	ds_bpermute_b32 v61, v156, v60
	v_cvt_pk_bf16_f32 v50, v56, v57
	v_cvt_pk_bf16_f32 v51, v58, v59
	global_store_dwordx4 v[74:75], v[48:51], off
	s_waitcnt lgkmcnt(0)
	s_nop 0
	v_add_f32_e32 v48, v60, v61
	ds_bpermute_b32 v49, v155, v48
	v_cvt_pk_bf16_f32 v50, v52, v53
	v_cvt_pk_bf16_f32 v51, v54, v55
	v_cvt_pk_bf16_f32 v52, v68, v69
	v_cvt_pk_bf16_f32 v53, v66, v67
	global_store_dwordx4 v[74:75], v[50:53], off offset:256
	s_and_saveexec_b64 s[50:51], s[10:11]
	s_cbranch_execz .LBB0_1048
	s_waitcnt lgkmcnt(0)
	v_add_f32_e32 v48, v48, v49
	v_mul_f32_e32 v48, 0x4f800000, v48
	v_trunc_f32_e32 v48, v48
	v_mul_f32_e64 v49, |v48|, s63
	v_floor_f32_e32 v49, v49
	v_fma_f32 v50, v49, s64, |v48|
	v_cvt_u32_f32_e32 v50, v50
	v_cvt_u32_f32_e32 v49, v49
	v_ashrrev_i32_e32 v51, 31, v48
	v_xor_b32_e32 v48, v50, v51
	v_xor_b32_e32 v49, v49, v51
	v_sub_co_u32_e32 v48, vcc, v48, v51
	s_nop 1
	v_subb_co_u32_e32 v49, vcc, v49, v51, vcc
	v_lshl_add_u64 v[50:51], v[64:65], 3, s[36:37]
	global_atomic_add_x2 v[50:51], v[48:49], off
.LBB0_1048:
	s_or_b64 exec, exec, s[50:51]
	v_add_u32_e32 v48, 0x90, v146
	s_waitcnt lgkmcnt(0)
	v_ashrrev_i32_e32 v49, 31, v48
	v_lshlrev_b64 v[50:51], 11, v[48:49]
	v_lshl_add_u64 v[50:51], s[22:23], 0, v[50:51]
	v_lshl_add_u64 v[58:59], v[144:145], 1, v[50:51]
	global_load_dwordx4 v[50:53], v[58:59], off
	global_load_dwordx4 v[54:57], v[58:59], off offset:256
	s_waitcnt vmcnt(1)
	v_lshlrev_b32_e32 v60, 16, v50
	v_and_b32_e32 v61, 0xffff0000, v50
	v_lshlrev_b32_e32 v50, 16, v51
	v_and_b32_e32 v51, 0xffff0000, v51
	s_waitcnt vmcnt(0)
	v_lshlrev_b32_e32 v64, 16, v54
	v_and_b32_e32 v65, 0xffff0000, v54
	v_lshlrev_b32_e32 v54, 16, v55
	v_and_b32_e32 v55, 0xffff0000, v55
	v_lshlrev_b32_e32 v62, 16, v52
	v_and_b32_e32 v63, 0xffff0000, v52
	v_lshlrev_b32_e32 v52, 16, v53
	v_and_b32_e32 v53, 0xffff0000, v53
	v_lshlrev_b32_e32 v66, 16, v56
	v_and_b32_e32 v67, 0xffff0000, v56
	v_lshlrev_b32_e32 v56, 16, v57
	v_and_b32_e32 v57, 0xffff0000, v57
	v_fma_f32 v46, v46, 0.5, v50
	v_fma_f32 v47, v47, 0.5, v51
	v_fma_f32 v44, v44, 0.5, v60
	v_fma_f32 v45, v45, 0.5, v61
	v_fma_f32 v38, v38, 0.5, v54
	v_fma_f32 v39, v39, 0.5, v55
	v_fma_f32 v36, v36, 0.5, v64
	v_fma_f32 v37, v37, 0.5, v65
	v_fma_f32 v42, v42, 0.5, v52
	v_fma_f32 v43, v43, 0.5, v53
	v_fma_f32 v40, v40, 0.5, v62
	v_fma_f32 v41, v41, 0.5, v63
	v_fma_f32 v50, v34, 0.5, v56
	v_fma_f32 v51, v35, 0.5, v57
	v_fma_f32 v52, v32, 0.5, v66
	v_fma_f32 v53, v33, 0.5, v67
	v_mul_f32_e32 v34, v45, v45
	v_mul_f32_e32 v35, v47, v47
	v_mul_f32_e32 v54, v37, v37
	v_mul_f32_e32 v55, v39, v39
	v_cvt_pk_bf16_f32 v32, v44, v45
	v_mul_f32_e32 v45, v41, v41
	v_mul_f32_e32 v56, v53, v53
	v_fmac_f32_e32 v34, v44, v44
	v_fmac_f32_e32 v35, v46, v46
	v_fmac_f32_e32 v54, v36, v36
	v_fmac_f32_e32 v55, v38, v38
	v_cvt_pk_bf16_f32 v33, v46, v47
	v_mul_f32_e32 v47, v43, v43
	v_mul_f32_e32 v57, v51, v51
	v_fmac_f32_e32 v45, v40, v40
	v_fmac_f32_e32 v56, v52, v52
	v_add_f32_e32 v34, v34, v35
	v_add_f32_e32 v35, v54, v55
	v_fmac_f32_e32 v47, v42, v42
	v_fmac_f32_e32 v57, v50, v50
	v_add_f32_e32 v34, v45, v34
	v_add_f32_e32 v35, v56, v35
	v_add_f32_e32 v34, v47, v34
	v_add_f32_e32 v35, v57, v35
	v_add_f32_e32 v44, v34, v35
	ds_bpermute_b32 v45, v156, v44
	v_cvt_pk_bf16_f32 v34, v40, v41
	v_cvt_pk_bf16_f32 v35, v42, v43
	global_store_dwordx4 v[58:59], v[32:35], off
	s_waitcnt lgkmcnt(0)
	s_nop 0
	v_add_f32_e32 v32, v44, v45
	ds_bpermute_b32 v33, v155, v32
	v_cvt_pk_bf16_f32 v34, v36, v37
	v_cvt_pk_bf16_f32 v35, v38, v39
	v_cvt_pk_bf16_f32 v36, v52, v53
	v_cvt_pk_bf16_f32 v37, v50, v51
	global_store_dwordx4 v[58:59], v[34:37], off offset:256
	s_and_saveexec_b64 s[50:51], s[10:11]
	s_cbranch_execz .LBB0_1050
	s_waitcnt lgkmcnt(0)
	v_add_f32_e32 v32, v32, v33
	v_mul_f32_e32 v32, 0x4f800000, v32
	v_trunc_f32_e32 v32, v32
	v_mul_f32_e64 v33, |v32|, s63
	v_floor_f32_e32 v33, v33
	v_fma_f32 v34, v33, s64, |v32|
	v_cvt_u32_f32_e32 v34, v34
	v_cvt_u32_f32_e32 v33, v33
	v_ashrrev_i32_e32 v35, 31, v32
	v_xor_b32_e32 v32, v34, v35
	v_xor_b32_e32 v33, v33, v35
	v_sub_co_u32_e32 v32, vcc, v32, v35
	s_nop 1
	v_subb_co_u32_e32 v33, vcc, v33, v35, vcc
	v_lshl_add_u64 v[34:35], v[48:49], 3, s[36:37]
	global_atomic_add_x2 v[34:35], v[32:33], off
; __device__ __forceinline__ void fx_add(float* p, size_t idx, float s) { atomicAdd((unsigned long long*)p + idx, (unsigned long long)(long long)(s * 4294967296.0f)); }
; __device__ __forceinline__ unsigned cvtpk(float lo, float hi) { f32x2v_ v = {lo, hi}; bf16x2v_ b = __builtin_convertvector(v, bf16x2v_); return __builtin_bit_cast(unsigned, b); }
;     __device__ __forceinline__ void operator()(const f32x4 (&acc)[2][2][4][2], const Unit& u, int wr, int wc, int fr, int fq) const {
;     ...
;             for (int m = 0; m < 4; ++m) { const int row = row0 + ai * HALF + m * 16; const size_t off = (size_t)row * 1024 + col0; float s = 0.f;
; #pragma unroll
;                 for (int bj = 0; bj < 2; ++bj) { f32x4 a0, a1;
;                     if (xin32) { const float* p = xin32 + off + bj * HALF; a0 = *(const f32x4*)p; a1 = *(const f32x4*)(p + 4); }
;                     else { const u32x4 w = *(const u32x4*)(xb + off + bj * HALF);
;                         a0 = (f32x4){__uint_as_float(w.x << 16), __uint_as_float(w.x & 0xffff0000u), __uint_as_float(w.y << 16), __uint_as_float(w.y & 0xffff0000u)};
;                         a1 = (f32x4){__uint_as_float(w.z << 16), __uint_as_float(w.z & 0xffff0000u), __uint_as_float(w.w << 16), __uint_as_float(w.w & 0xffff0000u)}; }
;                     const f32x4 v0 = a0 + acc[ai][bj][m][0] * alpha, v1 = a1 + acc[ai][bj][m][1] * alpha;
;                     u32x4 w; w.x = cvtpk(v0[0], v0[1]); w.y = cvtpk(v0[2], v0[3]); w.z = cvtpk(v1[0], v1[1]); w.w = cvtpk(v1[2], v1[3]);
;                     *(u32x4*)(xb + off + bj * HALF) = w;
;                     s += (v0[0] * v0[0] + v0[1] * v0[1]) + (v0[2] * v0[2] + v0[3] * v0[3]) + (v1[0] * v1[0] + v1[1] * v1[1]) + (v1[2] * v1[2] + v1[3] * v1[3]); }
;                 s += __shfl_xor(s, 16); s += __shfl_xor(s, 32);
;                 if (fq == 0) fx_add(ssout, row, s); }
.LBB0_1050:
	s_or_b64 exec, exec, s[50:51]
	v_add_u32_e32 v32, 0xa0, v146
	s_waitcnt lgkmcnt(0)
	v_ashrrev_i32_e32 v33, 31, v32
	v_lshlrev_b64 v[34:35], 11, v[32:33]
	v_lshl_add_u64 v[34:35], s[22:23], 0, v[34:35]
	v_lshl_add_u64 v[42:43], v[144:145], 1, v[34:35]
	global_load_dwordx4 v[34:37], v[42:43], off
	global_load_dwordx4 v[38:41], v[42:43], off offset:256
	s_waitcnt vmcnt(1)
	v_lshlrev_b32_e32 v44, 16, v34
	v_and_b32_e32 v45, 0xffff0000, v34
	v_lshlrev_b32_e32 v34, 16, v35
	v_and_b32_e32 v35, 0xffff0000, v35
	s_waitcnt vmcnt(0)
	v_lshlrev_b32_e32 v48, 16, v38
	v_and_b32_e32 v49, 0xffff0000, v38
	v_lshlrev_b32_e32 v38, 16, v39
	v_and_b32_e32 v39, 0xffff0000, v39
	v_lshlrev_b32_e32 v46, 16, v36
	v_and_b32_e32 v47, 0xffff0000, v36
	v_lshlrev_b32_e32 v36, 16, v37
	v_and_b32_e32 v37, 0xffff0000, v37
	v_lshlrev_b32_e32 v50, 16, v40
	v_and_b32_e32 v51, 0xffff0000, v40
	v_lshlrev_b32_e32 v40, 16, v41
	v_and_b32_e32 v41, 0xffff0000, v41
	v_fma_f32 v30, v30, 0.5, v34
	v_fma_f32 v31, v31, 0.5, v35
	v_fma_f32 v28, v28, 0.5, v44
	v_fma_f32 v29, v29, 0.5, v45
	v_fma_f32 v22, v22, 0.5, v38
	v_fma_f32 v23, v23, 0.5, v39
	v_fma_f32 v20, v20, 0.5, v48
	v_fma_f32 v21, v21, 0.5, v49
	v_fma_f32 v26, v26, 0.5, v36
	v_fma_f32 v27, v27, 0.5, v37
	v_fma_f32 v24, v24, 0.5, v46
	v_fma_f32 v25, v25, 0.5, v47
	v_fma_f32 v34, v18, 0.5, v40
	v_fma_f32 v35, v19, 0.5, v41
	v_fma_f32 v36, v16, 0.5, v50
	v_fma_f32 v37, v17, 0.5, v51
	v_mul_f32_e32 v18, v29, v29
	v_mul_f32_e32 v19, v31, v31
	v_mul_f32_e32 v38, v21, v21
	v_mul_f32_e32 v39, v23, v23
	v_cvt_pk_bf16_f32 v16, v28, v29
	v_mul_f32_e32 v29, v25, v25
	v_mul_f32_e32 v40, v37, v37
	v_fmac_f32_e32 v18, v28, v28
	v_fmac_f32_e32 v19, v30, v30
	v_fmac_f32_e32 v38, v20, v20
	v_fmac_f32_e32 v39, v22, v22
	v_cvt_pk_bf16_f32 v17, v30, v31
	v_mul_f32_e32 v31, v27, v27
	v_mul_f32_e32 v41, v35, v35
	v_fmac_f32_e32 v29, v24, v24
	v_fmac_f32_e32 v40, v36, v36
	v_add_f32_e32 v18, v18, v19
	v_add_f32_e32 v19, v38, v39
	v_fmac_f32_e32 v31, v26, v26
	v_fmac_f32_e32 v41, v34, v34
	v_add_f32_e32 v18, v29, v18
	v_add_f32_e32 v19, v40, v19
	v_add_f32_e32 v18, v31, v18
	v_add_f32_e32 v19, v41, v19
	v_add_f32_e32 v28, v18, v19
	ds_bpermute_b32 v29, v156, v28
	v_cvt_pk_bf16_f32 v18, v24, v25
	v_cvt_pk_bf16_f32 v19, v26, v27
	global_store_dwordx4 v[42:43], v[16:19], off
	s_waitcnt lgkmcnt(0)
	s_nop 0
	v_add_f32_e32 v16, v28, v29
	ds_bpermute_b32 v17, v155, v16
	v_cvt_pk_bf16_f32 v18, v20, v21
	v_cvt_pk_bf16_f32 v19, v22, v23
	v_cvt_pk_bf16_f32 v20, v36, v37
	v_cvt_pk_bf16_f32 v21, v34, v35
	global_store_dwordx4 v[42:43], v[18:21], off offset:256
	s_and_saveexec_b64 s[50:51], s[10:11]
	s_cbranch_execz .LBB0_1052
	s_waitcnt lgkmcnt(0)
	v_add_f32_e32 v16, v16, v17
	v_mul_f32_e32 v16, 0x4f800000, v16
	v_trunc_f32_e32 v16, v16
	v_mul_f32_e64 v17, |v16|, s63
	v_floor_f32_e32 v17, v17
	v_fma_f32 v18, v17, s64, |v16|
	v_cvt_u32_f32_e32 v18, v18
	v_cvt_u32_f32_e32 v17, v17
	v_ashrrev_i32_e32 v19, 31, v16
	v_xor_b32_e32 v16, v18, v19
	v_xor_b32_e32 v17, v17, v19
	v_sub_co_u32_e32 v16, vcc, v16, v19
	s_nop 1
	v_subb_co_u32_e32 v17, vcc, v17, v19, vcc
	v_lshl_add_u64 v[18:19], v[32:33], 3, s[36:37]
	global_atomic_add_x2 v[18:19], v[16:17], off
.LBB0_1052:
	s_or_b64 exec, exec, s[50:51]
	v_add_u32_e32 v16, 0xb0, v146
	s_waitcnt lgkmcnt(0)
	v_ashrrev_i32_e32 v17, 31, v16
	v_lshlrev_b64 v[18:19], 11, v[16:17]
	v_lshl_add_u64 v[18:19], s[22:23], 0, v[18:19]
	v_lshl_add_u64 v[26:27], v[144:145], 1, v[18:19]
	global_load_dwordx4 v[18:21], v[26:27], off
	global_load_dwordx4 v[22:25], v[26:27], off offset:256
	s_waitcnt vmcnt(1)
	v_lshlrev_b32_e32 v28, 16, v18
	v_and_b32_e32 v29, 0xffff0000, v18
	v_lshlrev_b32_e32 v18, 16, v19
	v_and_b32_e32 v19, 0xffff0000, v19
	s_waitcnt vmcnt(0)
	v_lshlrev_b32_e32 v32, 16, v22
	v_and_b32_e32 v33, 0xffff0000, v22
	v_lshlrev_b32_e32 v22, 16, v23
	v_and_b32_e32 v23, 0xffff0000, v23
	v_lshlrev_b32_e32 v30, 16, v20
	v_and_b32_e32 v31, 0xffff0000, v20
	v_lshlrev_b32_e32 v20, 16, v21
	v_and_b32_e32 v21, 0xffff0000, v21
	v_lshlrev_b32_e32 v34, 16, v24
	v_and_b32_e32 v35, 0xffff0000, v24
	v_lshlrev_b32_e32 v24, 16, v25
	v_and_b32_e32 v25, 0xffff0000, v25
	v_fma_f32 v14, v14, 0.5, v18
	v_fma_f32 v15, v15, 0.5, v19
	v_fma_f32 v12, v12, 0.5, v28
	v_fma_f32 v13, v13, 0.5, v29
	v_fma_f32 v6, v6, 0.5, v22
	v_fma_f32 v7, v7, 0.5, v23
	v_fma_f32 v4, v4, 0.5, v32
	v_fma_f32 v5, v5, 0.5, v33
	v_fma_f32 v10, v10, 0.5, v20
	v_fma_f32 v11, v11, 0.5, v21
	v_fma_f32 v8, v8, 0.5, v30
	v_fma_f32 v9, v9, 0.5, v31
	v_fma_f32 v18, v2, 0.5, v24
	v_fma_f32 v19, v3, 0.5, v25
	v_fma_f32 v20, v0, 0.5, v34
	v_fma_f32 v21, v1, 0.5, v35
	v_mul_f32_e32 v2, v13, v13
	v_mul_f32_e32 v3, v15, v15
	v_mul_f32_e32 v22, v5, v5
	v_mul_f32_e32 v23, v7, v7
	v_cvt_pk_bf16_f32 v0, v12, v13
	v_mul_f32_e32 v13, v9, v9
	v_mul_f32_e32 v24, v21, v21
	v_fmac_f32_e32 v2, v12, v12
	v_fmac_f32_e32 v3, v14, v14
	v_fmac_f32_e32 v22, v4, v4
	v_fmac_f32_e32 v23, v6, v6
	v_cvt_pk_bf16_f32 v1, v14, v15
	v_mul_f32_e32 v15, v11, v11
	v_mul_f32_e32 v25, v19, v19
	v_fmac_f32_e32 v13, v8, v8
	v_fmac_f32_e32 v24, v20, v20
	v_add_f32_e32 v2, v2, v3
	v_add_f32_e32 v3, v22, v23
	v_fmac_f32_e32 v15, v10, v10
	v_fmac_f32_e32 v25, v18, v18
	v_add_f32_e32 v2, v13, v2
	v_add_f32_e32 v3, v24, v3
	v_add_f32_e32 v2, v15, v2
	v_add_f32_e32 v3, v25, v3
	v_add_f32_e32 v12, v2, v3
	ds_bpermute_b32 v13, v156, v12
	v_cvt_pk_bf16_f32 v2, v8, v9
	v_cvt_pk_bf16_f32 v3, v10, v11
	global_store_dwordx4 v[26:27], v[0:3], off
	s_waitcnt lgkmcnt(0)
	s_nop 0
	v_add_f32_e32 v0, v12, v13
	ds_bpermute_b32 v1, v155, v0
	v_cvt_pk_bf16_f32 v2, v4, v5
	v_cvt_pk_bf16_f32 v3, v6, v7
	v_cvt_pk_bf16_f32 v4, v20, v21
	v_cvt_pk_bf16_f32 v5, v18, v19
	global_store_dwordx4 v[26:27], v[2:5], off offset:256
	s_and_saveexec_b64 s[50:51], s[10:11]
	s_cbranch_execz .LBB0_1054
	s_waitcnt lgkmcnt(0)
	v_add_f32_e32 v0, v0, v1
	v_mul_f32_e32 v0, 0x4f800000, v0
	v_trunc_f32_e32 v0, v0
	v_mul_f32_e64 v1, |v0|, s63
	v_floor_f32_e32 v1, v1
	v_fma_f32 v2, v1, s64, |v0|
	v_cvt_u32_f32_e32 v2, v2
	v_cvt_u32_f32_e32 v1, v1
	v_ashrrev_i32_e32 v3, 31, v0
	v_xor_b32_e32 v0, v2, v3
	v_xor_b32_e32 v1, v1, v3
	v_sub_co_u32_e32 v0, vcc, v0, v3
	s_nop 1
	v_subb_co_u32_e32 v1, vcc, v1, v3, vcc
	v_lshl_add_u64 v[2:3], v[16:17], 3, s[36:37]
	global_atomic_add_x2 v[2:3], v[0:1], off

; __device__ __forceinline__ void fx_add(float* p, size_t idx, float s) { atomicAdd((unsigned long long*)p + idx, (unsigned long long)(long long)(s * 4294967296.0f)); }
; __device__ __forceinline__ unsigned cvtpk(float lo, float hi) { f32x2v_ v = {lo, hi}; bf16x2v_ b = __builtin_convertvector(v, bf16x2v_); return __builtin_bit_cast(unsigned, b); }
;     __device__ __forceinline__ void operator()(const f32x4 (&acc)[2][2][4][2], const Unit& u, int wr, int wc, int fr, int fq) const {
;     ...
;             for (int m = 0; m < 4; ++m) { const int row = row0 + ai * HALF + m * 16; const size_t off = (size_t)row * 1024 + col0; float s = 0.f;
; #pragma unroll
;                 for (int bj = 0; bj < 2; ++bj) { f32x4 a0, a1;
;                     if (xin32) { const float* p = xin32 + off + bj * HALF; a0 = *(const f32x4*)p; a1 = *(const f32x4*)(p + 4); }
;                     else { const u32x4 w = *(const u32x4*)(xb + off + bj * HALF);
;                         a0 = (f32x4){__uint_as_float(w.x << 16), __uint_as_float(w.x & 0xffff0000u), __uint_as_float(w.y << 16), __uint_as_float(w.y & 0xffff0000u)};
;                         a1 = (f32x4){__uint_as_float(w.z << 16), __uint_as_float(w.z & 0xffff0000u), __uint_as_float(w.w << 16), __uint_as_float(w.w & 0xffff0000u)}; }
;                     const f32x4 v0 = a0 + acc[ai][bj][m][0] * alpha, v1 = a1 + acc[ai][bj][m][1] * alpha;
;                     u32x4 w; w.x = cvtpk(v0[0], v0[1]); w.y = cvtpk(v0[2], v0[3]); w.z = cvtpk(v1[0], v1[1]); w.w = cvtpk(v1[2], v1[3]);
;                     *(u32x4*)(xb + off + bj * HALF) = w;
;                     s += (v0[0] * v0[0] + v0[1] * v0[1]) + (v0[2] * v0[2] + v0[3] * v0[3]) + (v1[0] * v1[0] + v1[1] * v1[1]) + (v1[2] * v1[2] + v1[3] * v1[3]); }
;                 s += __shfl_xor(s, 16); s += __shfl_xor(s, 32);
;                 if (fq == 0) fx_add(ssout, row, s); }
.LBB0_1200:
	v_lshl_add_u32 v146, s77, 8, v148
	v_ashrrev_i32_e32 v147, 31, v146
	v_lshl_or_b32 v144, s76, 8, v150
	v_lshlrev_b64 v[156:157], 11, v[146:147]
	v_ashrrev_i32_e32 v145, 31, v144
	v_lshl_add_u64 v[156:157], s[22:23], 0, v[156:157]
	v_lshl_add_u64 v[166:167], v[144:145], 1, v[156:157]
	global_load_dwordx4 v[158:161], v[166:167], off
	global_load_dwordx4 v[162:165], v[166:167], off offset:256
	v_and_b32_e32 v156, 64, v154
	v_xor_b32_e32 v155, 16, v154
	v_add_u32_e32 v156, 64, v156
	v_xor_b32_e32 v157, 32, v154
	v_cmp_lt_i32_e32 vcc, v155, v156
	s_waitcnt vmcnt(0)
	v_lshlrev_b32_e32 v168, 16, v158
	v_cndmask_b32_e32 v155, v154, v155, vcc
	v_cmp_lt_i32_e32 vcc, v157, v156
	v_and_b32_e32 v169, 0xffff0000, v158
	v_lshlrev_b32_e32 v158, 16, v159
	v_and_b32_e32 v159, 0xffff0000, v159
	v_lshlrev_b32_e32 v172, 16, v162
	v_and_b32_e32 v173, 0xffff0000, v162
	v_lshlrev_b32_e32 v162, 16, v163
	v_and_b32_e32 v163, 0xffff0000, v163
	v_cndmask_b32_e32 v157, v154, v157, vcc
	v_lshlrev_b32_e32 v170, 16, v160
	v_and_b32_e32 v171, 0xffff0000, v160
	v_lshlrev_b32_e32 v160, 16, v161
	v_and_b32_e32 v161, 0xffff0000, v161
	v_lshlrev_b32_e32 v174, 16, v164
	v_and_b32_e32 v175, 0xffff0000, v164
	v_lshlrev_b32_e32 v164, 16, v165
	v_and_b32_e32 v165, 0xffff0000, v165
	v_fma_f32 v126, v126, 0.5, v158
	v_fma_f32 v127, v127, 0.5, v159
	v_fma_f32 v124, v124, 0.5, v168
	v_fma_f32 v125, v125, 0.5, v169
	v_fma_f32 v118, v118, 0.5, v162
	v_fma_f32 v119, v119, 0.5, v163
	v_fma_f32 v116, v116, 0.5, v172
	v_fma_f32 v117, v117, 0.5, v173
	v_lshlrev_b32_e32 v156, 2, v155
	v_lshlrev_b32_e32 v155, 2, v157
	v_fma_f32 v122, v122, 0.5, v160
	v_fma_f32 v123, v123, 0.5, v161
	v_fma_f32 v120, v120, 0.5, v170
	v_fma_f32 v121, v121, 0.5, v171
	v_fma_f32 v158, v114, 0.5, v164
	v_fma_f32 v159, v115, 0.5, v165
	v_fma_f32 v160, v112, 0.5, v174
	v_fma_f32 v161, v113, 0.5, v175
	v_mul_f32_e32 v114, v125, v125
	v_mul_f32_e32 v115, v127, v127
	v_mul_f32_e32 v157, v117, v117
	v_mul_f32_e32 v162, v119, v119
	v_cvt_pk_bf16_f32 v112, v124, v125
	v_mul_f32_e32 v125, v121, v121
	v_mul_f32_e32 v163, v161, v161
	v_fmac_f32_e32 v114, v124, v124
	v_fmac_f32_e32 v115, v126, v126
	v_fmac_f32_e32 v157, v116, v116
	v_fmac_f32_e32 v162, v118, v118
	v_cvt_pk_bf16_f32 v113, v126, v127
	v_mul_f32_e32 v127, v123, v123
	v_mul_f32_e32 v164, v159, v159
	v_fmac_f32_e32 v125, v120, v120
	v_fmac_f32_e32 v163, v160, v160
	v_add_f32_e32 v114, v114, v115
	v_add_f32_e32 v115, v157, v162
	v_fmac_f32_e32 v127, v122, v122
	v_fmac_f32_e32 v164, v158, v158
	v_add_f32_e32 v114, v125, v114
	v_add_f32_e32 v115, v163, v115
	v_add_f32_e32 v114, v127, v114
	v_add_f32_e32 v115, v164, v115
	v_add_f32_e32 v124, v114, v115
	ds_bpermute_b32 v125, v156, v124
	v_cvt_pk_bf16_f32 v114, v120, v121
	v_cvt_pk_bf16_f32 v115, v122, v123
	global_store_dwordx4 v[166:167], v[112:115], off
	s_waitcnt lgkmcnt(0)
	s_nop 0
	v_add_f32_e32 v112, v124, v125
	ds_bpermute_b32 v113, v155, v112
	v_cvt_pk_bf16_f32 v114, v116, v117
	v_cvt_pk_bf16_f32 v115, v118, v119
	v_cvt_pk_bf16_f32 v116, v160, v161
	v_cvt_pk_bf16_f32 v117, v158, v159
	global_store_dwordx4 v[166:167], v[114:117], off offset:256
	s_and_saveexec_b64 s[50:51], s[10:11]
	s_cbranch_execz .LBB0_1202
	s_waitcnt lgkmcnt(0)
	v_add_f32_e32 v112, v112, v113
	v_mul_f32_e32 v112, 0x4f800000, v112
	v_trunc_f32_e32 v112, v112
	v_mul_f32_e64 v113, |v112|, s66
	v_floor_f32_e32 v113, v113
	v_fma_f32 v114, v113, s67, |v112|
	v_cvt_u32_f32_e32 v114, v114
	v_cvt_u32_f32_e32 v113, v113
	v_ashrrev_i32_e32 v115, 31, v112
	v_xor_b32_e32 v112, v114, v115
	v_xor_b32_e32 v113, v113, v115
	v_sub_co_u32_e32 v112, vcc, v112, v115
	s_nop 1
	v_subb_co_u32_e32 v113, vcc, v113, v115, vcc
	v_lshl_add_u64 v[114:115], v[146:147], 3, s[36:37]
	global_atomic_add_x2 v[114:115], v[112:113], off
.LBB0_1202:
	s_or_b64 exec, exec, s[50:51]
	v_or_b32_e32 v112, 16, v146
	s_waitcnt lgkmcnt(0)
	v_ashrrev_i32_e32 v113, 31, v112
	v_lshlrev_b64 v[114:115], 11, v[112:113]
	v_lshl_add_u64 v[114:115], s[22:23], 0, v[114:115]
	v_lshl_add_u64 v[122:123], v[144:145], 1, v[114:115]
	global_load_dwordx4 v[114:117], v[122:123], off
	global_load_dwordx4 v[118:121], v[122:123], off offset:256
	s_waitcnt vmcnt(1)
	v_lshlrev_b32_e32 v124, 16, v114
	v_and_b32_e32 v125, 0xffff0000, v114
	v_lshlrev_b32_e32 v114, 16, v115
	v_and_b32_e32 v115, 0xffff0000, v115
	s_waitcnt vmcnt(0)
	v_lshlrev_b32_e32 v158, 16, v118
	v_and_b32_e32 v159, 0xffff0000, v118
	v_lshlrev_b32_e32 v118, 16, v119
	v_and_b32_e32 v119, 0xffff0000, v119
	v_lshlrev_b32_e32 v126, 16, v116
	v_and_b32_e32 v127, 0xffff0000, v116
	v_lshlrev_b32_e32 v116, 16, v117
	v_and_b32_e32 v117, 0xffff0000, v117
	v_lshlrev_b32_e32 v160, 16, v120
	v_and_b32_e32 v161, 0xffff0000, v120
	v_lshlrev_b32_e32 v120, 16, v121
	v_and_b32_e32 v121, 0xffff0000, v121
	v_fma_f32 v110, v110, 0.5, v114
	v_fma_f32 v111, v111, 0.5, v115
	v_fma_f32 v108, v108, 0.5, v124
	v_fma_f32 v109, v109, 0.5, v125
	v_fma_f32 v102, v102, 0.5, v118
	v_fma_f32 v103, v103, 0.5, v119
	v_fma_f32 v100, v100, 0.5, v158
	v_fma_f32 v101, v101, 0.5, v159
	v_fma_f32 v106, v106, 0.5, v116
	v_fma_f32 v107, v107, 0.5, v117
	v_fma_f32 v104, v104, 0.5, v126
	v_fma_f32 v105, v105, 0.5, v127
	v_fma_f32 v114, v98, 0.5, v120
	v_fma_f32 v115, v99, 0.5, v121
	v_fma_f32 v116, v96, 0.5, v160
	v_fma_f32 v117, v97, 0.5, v161
	v_mul_f32_e32 v98, v109, v109
	v_mul_f32_e32 v99, v111, v111
	v_mul_f32_e32 v118, v101, v101
	v_mul_f32_e32 v119, v103, v103
	v_cvt_pk_bf16_f32 v96, v108, v109
	v_mul_f32_e32 v109, v105, v105
	v_mul_f32_e32 v120, v117, v117
	v_fmac_f32_e32 v98, v108, v108
	v_fmac_f32_e32 v99, v110, v110
	v_fmac_f32_e32 v118, v100, v100
	v_fmac_f32_e32 v119, v102, v102
	v_cvt_pk_bf16_f32 v97, v110, v111
	v_mul_f32_e32 v111, v107, v107
	v_mul_f32_e32 v121, v115, v115
	v_fmac_f32_e32 v109, v104, v104
	v_fmac_f32_e32 v120, v116, v116
	v_add_f32_e32 v98, v98, v99
	v_add_f32_e32 v99, v118, v119
	v_fmac_f32_e32 v111, v106, v106
	v_fmac_f32_e32 v121, v114, v114
	v_add_f32_e32 v98, v109, v98
	v_add_f32_e32 v99, v120, v99
	v_add_f32_e32 v98, v111, v98
	v_add_f32_e32 v99, v121, v99
	v_add_f32_e32 v108, v98, v99
	ds_bpermute_b32 v109, v156, v108
	v_cvt_pk_bf16_f32 v98, v104, v105
	v_cvt_pk_bf16_f32 v99, v106, v107
	global_store_dwordx4 v[122:123], v[96:99], off
	s_waitcnt lgkmcnt(0)
	s_nop 0
	v_add_f32_e32 v96, v108, v109
	ds_bpermute_b32 v97, v155, v96
	v_cvt_pk_bf16_f32 v98, v100, v101
	v_cvt_pk_bf16_f32 v99, v102, v103
	v_cvt_pk_bf16_f32 v100, v116, v117
	v_cvt_pk_bf16_f32 v101, v114, v115
	global_store_dwordx4 v[122:123], v[98:101], off offset:256
	s_and_saveexec_b64 s[50:51], s[10:11]
	s_cbranch_execz .LBB0_1204
; __device__ __forceinline__ void fx_add(float* p, size_t idx, float s) { atomicAdd((unsigned long long*)p + idx, (unsigned long long)(long long)(s * 4294967296.0f)); }
; __device__ __forceinline__ unsigned cvtpk(float lo, float hi) { f32x2v_ v = {lo, hi}; bf16x2v_ b = __builtin_convertvector(v, bf16x2v_); return __builtin_bit_cast(unsigned, b); }
;     __device__ __forceinline__ void operator()(const f32x4 (&acc)[2][2][4][2], const Unit& u, int wr, int wc, int fr, int fq) const {
;     ...
;             for (int m = 0; m < 4; ++m) { const int row = row0 + ai * HALF + m * 16; const size_t off = (size_t)row * 1024 + col0; float s = 0.f;
; #pragma unroll
;                 for (int bj = 0; bj < 2; ++bj) { f32x4 a0, a1;
;                     if (xin32) { const float* p = xin32 + off + bj * HALF; a0 = *(const f32x4*)p; a1 = *(const f32x4*)(p + 4); }
;                     else { const u32x4 w = *(const u32x4*)(xb + off + bj * HALF);
;                         a0 = (f32x4){__uint_as_float(w.x << 16), __uint_as_float(w.x & 0xffff0000u), __uint_as_float(w.y << 16), __uint_as_float(w.y & 0xffff0000u)};
;                         a1 = (f32x4){__uint_as_float(w.z << 16), __uint_as_float(w.z & 0xffff0000u), __uint_as_float(w.w << 16), __uint_as_float(w.w & 0xffff0000u)}; }
;                     const f32x4 v0 = a0 + acc[ai][bj][m][0] * alpha, v1 = a1 + acc[ai][bj][m][1] * alpha;
;                     u32x4 w; w.x = cvtpk(v0[0], v0[1]); w.y = cvtpk(v0[2], v0[3]); w.z = cvtpk(v1[0], v1[1]); w.w = cvtpk(v1[2], v1[3]);
;                     *(u32x4*)(xb + off + bj * HALF) = w;
;                     s += (v0[0] * v0[0] + v0[1] * v0[1]) + (v0[2] * v0[2] + v0[3] * v0[3]) + (v1[0] * v1[0] + v1[1] * v1[1]) + (v1[2] * v1[2] + v1[3] * v1[3]); }
;                 s += __shfl_xor(s, 16); s += __shfl_xor(s, 32);
;                 if (fq == 0) fx_add(ssout, row, s); }
	s_waitcnt lgkmcnt(0)
	v_add_f32_e32 v96, v96, v97
	v_mul_f32_e32 v96, 0x4f800000, v96
	v_trunc_f32_e32 v96, v96
	v_mul_f32_e64 v97, |v96|, s66
	v_floor_f32_e32 v97, v97
	v_fma_f32 v98, v97, s67, |v96|
	v_cvt_u32_f32_e32 v98, v98
	v_cvt_u32_f32_e32 v97, v97
	v_ashrrev_i32_e32 v99, 31, v96
	v_xor_b32_e32 v96, v98, v99
	v_xor_b32_e32 v97, v97, v99
	v_sub_co_u32_e32 v96, vcc, v96, v99
	s_nop 1
	v_subb_co_u32_e32 v97, vcc, v97, v99, vcc
	v_lshl_add_u64 v[98:99], v[112:113], 3, s[36:37]
	global_atomic_add_x2 v[98:99], v[96:97], off
.LBB0_1204:
	s_or_b64 exec, exec, s[50:51]
	v_or_b32_e32 v96, 32, v146
	s_waitcnt lgkmcnt(0)
	v_ashrrev_i32_e32 v97, 31, v96
	v_lshlrev_b64 v[98:99], 11, v[96:97]
	v_lshl_add_u64 v[98:99], s[22:23], 0, v[98:99]
	v_lshl_add_u64 v[106:107], v[144:145], 1, v[98:99]
	global_load_dwordx4 v[98:101], v[106:107], off
	global_load_dwordx4 v[102:105], v[106:107], off offset:256
	s_waitcnt vmcnt(1)
	v_lshlrev_b32_e32 v108, 16, v98
	v_and_b32_e32 v109, 0xffff0000, v98
	v_lshlrev_b32_e32 v98, 16, v99
	v_and_b32_e32 v99, 0xffff0000, v99
	s_waitcnt vmcnt(0)
	v_lshlrev_b32_e32 v112, 16, v102
	v_and_b32_e32 v113, 0xffff0000, v102
	v_lshlrev_b32_e32 v102, 16, v103
	v_and_b32_e32 v103, 0xffff0000, v103
	v_lshlrev_b32_e32 v110, 16, v100
	v_and_b32_e32 v111, 0xffff0000, v100
	v_lshlrev_b32_e32 v100, 16, v101
	v_and_b32_e32 v101, 0xffff0000, v101
	v_lshlrev_b32_e32 v114, 16, v104
	v_and_b32_e32 v115, 0xffff0000, v104
	v_lshlrev_b32_e32 v104, 16, v105
	v_and_b32_e32 v105, 0xffff0000, v105
	v_fma_f32 v94, v94, 0.5, v98
	v_fma_f32 v95, v95, 0.5, v99
	v_fma_f32 v92, v92, 0.5, v108
	v_fma_f32 v93, v93, 0.5, v109
	v_fma_f32 v86, v86, 0.5, v102
	v_fma_f32 v87, v87, 0.5, v103
	v_fma_f32 v84, v84, 0.5, v112
	v_fma_f32 v85, v85, 0.5, v113
	v_fma_f32 v90, v90, 0.5, v100
	v_fma_f32 v91, v91, 0.5, v101
	v_fma_f32 v88, v88, 0.5, v110
	v_fma_f32 v89, v89, 0.5, v111
	v_fma_f32 v98, v82, 0.5, v104
	v_fma_f32 v99, v83, 0.5, v105
	v_fma_f32 v100, v80, 0.5, v114
	v_fma_f32 v101, v81, 0.5, v115
	v_mul_f32_e32 v82, v93, v93
	v_mul_f32_e32 v83, v95, v95
	v_mul_f32_e32 v102, v85, v85
	v_mul_f32_e32 v103, v87, v87
	v_cvt_pk_bf16_f32 v80, v92, v93
	v_mul_f32_e32 v93, v89, v89
	v_mul_f32_e32 v104, v101, v101
	v_fmac_f32_e32 v82, v92, v92
	v_fmac_f32_e32 v83, v94, v94
	v_fmac_f32_e32 v102, v84, v84
	v_fmac_f32_e32 v103, v86, v86
	v_cvt_pk_bf16_f32 v81, v94, v95
	v_mul_f32_e32 v95, v91, v91
	v_mul_f32_e32 v105, v99, v99
	v_fmac_f32_e32 v93, v88, v88
	v_fmac_f32_e32 v104, v100, v100
	v_add_f32_e32 v82, v82, v83
	v_add_f32_e32 v83, v102, v103
	v_fmac_f32_e32 v95, v90, v90
	v_fmac_f32_e32 v105, v98, v98
	v_add_f32_e32 v82, v93, v82
	v_add_f32_e32 v83, v104, v83
	v_add_f32_e32 v82, v95, v82
	v_add_f32_e32 v83, v105, v83
	v_add_f32_e32 v92, v82, v83
	ds_bpermute_b32 v93, v156, v92
	v_cvt_pk_bf16_f32 v82, v88, v89
	v_cvt_pk_bf16_f32 v83, v90, v91
	global_store_dwordx4 v[106:107], v[80:83], off
	s_waitcnt lgkmcnt(0)
	s_nop 0
	v_add_f32_e32 v80, v92, v93
	ds_bpermute_b32 v81, v155, v80
	v_cvt_pk_bf16_f32 v82, v84, v85
	v_cvt_pk_bf16_f32 v83, v86, v87
	v_cvt_pk_bf16_f32 v84, v100, v101
	v_cvt_pk_bf16_f32 v85, v98, v99
	global_store_dwordx4 v[106:107], v[82:85], off offset:256
	s_and_saveexec_b64 s[50:51], s[10:11]
	s_cbranch_execz .LBB0_1206
	s_waitcnt lgkmcnt(0)
	v_add_f32_e32 v80, v80, v81
	v_mul_f32_e32 v80, 0x4f800000, v80
	v_trunc_f32_e32 v80, v80
	v_mul_f32_e64 v81, |v80|, s66
	v_floor_f32_e32 v81, v81
	v_fma_f32 v82, v81, s67, |v80|
	v_cvt_u32_f32_e32 v82, v82
	v_cvt_u32_f32_e32 v81, v81
	v_ashrrev_i32_e32 v83, 31, v80
	v_xor_b32_e32 v80, v82, v83
	v_xor_b32_e32 v81, v81, v83
	v_sub_co_u32_e32 v80, vcc, v80, v83
	s_nop 1
	v_subb_co_u32_e32 v81, vcc, v81, v83, vcc
	v_lshl_add_u64 v[82:83], v[96:97], 3, s[36:37]
	global_atomic_add_x2 v[82:83], v[80:81], off
.LBB0_1206:
	s_or_b64 exec, exec, s[50:51]
	v_or_b32_e32 v80, 48, v146
	s_waitcnt lgkmcnt(0)
	v_ashrrev_i32_e32 v81, 31, v80
	v_lshlrev_b64 v[82:83], 11, v[80:81]
	v_lshl_add_u64 v[82:83], s[22:23], 0, v[82:83]
	v_lshl_add_u64 v[90:91], v[144:145], 1, v[82:83]
	global_load_dwordx4 v[82:85], v[90:91], off
	global_load_dwordx4 v[86:89], v[90:91], off offset:256
	s_waitcnt vmcnt(1)
	v_lshlrev_b32_e32 v92, 16, v82
	v_and_b32_e32 v93, 0xffff0000, v82
	v_lshlrev_b32_e32 v82, 16, v83
	v_and_b32_e32 v83, 0xffff0000, v83
	s_waitcnt vmcnt(0)
	v_lshlrev_b32_e32 v96, 16, v86
	v_and_b32_e32 v97, 0xffff0000, v86
	v_lshlrev_b32_e32 v86, 16, v87
	v_and_b32_e32 v87, 0xffff0000, v87
	v_lshlrev_b32_e32 v94, 16, v84
	v_and_b32_e32 v95, 0xffff0000, v84
	v_lshlrev_b32_e32 v84, 16, v85
	v_and_b32_e32 v85, 0xffff0000, v85
	v_lshlrev_b32_e32 v98, 16, v88
	v_and_b32_e32 v99, 0xffff0000, v88
	v_lshlrev_b32_e32 v88, 16, v89
	v_and_b32_e32 v89, 0xffff0000, v89
	v_fma_f32 v78, v78, 0.5, v82
	v_fma_f32 v79, v79, 0.5, v83
	v_fma_f32 v76, v76, 0.5, v92
	v_fma_f32 v77, v77, 0.5, v93
	v_fma_f32 v70, v70, 0.5, v86
	v_fma_f32 v71, v71, 0.5, v87
	v_fma_f32 v68, v68, 0.5, v96
	v_fma_f32 v69, v69, 0.5, v97
	v_fma_f32 v74, v74, 0.5, v84
	v_fma_f32 v75, v75, 0.5, v85
	v_fma_f32 v72, v72, 0.5, v94
	v_fma_f32 v73, v73, 0.5, v95
	v_fma_f32 v82, v66, 0.5, v88
	v_fma_f32 v83, v67, 0.5, v89
	v_fma_f32 v84, v64, 0.5, v98
	v_fma_f32 v85, v65, 0.5, v99
	v_mul_f32_e32 v66, v77, v77
	v_mul_f32_e32 v67, v79, v79
	v_mul_f32_e32 v86, v69, v69
	v_mul_f32_e32 v87, v71, v71
	v_cvt_pk_bf16_f32 v64, v76, v77
	v_mul_f32_e32 v77, v73, v73
	v_mul_f32_e32 v88, v85, v85
	v_fmac_f32_e32 v66, v76, v76
	v_fmac_f32_e32 v67, v78, v78
	v_fmac_f32_e32 v86, v68, v68
	v_fmac_f32_e32 v87, v70, v70
	v_cvt_pk_bf16_f32 v65, v78, v79
	v_mul_f32_e32 v79, v75, v75
	v_mul_f32_e32 v89, v83, v83
	v_fmac_f32_e32 v77, v72, v72
	v_fmac_f32_e32 v88, v84, v84
	v_add_f32_e32 v66, v66, v67
	v_add_f32_e32 v67, v86, v87
	v_fmac_f32_e32 v79, v74, v74
	v_fmac_f32_e32 v89, v82, v82
	v_add_f32_e32 v66, v77, v66
	v_add_f32_e32 v67, v88, v67
	v_add_f32_e32 v66, v79, v66
	v_add_f32_e32 v67, v89, v67
	v_add_f32_e32 v76, v66, v67
	ds_bpermute_b32 v77, v156, v76
	v_cvt_pk_bf16_f32 v66, v72, v73
	v_cvt_pk_bf16_f32 v67, v74, v75
	global_store_dwordx4 v[90:91], v[64:67], off
	s_waitcnt lgkmcnt(0)
	s_nop 0
	v_add_f32_e32 v64, v76, v77
	ds_bpermute_b32 v65, v155, v64
	v_cvt_pk_bf16_f32 v66, v68, v69
	v_cvt_pk_bf16_f32 v67, v70, v71
	v_cvt_pk_bf16_f32 v68, v84, v85
	v_cvt_pk_bf16_f32 v69, v82, v83
	global_store_dwordx4 v[90:91], v[66:69], off offset:256
	s_and_saveexec_b64 s[50:51], s[10:11]
	s_cbranch_execz .LBB0_1208
	s_waitcnt lgkmcnt(0)
	v_add_f32_e32 v64, v64, v65
	v_mul_f32_e32 v64, 0x4f800000, v64
	v_trunc_f32_e32 v64, v64
	v_mul_f32_e64 v65, |v64|, s66
	v_floor_f32_e32 v65, v65
	v_fma_f32 v66, v65, s67, |v64|
	v_cvt_u32_f32_e32 v66, v66
	v_cvt_u32_f32_e32 v65, v65
	v_ashrrev_i32_e32 v67, 31, v64
	v_xor_b32_e32 v64, v66, v67
	v_xor_b32_e32 v65, v65, v67
	v_sub_co_u32_e32 v64, vcc, v64, v67
	s_nop 1
	v_subb_co_u32_e32 v65, vcc, v65, v67, vcc
	v_lshl_add_u64 v[66:67], v[80:81], 3, s[36:37]
	global_atomic_add_x2 v[66:67], v[64:65], off
; __device__ __forceinline__ void fx_add(float* p, size_t idx, float s) { atomicAdd((unsigned long long*)p + idx, (unsigned long long)(long long)(s * 4294967296.0f)); }
; __device__ __forceinline__ unsigned cvtpk(float lo, float hi) { f32x2v_ v = {lo, hi}; bf16x2v_ b = __builtin_convertvector(v, bf16x2v_); return __builtin_bit_cast(unsigned, b); }
;     __device__ __forceinline__ void operator()(const f32x4 (&acc)[2][2][4][2], const Unit& u, int wr, int wc, int fr, int fq) const {
;     ...
;             for (int m = 0; m < 4; ++m) { const int row = row0 + ai * HALF + m * 16; const size_t off = (size_t)row * 1024 + col0; float s = 0.f;
; #pragma unroll
;                 for (int bj = 0; bj < 2; ++bj) { f32x4 a0, a1;
;                     if (xin32) { const float* p = xin32 + off + bj * HALF; a0 = *(const f32x4*)p; a1 = *(const f32x4*)(p + 4); }
;                     else { const u32x4 w = *(const u32x4*)(xb + off + bj * HALF);
;                         a0 = (f32x4){__uint_as_float(w.x << 16), __uint_as_float(w.x & 0xffff0000u), __uint_as_float(w.y << 16), __uint_as_float(w.y & 0xffff0000u)};
;                         a1 = (f32x4){__uint_as_float(w.z << 16), __uint_as_float(w.z & 0xffff0000u), __uint_as_float(w.w << 16), __uint_as_float(w.w & 0xffff0000u)}; }
;                     const f32x4 v0 = a0 + acc[ai][bj][m][0] * alpha, v1 = a1 + acc[ai][bj][m][1] * alpha;
;                     u32x4 w; w.x = cvtpk(v0[0], v0[1]); w.y = cvtpk(v0[2], v0[3]); w.z = cvtpk(v1[0], v1[1]); w.w = cvtpk(v1[2], v1[3]);
;                     *(u32x4*)(xb + off + bj * HALF) = w;
;                     s += (v0[0] * v0[0] + v0[1] * v0[1]) + (v0[2] * v0[2] + v0[3] * v0[3]) + (v1[0] * v1[0] + v1[1] * v1[1]) + (v1[2] * v1[2] + v1[3] * v1[3]); }
;                 s += __shfl_xor(s, 16); s += __shfl_xor(s, 32);
;                 if (fq == 0) fx_add(ssout, row, s); }
.LBB0_1208:
	s_or_b64 exec, exec, s[50:51]
	v_add_u32_e32 v64, 0x80, v146
	s_waitcnt lgkmcnt(0)
	v_ashrrev_i32_e32 v65, 31, v64
	v_lshlrev_b64 v[66:67], 11, v[64:65]
	v_lshl_add_u64 v[66:67], s[22:23], 0, v[66:67]
	v_lshl_add_u64 v[74:75], v[144:145], 1, v[66:67]
	global_load_dwordx4 v[66:69], v[74:75], off
	global_load_dwordx4 v[70:73], v[74:75], off offset:256
	s_waitcnt vmcnt(1)
	v_lshlrev_b32_e32 v76, 16, v66
	v_and_b32_e32 v77, 0xffff0000, v66
	v_lshlrev_b32_e32 v66, 16, v67
	v_and_b32_e32 v67, 0xffff0000, v67
	s_waitcnt vmcnt(0)
	v_lshlrev_b32_e32 v80, 16, v70
	v_and_b32_e32 v81, 0xffff0000, v70
	v_lshlrev_b32_e32 v70, 16, v71
	v_and_b32_e32 v71, 0xffff0000, v71
	v_lshlrev_b32_e32 v78, 16, v68
	v_and_b32_e32 v79, 0xffff0000, v68
	v_lshlrev_b32_e32 v68, 16, v69
	v_and_b32_e32 v69, 0xffff0000, v69
	v_lshlrev_b32_e32 v82, 16, v72
	v_and_b32_e32 v83, 0xffff0000, v72
	v_lshlrev_b32_e32 v72, 16, v73
	v_and_b32_e32 v73, 0xffff0000, v73
	v_fma_f32 v62, v62, 0.5, v66
	v_fma_f32 v63, v63, 0.5, v67
	v_fma_f32 v60, v60, 0.5, v76
	v_fma_f32 v61, v61, 0.5, v77
	v_fma_f32 v54, v54, 0.5, v70
	v_fma_f32 v55, v55, 0.5, v71
	v_fma_f32 v52, v52, 0.5, v80
	v_fma_f32 v53, v53, 0.5, v81
	v_fma_f32 v58, v58, 0.5, v68
	v_fma_f32 v59, v59, 0.5, v69
	v_fma_f32 v56, v56, 0.5, v78
	v_fma_f32 v57, v57, 0.5, v79
	v_fma_f32 v66, v50, 0.5, v72
	v_fma_f32 v67, v51, 0.5, v73
	v_fma_f32 v68, v48, 0.5, v82
	v_fma_f32 v69, v49, 0.5, v83
	v_mul_f32_e32 v50, v61, v61
	v_mul_f32_e32 v51, v63, v63
	v_mul_f32_e32 v70, v53, v53
	v_mul_f32_e32 v71, v55, v55
	v_cvt_pk_bf16_f32 v48, v60, v61
	v_mul_f32_e32 v61, v57, v57
	v_mul_f32_e32 v72, v69, v69
	v_fmac_f32_e32 v50, v60, v60
	v_fmac_f32_e32 v51, v62, v62
	v_fmac_f32_e32 v70, v52, v52
	v_fmac_f32_e32 v71, v54, v54
	v_cvt_pk_bf16_f32 v49, v62, v63
	v_mul_f32_e32 v63, v59, v59
	v_mul_f32_e32 v73, v67, v67
	v_fmac_f32_e32 v61, v56, v56
	v_fmac_f32_e32 v72, v68, v68
	v_add_f32_e32 v50, v50, v51
	v_add_f32_e32 v51, v70, v71
	v_fmac_f32_e32 v63, v58, v58
	v_fmac_f32_e32 v73, v66, v66
	v_add_f32_e32 v50, v61, v50
	v_add_f32_e32 v51, v72, v51
	v_add_f32_e32 v50, v63, v50
	v_add_f32_e32 v51, v73, v51
	v_add_f32_e32 v60, v50, v51
	ds_bpermute_b32 v61, v156, v60
	v_cvt_pk_bf16_f32 v50, v56, v57
	v_cvt_pk_bf16_f32 v51, v58, v59
	global_store_dwordx4 v[74:75], v[48:51], off
	s_waitcnt lgkmcnt(0)
	s_nop 0
	v_add_f32_e32 v48, v60, v61
	ds_bpermute_b32 v49, v155, v48
	v_cvt_pk_bf16_f32 v50, v52, v53
	v_cvt_pk_bf16_f32 v51, v54, v55
	v_cvt_pk_bf16_f32 v52, v68, v69
	v_cvt_pk_bf16_f32 v53, v66, v67
	global_store_dwordx4 v[74:75], v[50:53], off offset:256
	s_and_saveexec_b64 s[50:51], s[10:11]
	s_cbranch_execz .LBB0_1210
	s_waitcnt lgkmcnt(0)
	v_add_f32_e32 v48, v48, v49
	v_mul_f32_e32 v48, 0x4f800000, v48
	v_trunc_f32_e32 v48, v48
	v_mul_f32_e64 v49, |v48|, s66
	v_floor_f32_e32 v49, v49
	v_fma_f32 v50, v49, s67, |v48|
	v_cvt_u32_f32_e32 v50, v50
	v_cvt_u32_f32_e32 v49, v49
	v_ashrrev_i32_e32 v51, 31, v48
	v_xor_b32_e32 v48, v50, v51
	v_xor_b32_e32 v49, v49, v51
	v_sub_co_u32_e32 v48, vcc, v48, v51
	s_nop 1
	v_subb_co_u32_e32 v49, vcc, v49, v51, vcc
	v_lshl_add_u64 v[50:51], v[64:65], 3, s[36:37]
	global_atomic_add_x2 v[50:51], v[48:49], off
.LBB0_1210:
	s_or_b64 exec, exec, s[50:51]
	v_add_u32_e32 v48, 0x90, v146
	s_waitcnt lgkmcnt(0)
	v_ashrrev_i32_e32 v49, 31, v48
	v_lshlrev_b64 v[50:51], 11, v[48:49]
	v_lshl_add_u64 v[50:51], s[22:23], 0, v[50:51]
	v_lshl_add_u64 v[58:59], v[144:145], 1, v[50:51]
	global_load_dwordx4 v[50:53], v[58:59], off
	global_load_dwordx4 v[54:57], v[58:59], off offset:256
	s_waitcnt vmcnt(1)
	v_lshlrev_b32_e32 v60, 16, v50
	v_and_b32_e32 v61, 0xffff0000, v50
	v_lshlrev_b32_e32 v50, 16, v51
	v_and_b32_e32 v51, 0xffff0000, v51
	s_waitcnt vmcnt(0)
	v_lshlrev_b32_e32 v64, 16, v54
	v_and_b32_e32 v65, 0xffff0000, v54
	v_lshlrev_b32_e32 v54, 16, v55
	v_and_b32_e32 v55, 0xffff0000, v55
	v_lshlrev_b32_e32 v62, 16, v52
	v_and_b32_e32 v63, 0xffff0000, v52
	v_lshlrev_b32_e32 v52, 16, v53
	v_and_b32_e32 v53, 0xffff0000, v53
	v_lshlrev_b32_e32 v66, 16, v56
	v_and_b32_e32 v67, 0xffff0000, v56
	v_lshlrev_b32_e32 v56, 16, v57
	v_and_b32_e32 v57, 0xffff0000, v57
	v_fma_f32 v46, v46, 0.5, v50
	v_fma_f32 v47, v47, 0.5, v51
	v_fma_f32 v44, v44, 0.5, v60
	v_fma_f32 v45, v45, 0.5, v61
	v_fma_f32 v38, v38, 0.5, v54
	v_fma_f32 v39, v39, 0.5, v55
	v_fma_f32 v36, v36, 0.5, v64
	v_fma_f32 v37, v37, 0.5, v65
	v_fma_f32 v42, v42, 0.5, v52
	v_fma_f32 v43, v43, 0.5, v53
	v_fma_f32 v40, v40, 0.5, v62
	v_fma_f32 v41, v41, 0.5, v63
	v_fma_f32 v50, v34, 0.5, v56
	v_fma_f32 v51, v35, 0.5, v57
	v_fma_f32 v52, v32, 0.5, v66
	v_fma_f32 v53, v33, 0.5, v67
	v_mul_f32_e32 v34, v45, v45
	v_mul_f32_e32 v35, v47, v47
	v_mul_f32_e32 v54, v37, v37
	v_mul_f32_e32 v55, v39, v39
	v_cvt_pk_bf16_f32 v32, v44, v45
	v_mul_f32_e32 v45, v41, v41
	v_mul_f32_e32 v56, v53, v53
	v_fmac_f32_e32 v34, v44, v44
	v_fmac_f32_e32 v35, v46, v46
	v_fmac_f32_e32 v54, v36, v36
	v_fmac_f32_e32 v55, v38, v38
	v_cvt_pk_bf16_f32 v33, v46, v47
	v_mul_f32_e32 v47, v43, v43
	v_mul_f32_e32 v57, v51, v51
	v_fmac_f32_e32 v45, v40, v40
	v_fmac_f32_e32 v56, v52, v52
	v_add_f32_e32 v34, v34, v35
	v_add_f32_e32 v35, v54, v55
	v_fmac_f32_e32 v47, v42, v42
	v_fmac_f32_e32 v57, v50, v50
	v_add_f32_e32 v34, v45, v34
	v_add_f32_e32 v35, v56, v35
	v_add_f32_e32 v34, v47, v34
	v_add_f32_e32 v35, v57, v35
	v_add_f32_e32 v44, v34, v35
	ds_bpermute_b32 v45, v156, v44
	v_cvt_pk_bf16_f32 v34, v40, v41
	v_cvt_pk_bf16_f32 v35, v42, v43
	global_store_dwordx4 v[58:59], v[32:35], off
	s_waitcnt lgkmcnt(0)
	s_nop 0
	v_add_f32_e32 v32, v44, v45
	ds_bpermute_b32 v33, v155, v32
	v_cvt_pk_bf16_f32 v34, v36, v37
	v_cvt_pk_bf16_f32 v35, v38, v39
	v_cvt_pk_bf16_f32 v36, v52, v53
	v_cvt_pk_bf16_f32 v37, v50, v51
	global_store_dwordx4 v[58:59], v[34:37], off offset:256
	s_and_saveexec_b64 s[50:51], s[10:11]
	s_cbranch_execz .LBB0_1212
	s_waitcnt lgkmcnt(0)
	v_add_f32_e32 v32, v32, v33
	v_mul_f32_e32 v32, 0x4f800000, v32
	v_trunc_f32_e32 v32, v32
	v_mul_f32_e64 v33, |v32|, s66
	v_floor_f32_e32 v33, v33
	v_fma_f32 v34, v33, s67, |v32|
	v_cvt_u32_f32_e32 v34, v34
	v_cvt_u32_f32_e32 v33, v33
	v_ashrrev_i32_e32 v35, 31, v32
	v_xor_b32_e32 v32, v34, v35
	v_xor_b32_e32 v33, v33, v35
	v_sub_co_u32_e32 v32, vcc, v32, v35
	s_nop 1
	v_subb_co_u32_e32 v33, vcc, v33, v35, vcc
	v_lshl_add_u64 v[34:35], v[48:49], 3, s[36:37]
	global_atomic_add_x2 v[34:35], v[32:33], off
; __device__ __forceinline__ void fx_add(float* p, size_t idx, float s) { atomicAdd((unsigned long long*)p + idx, (unsigned long long)(long long)(s * 4294967296.0f)); }
; __device__ __forceinline__ unsigned cvtpk(float lo, float hi) { f32x2v_ v = {lo, hi}; bf16x2v_ b = __builtin_convertvector(v, bf16x2v_); return __builtin_bit_cast(unsigned, b); }
;     __device__ __forceinline__ void operator()(const f32x4 (&acc)[2][2][4][2], const Unit& u, int wr, int wc, int fr, int fq) const {
;     ...
;             for (int m = 0; m < 4; ++m) { const int row = row0 + ai * HALF + m * 16; const size_t off = (size_t)row * 1024 + col0; float s = 0.f;
; #pragma unroll
;                 for (int bj = 0; bj < 2; ++bj) { f32x4 a0, a1;
;                     if (xin32) { const float* p = xin32 + off + bj * HALF; a0 = *(const f32x4*)p; a1 = *(const f32x4*)(p + 4); }
;                     else { const u32x4 w = *(const u32x4*)(xb + off + bj * HALF);
;                         a0 = (f32x4){__uint_as_float(w.x << 16), __uint_as_float(w.x & 0xffff0000u), __uint_as_float(w.y << 16), __uint_as_float(w.y & 0xffff0000u)};
;                         a1 = (f32x4){__uint_as_float(w.z << 16), __uint_as_float(w.z & 0xffff0000u), __uint_as_float(w.w << 16), __uint_as_float(w.w & 0xffff0000u)}; }
;                     const f32x4 v0 = a0 + acc[ai][bj][m][0] * alpha, v1 = a1 + acc[ai][bj][m][1] * alpha;
;                     u32x4 w; w.x = cvtpk(v0[0], v0[1]); w.y = cvtpk(v0[2], v0[3]); w.z = cvtpk(v1[0], v1[1]); w.w = cvtpk(v1[2], v1[3]);
;                     *(u32x4*)(xb + off + bj * HALF) = w;
;                     s += (v0[0] * v0[0] + v0[1] * v0[1]) + (v0[2] * v0[2] + v0[3] * v0[3]) + (v1[0] * v1[0] + v1[1] * v1[1]) + (v1[2] * v1[2] + v1[3] * v1[3]); }
;                 s += __shfl_xor(s, 16); s += __shfl_xor(s, 32);
;                 if (fq == 0) fx_add(ssout, row, s); }
.LBB0_1212:
	s_or_b64 exec, exec, s[50:51]
	v_add_u32_e32 v32, 0xa0, v146
	s_waitcnt lgkmcnt(0)
	v_ashrrev_i32_e32 v33, 31, v32
	v_lshlrev_b64 v[34:35], 11, v[32:33]
	v_lshl_add_u64 v[34:35], s[22:23], 0, v[34:35]
	v_lshl_add_u64 v[42:43], v[144:145], 1, v[34:35]
	global_load_dwordx4 v[34:37], v[42:43], off
	global_load_dwordx4 v[38:41], v[42:43], off offset:256
	s_waitcnt vmcnt(1)
	v_lshlrev_b32_e32 v44, 16, v34
	v_and_b32_e32 v45, 0xffff0000, v34
	v_lshlrev_b32_e32 v34, 16, v35
	v_and_b32_e32 v35, 0xffff0000, v35
	s_waitcnt vmcnt(0)
	v_lshlrev_b32_e32 v48, 16, v38
	v_and_b32_e32 v49, 0xffff0000, v38
	v_lshlrev_b32_e32 v38, 16, v39
	v_and_b32_e32 v39, 0xffff0000, v39
	v_lshlrev_b32_e32 v46, 16, v36
	v_and_b32_e32 v47, 0xffff0000, v36
	v_lshlrev_b32_e32 v36, 16, v37
	v_and_b32_e32 v37, 0xffff0000, v37
	v_lshlrev_b32_e32 v50, 16, v40
	v_and_b32_e32 v51, 0xffff0000, v40
	v_lshlrev_b32_e32 v40, 16, v41
	v_and_b32_e32 v41, 0xffff0000, v41
	v_fma_f32 v30, v30, 0.5, v34
	v_fma_f32 v31, v31, 0.5, v35
	v_fma_f32 v28, v28, 0.5, v44
	v_fma_f32 v29, v29, 0.5, v45
	v_fma_f32 v22, v22, 0.5, v38
	v_fma_f32 v23, v23, 0.5, v39
	v_fma_f32 v20, v20, 0.5, v48
	v_fma_f32 v21, v21, 0.5, v49
	v_fma_f32 v26, v26, 0.5, v36
	v_fma_f32 v27, v27, 0.5, v37
	v_fma_f32 v24, v24, 0.5, v46
	v_fma_f32 v25, v25, 0.5, v47
	v_fma_f32 v34, v18, 0.5, v40
	v_fma_f32 v35, v19, 0.5, v41
	v_fma_f32 v36, v16, 0.5, v50
	v_fma_f32 v37, v17, 0.5, v51
	v_mul_f32_e32 v18, v29, v29
	v_mul_f32_e32 v19, v31, v31
	v_mul_f32_e32 v38, v21, v21
	v_mul_f32_e32 v39, v23, v23
	v_cvt_pk_bf16_f32 v16, v28, v29
	v_mul_f32_e32 v29, v25, v25
	v_mul_f32_e32 v40, v37, v37
	v_fmac_f32_e32 v18, v28, v28
	v_fmac_f32_e32 v19, v30, v30
	v_fmac_f32_e32 v38, v20, v20
	v_fmac_f32_e32 v39, v22, v22
	v_cvt_pk_bf16_f32 v17, v30, v31
	v_mul_f32_e32 v31, v27, v27
	v_mul_f32_e32 v41, v35, v35
	v_fmac_f32_e32 v29, v24, v24
	v_fmac_f32_e32 v40, v36, v36
	v_add_f32_e32 v18, v18, v19
	v_add_f32_e32 v19, v38, v39
	v_fmac_f32_e32 v31, v26, v26
	v_fmac_f32_e32 v41, v34, v34
	v_add_f32_e32 v18, v29, v18
	v_add_f32_e32 v19, v40, v19
	v_add_f32_e32 v18, v31, v18
	v_add_f32_e32 v19, v41, v19
	v_add_f32_e32 v28, v18, v19
	ds_bpermute_b32 v29, v156, v28
	v_cvt_pk_bf16_f32 v18, v24, v25
	v_cvt_pk_bf16_f32 v19, v26, v27
	global_store_dwordx4 v[42:43], v[16:19], off
	s_waitcnt lgkmcnt(0)
	s_nop 0
	v_add_f32_e32 v16, v28, v29
	ds_bpermute_b32 v17, v155, v16
	v_cvt_pk_bf16_f32 v18, v20, v21
	v_cvt_pk_bf16_f32 v19, v22, v23
	v_cvt_pk_bf16_f32 v20, v36, v37
	v_cvt_pk_bf16_f32 v21, v34, v35
	global_store_dwordx4 v[42:43], v[18:21], off offset:256
	s_and_saveexec_b64 s[50:51], s[10:11]
	s_cbranch_execz .LBB0_1214
	s_waitcnt lgkmcnt(0)
	v_add_f32_e32 v16, v16, v17
	v_mul_f32_e32 v16, 0x4f800000, v16
	v_trunc_f32_e32 v16, v16
	v_mul_f32_e64 v17, |v16|, s66
	v_floor_f32_e32 v17, v17
	v_fma_f32 v18, v17, s67, |v16|
	v_cvt_u32_f32_e32 v18, v18
	v_cvt_u32_f32_e32 v17, v17
	v_ashrrev_i32_e32 v19, 31, v16
	v_xor_b32_e32 v16, v18, v19
	v_xor_b32_e32 v17, v17, v19
	v_sub_co_u32_e32 v16, vcc, v16, v19
	s_nop 1
	v_subb_co_u32_e32 v17, vcc, v17, v19, vcc
	v_lshl_add_u64 v[18:19], v[32:33], 3, s[36:37]
	global_atomic_add_x2 v[18:19], v[16:17], off
.LBB0_1214:
	s_or_b64 exec, exec, s[50:51]
	v_add_u32_e32 v16, 0xb0, v146
	s_waitcnt lgkmcnt(0)
	v_ashrrev_i32_e32 v17, 31, v16
	v_lshlrev_b64 v[18:19], 11, v[16:17]
	v_lshl_add_u64 v[18:19], s[22:23], 0, v[18:19]
	v_lshl_add_u64 v[26:27], v[144:145], 1, v[18:19]
	global_load_dwordx4 v[18:21], v[26:27], off
	global_load_dwordx4 v[22:25], v[26:27], off offset:256
	s_waitcnt vmcnt(1)
	v_lshlrev_b32_e32 v28, 16, v18
	v_and_b32_e32 v29, 0xffff0000, v18
	v_lshlrev_b32_e32 v18, 16, v19
	v_and_b32_e32 v19, 0xffff0000, v19
	s_waitcnt vmcnt(0)
	v_lshlrev_b32_e32 v32, 16, v22
	v_and_b32_e32 v33, 0xffff0000, v22
	v_lshlrev_b32_e32 v22, 16, v23
	v_and_b32_e32 v23, 0xffff0000, v23
	v_lshlrev_b32_e32 v30, 16, v20
	v_and_b32_e32 v31, 0xffff0000, v20
	v_lshlrev_b32_e32 v20, 16, v21
	v_and_b32_e32 v21, 0xffff0000, v21
	v_lshlrev_b32_e32 v34, 16, v24
	v_and_b32_e32 v35, 0xffff0000, v24
	v_lshlrev_b32_e32 v24, 16, v25
	v_and_b32_e32 v25, 0xffff0000, v25
	v_fma_f32 v14, v14, 0.5, v18
	v_fma_f32 v15, v15, 0.5, v19
	v_fma_f32 v12, v12, 0.5, v28
	v_fma_f32 v13, v13, 0.5, v29
	v_fma_f32 v6, v6, 0.5, v22
	v_fma_f32 v7, v7, 0.5, v23
	v_fma_f32 v4, v4, 0.5, v32
	v_fma_f32 v5, v5, 0.5, v33
	v_fma_f32 v10, v10, 0.5, v20
	v_fma_f32 v11, v11, 0.5, v21
	v_fma_f32 v8, v8, 0.5, v30
	v_fma_f32 v9, v9, 0.5, v31
	v_fma_f32 v18, v2, 0.5, v24
	v_fma_f32 v19, v3, 0.5, v25
	v_fma_f32 v20, v0, 0.5, v34
	v_fma_f32 v21, v1, 0.5, v35
	v_mul_f32_e32 v2, v13, v13
	v_mul_f32_e32 v3, v15, v15
	v_mul_f32_e32 v22, v5, v5
	v_mul_f32_e32 v23, v7, v7
	v_cvt_pk_bf16_f32 v0, v12, v13
	v_mul_f32_e32 v13, v9, v9
	v_mul_f32_e32 v24, v21, v21
	v_fmac_f32_e32 v2, v12, v12
	v_fmac_f32_e32 v3, v14, v14
	v_fmac_f32_e32 v22, v4, v4
	v_fmac_f32_e32 v23, v6, v6
	v_cvt_pk_bf16_f32 v1, v14, v15
	v_mul_f32_e32 v15, v11, v11
	v_mul_f32_e32 v25, v19, v19
	v_fmac_f32_e32 v13, v8, v8
	v_fmac_f32_e32 v24, v20, v20
	v_add_f32_e32 v2, v2, v3
	v_add_f32_e32 v3, v22, v23
	v_fmac_f32_e32 v15, v10, v10
	v_fmac_f32_e32 v25, v18, v18
	v_add_f32_e32 v2, v13, v2
	v_add_f32_e32 v3, v24, v3
	v_add_f32_e32 v2, v15, v2
	v_add_f32_e32 v3, v25, v3
	v_add_f32_e32 v12, v2, v3
	ds_bpermute_b32 v13, v156, v12
	v_cvt_pk_bf16_f32 v2, v8, v9
	v_cvt_pk_bf16_f32 v3, v10, v11
	global_store_dwordx4 v[26:27], v[0:3], off
	s_waitcnt lgkmcnt(0)
	s_nop 0
	v_add_f32_e32 v0, v12, v13
	ds_bpermute_b32 v1, v155, v0
	v_cvt_pk_bf16_f32 v2, v4, v5
	v_cvt_pk_bf16_f32 v3, v6, v7
	v_cvt_pk_bf16_f32 v4, v20, v21
	v_cvt_pk_bf16_f32 v5, v18, v19
	global_store_dwordx4 v[26:27], v[2:5], off offset:256
	s_and_saveexec_b64 s[50:51], s[10:11]
	s_cbranch_execz .LBB0_1216
	s_waitcnt lgkmcnt(0)
	v_add_f32_e32 v0, v0, v1
	v_mul_f32_e32 v0, 0x4f800000, v0
	v_trunc_f32_e32 v0, v0
	v_mul_f32_e64 v1, |v0|, s66
	v_floor_f32_e32 v1, v1
	v_fma_f32 v2, v1, s67, |v0|
	v_cvt_u32_f32_e32 v2, v2
	v_cvt_u32_f32_e32 v1, v1
	v_ashrrev_i32_e32 v3, 31, v0
	v_xor_b32_e32 v0, v2, v3
	v_xor_b32_e32 v1, v1, v3
	v_sub_co_u32_e32 v0, vcc, v0, v3
	s_nop 1
	v_subb_co_u32_e32 v1, vcc, v1, v3, vcc
	v_lshl_add_u64 v[2:3], v[16:17], 3, s[36:37]
	global_atomic_add_x2 v[2:3], v[0:1], off

; #define LAS __attribute__((address_space(3)))
; template <int l> __device__ __forceinline__ void layer_body(const Args& args, LAS unsigned char* lds, const XcdBarrier& bar) {
;     ...
;                     auto logits = [&](int tt, f32x16& s_) {
;                         const int n = tt >> 3; const bool sel = (n >= own) || ((selmask >> n) & 1u);
;                         if (j * 32 - (tt * 32 + 31) >= 128) { const float madd = sel ? b128 : -INFINITY; s_ = s_ * scale2 + madd; }
;                         else { const LAS float* bp = tb + (TPAD - 23) + (qpos - tt * 32 - 8 * hh); const float madd = sel ? 0.0f : -INFINITY;
; #pragma unroll
;                             for (int i = 0; i < 16; ++i) s_[i] = __builtin_fmaf(s_[i], scale2, bp[23 - kofs(i)] + madd); } };
.LBB0_1518:
	s_andn2_b64 vcc, exec, s[50:51]
	s_cbranch_vccnz .LBB0_1520
	v_cndmask_b32_e64 v2, v183, v188, s[10:11]
	v_fma_f32 v174, v110, s46, v2
	v_fma_f32 v175, v111, s46, v2
	v_fma_f32 v14, v108, s46, v2
	v_fma_f32 v15, v109, s46, v2
	v_fma_f32 v12, v106, s46, v2
	v_fma_f32 v13, v107, s46, v2
	v_fma_f32 v10, v104, s46, v2
	v_fma_f32 v11, v105, s46, v2
	v_fma_f32 v8, v102, s46, v2
	v_fma_f32 v9, v103, s46, v2
	v_fma_f32 v6, v100, s46, v2
	v_fma_f32 v7, v101, s46, v2
	v_fma_f32 v4, v98, s46, v2
	v_fma_f32 v5, v99, s46, v2
	v_fma_f32 v3, v97, s46, v2
	v_fma_f32 v2, v96, s46, v2
.LBB0_1520:
	s_cmp_ge_i32 s77, s62
	s_cselect_b64 s[10:11], -1, 0
	v_cmp_ne_u32_e32 vcc, 0, v1
	s_or_b64 s[10:11], s[10:11], vcc
	s_cmpk_lt_i32 s67, 0x80
	s_mov_b64 s[50:51], -1
	s_cbranch_scc0 .LBB0_1522
	ds_read2_b32 v[96:97], v192 offset0:22 offset1:23
	ds_read2_b32 v[98:99], v192 offset0:20 offset1:21
	ds_read2_b32 v[100:101], v192 offset0:18 offset1:19
	ds_read2_b32 v[104:105], v192 offset0:16 offset1:17
	ds_read2_b32 v[106:107], v192 offset0:6 offset1:7
	ds_read2_b32 v[110:111], v192 offset0:4 offset1:5
	ds_read2_b32 v[194:195], v192 offset1:1
	v_cndmask_b32_e64 v108, v183, 0, s[10:11]
	s_waitcnt lgkmcnt(0)
	v_pk_add_f32 v[100:101], v[108:109], v[100:101] op_sel_hi:[0,1]
	v_fma_f32 v102, v84, s46, v101
	v_fma_f32 v103, v85, s46, v100
	v_pk_add_f32 v[100:101], v[108:109], v[104:105] op_sel_hi:[0,1]
	v_pk_add_f32 v[104:105], v[108:109], v[106:107] op_sel_hi:[0,1]
	ds_read2_b32 v[106:107], v192 offset0:2 offset1:3
	v_pk_add_f32 v[96:97], v[108:109], v[96:97] op_sel_hi:[0,1]
	v_pk_add_f32 v[98:99], v[108:109], v[98:99] op_sel_hi:[0,1]
	v_pk_add_f32 v[110:111], v[108:109], v[110:111] op_sel_hi:[0,1]
	v_pk_fma_f32 v[96:97], v[80:81], s[46:47], v[96:97] op_sel:[0,0,1] op_sel_hi:[1,0,0]
	s_waitcnt lgkmcnt(0)
	v_pk_add_f32 v[106:107], v[108:109], v[106:107] op_sel_hi:[0,1]
	v_pk_add_f32 v[108:109], v[108:109], v[194:195] op_sel_hi:[0,1]
	v_pk_fma_f32 v[98:99], v[82:83], s[46:47], v[98:99] op_sel:[0,0,1] op_sel_hi:[1,0,0]
	v_pk_fma_f32 v[100:101], v[86:87], s[46:47], v[100:101] op_sel:[0,0,1] op_sel_hi:[1,0,0]
	v_pk_fma_f32 v[104:105], v[88:89], s[46:47], v[104:105] op_sel:[0,0,1] op_sel_hi:[1,0,0]
	v_pk_fma_f32 v[110:111], v[90:91], s[46:47], v[110:111] op_sel:[0,0,1] op_sel_hi:[1,0,0]
	v_pk_fma_f32 v[106:107], v[92:93], s[46:47], v[106:107] op_sel:[0,0,1] op_sel_hi:[1,0,0]
	v_pk_fma_f32 v[108:109], v[94:95], s[46:47], v[108:109] op_sel:[0,0,1] op_sel_hi:[1,0,0]
	s_mov_b64 s[50:51], 0
.LBB0_1522:
	s_andn2_b64 vcc, exec, s[50:51]
	s_cbranch_vccnz .LBB0_1524
	v_cndmask_b32_e64 v96, v183, v188, s[10:11]
	v_fma_f32 v108, v94, s46, v96
	v_fma_f32 v109, v95, s46, v96
	v_fma_f32 v106, v92, s46, v96
	v_fma_f32 v107, v93, s46, v96
	v_fma_f32 v110, v90, s46, v96
	v_fma_f32 v111, v91, s46, v96
	v_fma_f32 v104, v88, s46, v96
	v_fma_f32 v105, v89, s46, v96
	v_fma_f32 v100, v86, s46, v96
	v_fma_f32 v101, v87, s46, v96
	v_fma_f32 v102, v84, s46, v96
	v_fma_f32 v103, v85, s46, v96
	v_fma_f32 v98, v82, s46, v96
	v_fma_f32 v99, v83, s46, v96
	v_fma_f32 v97, v81, s46, v96
	v_fma_f32 v96, v80, s46, v96

; __device__ __forceinline__ void fx_add(float* p, size_t idx, float s) { atomicAdd((unsigned long long*)p + idx, (unsigned long long)(long long)(s * 4294967296.0f)); }
; __device__ __forceinline__ unsigned cvtpk(float lo, float hi) { f32x2v_ v = {lo, hi}; bf16x2v_ b = __builtin_convertvector(v, bf16x2v_); return __builtin_bit_cast(unsigned, b); }
;     __device__ __forceinline__ void operator()(const f32x4 (&acc)[2][2][4][2], const Unit& u, int wr, int wc, int fr, int fq) const {
;     ...
;             for (int m = 0; m < 4; ++m) { const int row = row0 + ai * HALF + m * 16; const size_t off = (size_t)row * 1024 + col0; float s = 0.f;
; #pragma unroll
;                 for (int bj = 0; bj < 2; ++bj) { f32x4 a0, a1;
;                     if (xin32) { const float* p = xin32 + off + bj * HALF; a0 = *(const f32x4*)p; a1 = *(const f32x4*)(p + 4); }
;                     else { const u32x4 w = *(const u32x4*)(xb + off + bj * HALF);
;                         a0 = (f32x4){__uint_as_float(w.x << 16), __uint_as_float(w.x & 0xffff0000u), __uint_as_float(w.y << 16), __uint_as_float(w.y & 0xffff0000u)};
;                         a1 = (f32x4){__uint_as_float(w.z << 16), __uint_as_float(w.z & 0xffff0000u), __uint_as_float(w.w << 16), __uint_as_float(w.w & 0xffff0000u)}; }
;                     const f32x4 v0 = a0 + acc[ai][bj][m][0] * alpha, v1 = a1 + acc[ai][bj][m][1] * alpha;
;                     u32x4 w; w.x = cvtpk(v0[0], v0[1]); w.y = cvtpk(v0[2], v0[3]); w.z = cvtpk(v1[0], v1[1]); w.w = cvtpk(v1[2], v1[3]);
;                     *(u32x4*)(xb + off + bj * HALF) = w;
;                     s += (v0[0] * v0[0] + v0[1] * v0[1]) + (v0[2] * v0[2] + v0[3] * v0[3]) + (v1[0] * v1[0] + v1[1] * v1[1]) + (v1[2] * v1[2] + v1[3] * v1[3]); }
;                 s += __shfl_xor(s, 16); s += __shfl_xor(s, 32);
;                 if (fq == 0) fx_add(ssout, row, s); }
.LBB0_1981:
	v_lshl_add_u32 v146, s52, 8, v148
	v_ashrrev_i32_e32 v147, 31, v146
	v_lshl_or_b32 v144, s51, 8, v150
	v_lshlrev_b64 v[156:157], 11, v[146:147]
	v_ashrrev_i32_e32 v145, 31, v144
	v_lshl_add_u64 v[156:157], s[22:23], 0, v[156:157]
	v_lshl_add_u64 v[166:167], v[144:145], 1, v[156:157]
	global_load_dwordx4 v[158:161], v[166:167], off
	global_load_dwordx4 v[162:165], v[166:167], off offset:256
	v_and_b32_e32 v156, 64, v154
	v_xor_b32_e32 v155, 16, v154
	v_add_u32_e32 v156, 64, v156
	v_xor_b32_e32 v157, 32, v154
	v_cmp_lt_i32_e32 vcc, v155, v156
	s_waitcnt vmcnt(0)
	v_lshlrev_b32_e32 v168, 16, v158
	v_cndmask_b32_e32 v155, v154, v155, vcc
	v_cmp_lt_i32_e32 vcc, v157, v156
	v_and_b32_e32 v169, 0xffff0000, v158
	v_lshlrev_b32_e32 v158, 16, v159
	v_and_b32_e32 v159, 0xffff0000, v159
	v_lshlrev_b32_e32 v172, 16, v162
	v_and_b32_e32 v173, 0xffff0000, v162
	v_lshlrev_b32_e32 v162, 16, v163
	v_and_b32_e32 v163, 0xffff0000, v163
	v_cndmask_b32_e32 v157, v154, v157, vcc
	v_lshlrev_b32_e32 v170, 16, v160
	v_and_b32_e32 v171, 0xffff0000, v160
	v_lshlrev_b32_e32 v160, 16, v161
	v_and_b32_e32 v161, 0xffff0000, v161
	v_lshlrev_b32_e32 v174, 16, v164
	v_and_b32_e32 v175, 0xffff0000, v164
	v_lshlrev_b32_e32 v164, 16, v165
	v_and_b32_e32 v165, 0xffff0000, v165
	v_fma_f32 v126, v126, 0.5, v158
	v_fma_f32 v127, v127, 0.5, v159
	v_fma_f32 v124, v124, 0.5, v168
	v_fma_f32 v125, v125, 0.5, v169
	v_fma_f32 v118, v118, 0.5, v162
	v_fma_f32 v119, v119, 0.5, v163
	v_fma_f32 v116, v116, 0.5, v172
	v_fma_f32 v117, v117, 0.5, v173
	v_lshlrev_b32_e32 v156, 2, v155
	v_lshlrev_b32_e32 v155, 2, v157
	v_fma_f32 v122, v122, 0.5, v160
	v_fma_f32 v123, v123, 0.5, v161
	v_fma_f32 v120, v120, 0.5, v170
	v_fma_f32 v121, v121, 0.5, v171
	v_fma_f32 v158, v114, 0.5, v164
	v_fma_f32 v159, v115, 0.5, v165
	v_fma_f32 v160, v112, 0.5, v174
	v_fma_f32 v161, v113, 0.5, v175
	v_mul_f32_e32 v114, v125, v125
	v_mul_f32_e32 v115, v127, v127
	v_mul_f32_e32 v157, v117, v117
	v_mul_f32_e32 v162, v119, v119
	v_cvt_pk_bf16_f32 v112, v124, v125
	v_mul_f32_e32 v125, v121, v121
	v_mul_f32_e32 v163, v161, v161
	v_fmac_f32_e32 v114, v124, v124
	v_fmac_f32_e32 v115, v126, v126
	v_fmac_f32_e32 v157, v116, v116
	v_fmac_f32_e32 v162, v118, v118
	v_cvt_pk_bf16_f32 v113, v126, v127
	v_mul_f32_e32 v127, v123, v123
	v_mul_f32_e32 v164, v159, v159
	v_fmac_f32_e32 v125, v120, v120
	v_fmac_f32_e32 v163, v160, v160
	v_add_f32_e32 v114, v114, v115
	v_add_f32_e32 v115, v157, v162
	v_fmac_f32_e32 v127, v122, v122
	v_fmac_f32_e32 v164, v158, v158
	v_add_f32_e32 v114, v125, v114
	v_add_f32_e32 v115, v163, v115
	v_add_f32_e32 v114, v127, v114
	v_add_f32_e32 v115, v164, v115
	v_add_f32_e32 v124, v114, v115
	ds_bpermute_b32 v125, v156, v124
	v_cvt_pk_bf16_f32 v114, v120, v121
	v_cvt_pk_bf16_f32 v115, v122, v123
	global_store_dwordx4 v[166:167], v[112:115], off
	s_waitcnt lgkmcnt(0)
	s_nop 0
	v_add_f32_e32 v112, v124, v125
	ds_bpermute_b32 v113, v155, v112
	v_cvt_pk_bf16_f32 v114, v116, v117
	v_cvt_pk_bf16_f32 v115, v118, v119
	v_cvt_pk_bf16_f32 v116, v160, v161
	v_cvt_pk_bf16_f32 v117, v158, v159
	global_store_dwordx4 v[166:167], v[114:117], off offset:256
	s_and_saveexec_b64 s[26:27], s[6:7]
	s_cbranch_execz .LBB0_1983
	s_waitcnt lgkmcnt(0)
	v_add_f32_e32 v112, v112, v113
	v_mul_f32_e32 v112, 0x4f800000, v112
	v_trunc_f32_e32 v112, v112
	v_mul_f32_e64 v113, |v112|, s47
	v_floor_f32_e32 v113, v113
	v_fma_f32 v114, v113, s48, |v112|
	v_cvt_u32_f32_e32 v114, v114
	v_cvt_u32_f32_e32 v113, v113
	v_ashrrev_i32_e32 v115, 31, v112
	v_xor_b32_e32 v112, v114, v115
	v_xor_b32_e32 v113, v113, v115
	v_sub_co_u32_e32 v112, vcc, v112, v115
	s_nop 1
	v_subb_co_u32_e32 v113, vcc, v113, v115, vcc
	v_lshl_add_u64 v[114:115], v[146:147], 3, s[10:11]
	global_atomic_add_x2 v[114:115], v[112:113], off
.LBB0_1983:
	s_or_b64 exec, exec, s[26:27]
	v_or_b32_e32 v112, 16, v146
	s_waitcnt lgkmcnt(0)
	v_ashrrev_i32_e32 v113, 31, v112
	v_lshlrev_b64 v[114:115], 11, v[112:113]
	v_lshl_add_u64 v[114:115], s[22:23], 0, v[114:115]
	v_lshl_add_u64 v[122:123], v[144:145], 1, v[114:115]
	global_load_dwordx4 v[114:117], v[122:123], off
	global_load_dwordx4 v[118:121], v[122:123], off offset:256
	s_waitcnt vmcnt(1)
	v_lshlrev_b32_e32 v124, 16, v114
	v_and_b32_e32 v125, 0xffff0000, v114
	v_lshlrev_b32_e32 v114, 16, v115
	v_and_b32_e32 v115, 0xffff0000, v115
	s_waitcnt vmcnt(0)
	v_lshlrev_b32_e32 v158, 16, v118
	v_and_b32_e32 v159, 0xffff0000, v118
	v_lshlrev_b32_e32 v118, 16, v119
	v_and_b32_e32 v119, 0xffff0000, v119
	v_lshlrev_b32_e32 v126, 16, v116
	v_and_b32_e32 v127, 0xffff0000, v116
	v_lshlrev_b32_e32 v116, 16, v117
	v_and_b32_e32 v117, 0xffff0000, v117
	v_lshlrev_b32_e32 v160, 16, v120
	v_and_b32_e32 v161, 0xffff0000, v120
	v_lshlrev_b32_e32 v120, 16, v121
	v_and_b32_e32 v121, 0xffff0000, v121
	v_fma_f32 v110, v110, 0.5, v114
	v_fma_f32 v111, v111, 0.5, v115
	v_fma_f32 v108, v108, 0.5, v124
	v_fma_f32 v109, v109, 0.5, v125
	v_fma_f32 v102, v102, 0.5, v118
	v_fma_f32 v103, v103, 0.5, v119
	v_fma_f32 v100, v100, 0.5, v158
	v_fma_f32 v101, v101, 0.5, v159
	v_fma_f32 v106, v106, 0.5, v116
	v_fma_f32 v107, v107, 0.5, v117
	v_fma_f32 v104, v104, 0.5, v126
	v_fma_f32 v105, v105, 0.5, v127
	v_fma_f32 v114, v98, 0.5, v120
	v_fma_f32 v115, v99, 0.5, v121
	v_fma_f32 v116, v96, 0.5, v160
	v_fma_f32 v117, v97, 0.5, v161
	v_mul_f32_e32 v98, v109, v109
	v_mul_f32_e32 v99, v111, v111
	v_mul_f32_e32 v118, v101, v101
	v_mul_f32_e32 v119, v103, v103
	v_cvt_pk_bf16_f32 v96, v108, v109
	v_mul_f32_e32 v109, v105, v105
	v_mul_f32_e32 v120, v117, v117
	v_fmac_f32_e32 v98, v108, v108
	v_fmac_f32_e32 v99, v110, v110
	v_fmac_f32_e32 v118, v100, v100
	v_fmac_f32_e32 v119, v102, v102
	v_cvt_pk_bf16_f32 v97, v110, v111
	v_mul_f32_e32 v111, v107, v107
	v_mul_f32_e32 v121, v115, v115
	v_fmac_f32_e32 v109, v104, v104
	v_fmac_f32_e32 v120, v116, v116
	v_add_f32_e32 v98, v98, v99
	v_add_f32_e32 v99, v118, v119
	v_fmac_f32_e32 v111, v106, v106
	v_fmac_f32_e32 v121, v114, v114
	v_add_f32_e32 v98, v109, v98
	v_add_f32_e32 v99, v120, v99
	v_add_f32_e32 v98, v111, v98
	v_add_f32_e32 v99, v121, v99
	v_add_f32_e32 v108, v98, v99
	ds_bpermute_b32 v109, v156, v108
	v_cvt_pk_bf16_f32 v98, v104, v105
	v_cvt_pk_bf16_f32 v99, v106, v107
	global_store_dwordx4 v[122:123], v[96:99], off
	s_waitcnt lgkmcnt(0)
	s_nop 0
	v_add_f32_e32 v96, v108, v109
	ds_bpermute_b32 v97, v155, v96
	v_cvt_pk_bf16_f32 v98, v100, v101
	v_cvt_pk_bf16_f32 v99, v102, v103
	v_cvt_pk_bf16_f32 v100, v116, v117
	v_cvt_pk_bf16_f32 v101, v114, v115
	global_store_dwordx4 v[122:123], v[98:101], off offset:256
	s_and_saveexec_b64 s[26:27], s[6:7]
	s_cbranch_execz .LBB0_1985
; __device__ __forceinline__ void fx_add(float* p, size_t idx, float s) { atomicAdd((unsigned long long*)p + idx, (unsigned long long)(long long)(s * 4294967296.0f)); }
; __device__ __forceinline__ unsigned cvtpk(float lo, float hi) { f32x2v_ v = {lo, hi}; bf16x2v_ b = __builtin_convertvector(v, bf16x2v_); return __builtin_bit_cast(unsigned, b); }
;     __device__ __forceinline__ void operator()(const f32x4 (&acc)[2][2][4][2], const Unit& u, int wr, int wc, int fr, int fq) const {
;     ...
;             for (int m = 0; m < 4; ++m) { const int row = row0 + ai * HALF + m * 16; const size_t off = (size_t)row * 1024 + col0; float s = 0.f;
; #pragma unroll
;                 for (int bj = 0; bj < 2; ++bj) { f32x4 a0, a1;
;                     if (xin32) { const float* p = xin32 + off + bj * HALF; a0 = *(const f32x4*)p; a1 = *(const f32x4*)(p + 4); }
;                     else { const u32x4 w = *(const u32x4*)(xb + off + bj * HALF);
;                         a0 = (f32x4){__uint_as_float(w.x << 16), __uint_as_float(w.x & 0xffff0000u), __uint_as_float(w.y << 16), __uint_as_float(w.y & 0xffff0000u)};
;                         a1 = (f32x4){__uint_as_float(w.z << 16), __uint_as_float(w.z & 0xffff0000u), __uint_as_float(w.w << 16), __uint_as_float(w.w & 0xffff0000u)}; }
;                     const f32x4 v0 = a0 + acc[ai][bj][m][0] * alpha, v1 = a1 + acc[ai][bj][m][1] * alpha;
;                     u32x4 w; w.x = cvtpk(v0[0], v0[1]); w.y = cvtpk(v0[2], v0[3]); w.z = cvtpk(v1[0], v1[1]); w.w = cvtpk(v1[2], v1[3]);
;                     *(u32x4*)(xb + off + bj * HALF) = w;
;                     s += (v0[0] * v0[0] + v0[1] * v0[1]) + (v0[2] * v0[2] + v0[3] * v0[3]) + (v1[0] * v1[0] + v1[1] * v1[1]) + (v1[2] * v1[2] + v1[3] * v1[3]); }
;                 s += __shfl_xor(s, 16); s += __shfl_xor(s, 32);
;                 if (fq == 0) fx_add(ssout, row, s); }
	s_waitcnt lgkmcnt(0)
	v_add_f32_e32 v96, v96, v97
	v_mul_f32_e32 v96, 0x4f800000, v96
	v_trunc_f32_e32 v96, v96
	v_mul_f32_e64 v97, |v96|, s47
	v_floor_f32_e32 v97, v97
	v_fma_f32 v98, v97, s48, |v96|
	v_cvt_u32_f32_e32 v98, v98
	v_cvt_u32_f32_e32 v97, v97
	v_ashrrev_i32_e32 v99, 31, v96
	v_xor_b32_e32 v96, v98, v99
	v_xor_b32_e32 v97, v97, v99
	v_sub_co_u32_e32 v96, vcc, v96, v99
	s_nop 1
	v_subb_co_u32_e32 v97, vcc, v97, v99, vcc
	v_lshl_add_u64 v[98:99], v[112:113], 3, s[10:11]
	global_atomic_add_x2 v[98:99], v[96:97], off
.LBB0_1985:
	s_or_b64 exec, exec, s[26:27]
	v_or_b32_e32 v96, 32, v146
	s_waitcnt lgkmcnt(0)
	v_ashrrev_i32_e32 v97, 31, v96
	v_lshlrev_b64 v[98:99], 11, v[96:97]
	v_lshl_add_u64 v[98:99], s[22:23], 0, v[98:99]
	v_lshl_add_u64 v[106:107], v[144:145], 1, v[98:99]
	global_load_dwordx4 v[98:101], v[106:107], off
	global_load_dwordx4 v[102:105], v[106:107], off offset:256
	s_waitcnt vmcnt(1)
	v_lshlrev_b32_e32 v108, 16, v98
	v_and_b32_e32 v109, 0xffff0000, v98
	v_lshlrev_b32_e32 v98, 16, v99
	v_and_b32_e32 v99, 0xffff0000, v99
	s_waitcnt vmcnt(0)
	v_lshlrev_b32_e32 v112, 16, v102
	v_and_b32_e32 v113, 0xffff0000, v102
	v_lshlrev_b32_e32 v102, 16, v103
	v_and_b32_e32 v103, 0xffff0000, v103
	v_lshlrev_b32_e32 v110, 16, v100
	v_and_b32_e32 v111, 0xffff0000, v100
	v_lshlrev_b32_e32 v100, 16, v101
	v_and_b32_e32 v101, 0xffff0000, v101
	v_lshlrev_b32_e32 v114, 16, v104
	v_and_b32_e32 v115, 0xffff0000, v104
	v_lshlrev_b32_e32 v104, 16, v105
	v_and_b32_e32 v105, 0xffff0000, v105
	v_fma_f32 v94, v94, 0.5, v98
	v_fma_f32 v95, v95, 0.5, v99
	v_fma_f32 v92, v92, 0.5, v108
	v_fma_f32 v93, v93, 0.5, v109
	v_fma_f32 v86, v86, 0.5, v102
	v_fma_f32 v87, v87, 0.5, v103
	v_fma_f32 v84, v84, 0.5, v112
	v_fma_f32 v85, v85, 0.5, v113
	v_fma_f32 v90, v90, 0.5, v100
	v_fma_f32 v91, v91, 0.5, v101
	v_fma_f32 v88, v88, 0.5, v110
	v_fma_f32 v89, v89, 0.5, v111
	v_fma_f32 v98, v82, 0.5, v104
	v_fma_f32 v99, v83, 0.5, v105
	v_fma_f32 v100, v80, 0.5, v114
	v_fma_f32 v101, v81, 0.5, v115
	v_mul_f32_e32 v82, v93, v93
	v_mul_f32_e32 v83, v95, v95
	v_mul_f32_e32 v102, v85, v85
	v_mul_f32_e32 v103, v87, v87
	v_cvt_pk_bf16_f32 v80, v92, v93
	v_mul_f32_e32 v93, v89, v89
	v_mul_f32_e32 v104, v101, v101
	v_fmac_f32_e32 v82, v92, v92
	v_fmac_f32_e32 v83, v94, v94
	v_fmac_f32_e32 v102, v84, v84
	v_fmac_f32_e32 v103, v86, v86
	v_cvt_pk_bf16_f32 v81, v94, v95
	v_mul_f32_e32 v95, v91, v91
	v_mul_f32_e32 v105, v99, v99
	v_fmac_f32_e32 v93, v88, v88
	v_fmac_f32_e32 v104, v100, v100
	v_add_f32_e32 v82, v82, v83
	v_add_f32_e32 v83, v102, v103
	v_fmac_f32_e32 v95, v90, v90
	v_fmac_f32_e32 v105, v98, v98
	v_add_f32_e32 v82, v93, v82
	v_add_f32_e32 v83, v104, v83
	v_add_f32_e32 v82, v95, v82
	v_add_f32_e32 v83, v105, v83
	v_add_f32_e32 v92, v82, v83
	ds_bpermute_b32 v93, v156, v92
	v_cvt_pk_bf16_f32 v82, v88, v89
	v_cvt_pk_bf16_f32 v83, v90, v91
	global_store_dwordx4 v[106:107], v[80:83], off
	s_waitcnt lgkmcnt(0)
	s_nop 0
	v_add_f32_e32 v80, v92, v93
	ds_bpermute_b32 v81, v155, v80
	v_cvt_pk_bf16_f32 v82, v84, v85
	v_cvt_pk_bf16_f32 v83, v86, v87
	v_cvt_pk_bf16_f32 v84, v100, v101
	v_cvt_pk_bf16_f32 v85, v98, v99
	global_store_dwordx4 v[106:107], v[82:85], off offset:256
	s_and_saveexec_b64 s[26:27], s[6:7]
	s_cbranch_execz .LBB0_1987
	s_waitcnt lgkmcnt(0)
	v_add_f32_e32 v80, v80, v81
	v_mul_f32_e32 v80, 0x4f800000, v80
	v_trunc_f32_e32 v80, v80
	v_mul_f32_e64 v81, |v80|, s47
	v_floor_f32_e32 v81, v81
	v_fma_f32 v82, v81, s48, |v80|
	v_cvt_u32_f32_e32 v82, v82
	v_cvt_u32_f32_e32 v81, v81
	v_ashrrev_i32_e32 v83, 31, v80
	v_xor_b32_e32 v80, v82, v83
	v_xor_b32_e32 v81, v81, v83
	v_sub_co_u32_e32 v80, vcc, v80, v83
	s_nop 1
	v_subb_co_u32_e32 v81, vcc, v81, v83, vcc
	v_lshl_add_u64 v[82:83], v[96:97], 3, s[10:11]
	global_atomic_add_x2 v[82:83], v[80:81], off
.LBB0_1987:
	s_or_b64 exec, exec, s[26:27]
	v_or_b32_e32 v80, 48, v146
	s_waitcnt lgkmcnt(0)
	v_ashrrev_i32_e32 v81, 31, v80
	v_lshlrev_b64 v[82:83], 11, v[80:81]
	v_lshl_add_u64 v[82:83], s[22:23], 0, v[82:83]
	v_lshl_add_u64 v[90:91], v[144:145], 1, v[82:83]
	global_load_dwordx4 v[82:85], v[90:91], off
	global_load_dwordx4 v[86:89], v[90:91], off offset:256
	s_waitcnt vmcnt(1)
	v_lshlrev_b32_e32 v92, 16, v82
	v_and_b32_e32 v93, 0xffff0000, v82
	v_lshlrev_b32_e32 v82, 16, v83
	v_and_b32_e32 v83, 0xffff0000, v83
	s_waitcnt vmcnt(0)
	v_lshlrev_b32_e32 v96, 16, v86
	v_and_b32_e32 v97, 0xffff0000, v86
	v_lshlrev_b32_e32 v86, 16, v87
	v_and_b32_e32 v87, 0xffff0000, v87
	v_lshlrev_b32_e32 v94, 16, v84
	v_and_b32_e32 v95, 0xffff0000, v84
	v_lshlrev_b32_e32 v84, 16, v85
	v_and_b32_e32 v85, 0xffff0000, v85
	v_lshlrev_b32_e32 v98, 16, v88
	v_and_b32_e32 v99, 0xffff0000, v88
	v_lshlrev_b32_e32 v88, 16, v89
	v_and_b32_e32 v89, 0xffff0000, v89
	v_fma_f32 v78, v78, 0.5, v82
	v_fma_f32 v79, v79, 0.5, v83
	v_fma_f32 v76, v76, 0.5, v92
	v_fma_f32 v77, v77, 0.5, v93
	v_fma_f32 v70, v70, 0.5, v86
	v_fma_f32 v71, v71, 0.5, v87
	v_fma_f32 v68, v68, 0.5, v96
	v_fma_f32 v69, v69, 0.5, v97
	v_fma_f32 v74, v74, 0.5, v84
	v_fma_f32 v75, v75, 0.5, v85
	v_fma_f32 v72, v72, 0.5, v94
	v_fma_f32 v73, v73, 0.5, v95
	v_fma_f32 v82, v66, 0.5, v88
	v_fma_f32 v83, v67, 0.5, v89
	v_fma_f32 v84, v64, 0.5, v98
	v_fma_f32 v85, v65, 0.5, v99
	v_mul_f32_e32 v66, v77, v77
	v_mul_f32_e32 v67, v79, v79
	v_mul_f32_e32 v86, v69, v69
	v_mul_f32_e32 v87, v71, v71
	v_cvt_pk_bf16_f32 v64, v76, v77
	v_mul_f32_e32 v77, v73, v73
	v_mul_f32_e32 v88, v85, v85
	v_fmac_f32_e32 v66, v76, v76
	v_fmac_f32_e32 v67, v78, v78
	v_fmac_f32_e32 v86, v68, v68
	v_fmac_f32_e32 v87, v70, v70
	v_cvt_pk_bf16_f32 v65, v78, v79
	v_mul_f32_e32 v79, v75, v75
	v_mul_f32_e32 v89, v83, v83
	v_fmac_f32_e32 v77, v72, v72
	v_fmac_f32_e32 v88, v84, v84
	v_add_f32_e32 v66, v66, v67
	v_add_f32_e32 v67, v86, v87
	v_fmac_f32_e32 v79, v74, v74
	v_fmac_f32_e32 v89, v82, v82
	v_add_f32_e32 v66, v77, v66
	v_add_f32_e32 v67, v88, v67
	v_add_f32_e32 v66, v79, v66
	v_add_f32_e32 v67, v89, v67
	v_add_f32_e32 v76, v66, v67
	ds_bpermute_b32 v77, v156, v76
	v_cvt_pk_bf16_f32 v66, v72, v73
	v_cvt_pk_bf16_f32 v67, v74, v75
	global_store_dwordx4 v[90:91], v[64:67], off
	s_waitcnt lgkmcnt(0)
	s_nop 0
	v_add_f32_e32 v64, v76, v77
	ds_bpermute_b32 v65, v155, v64
	v_cvt_pk_bf16_f32 v66, v68, v69
	v_cvt_pk_bf16_f32 v67, v70, v71
	v_cvt_pk_bf16_f32 v68, v84, v85
	v_cvt_pk_bf16_f32 v69, v82, v83
	global_store_dwordx4 v[90:91], v[66:69], off offset:256
	s_and_saveexec_b64 s[26:27], s[6:7]
	s_cbranch_execz .LBB0_1989
	s_waitcnt lgkmcnt(0)
	v_add_f32_e32 v64, v64, v65
	v_mul_f32_e32 v64, 0x4f800000, v64
	v_trunc_f32_e32 v64, v64
	v_mul_f32_e64 v65, |v64|, s47
	v_floor_f32_e32 v65, v65
	v_fma_f32 v66, v65, s48, |v64|
	v_cvt_u32_f32_e32 v66, v66
	v_cvt_u32_f32_e32 v65, v65
	v_ashrrev_i32_e32 v67, 31, v64
	v_xor_b32_e32 v64, v66, v67
	v_xor_b32_e32 v65, v65, v67
	v_sub_co_u32_e32 v64, vcc, v64, v67
	s_nop 1
	v_subb_co_u32_e32 v65, vcc, v65, v67, vcc
	v_lshl_add_u64 v[66:67], v[80:81], 3, s[10:11]
	global_atomic_add_x2 v[66:67], v[64:65], off
; __device__ __forceinline__ void fx_add(float* p, size_t idx, float s) { atomicAdd((unsigned long long*)p + idx, (unsigned long long)(long long)(s * 4294967296.0f)); }
; __device__ __forceinline__ unsigned cvtpk(float lo, float hi) { f32x2v_ v = {lo, hi}; bf16x2v_ b = __builtin_convertvector(v, bf16x2v_); return __builtin_bit_cast(unsigned, b); }
;     __device__ __forceinline__ void operator()(const f32x4 (&acc)[2][2][4][2], const Unit& u, int wr, int wc, int fr, int fq) const {
;     ...
;             for (int m = 0; m < 4; ++m) { const int row = row0 + ai * HALF + m * 16; const size_t off = (size_t)row * 1024 + col0; float s = 0.f;
; #pragma unroll
;                 for (int bj = 0; bj < 2; ++bj) { f32x4 a0, a1;
;                     if (xin32) { const float* p = xin32 + off + bj * HALF; a0 = *(const f32x4*)p; a1 = *(const f32x4*)(p + 4); }
;                     else { const u32x4 w = *(const u32x4*)(xb + off + bj * HALF);
;                         a0 = (f32x4){__uint_as_float(w.x << 16), __uint_as_float(w.x & 0xffff0000u), __uint_as_float(w.y << 16), __uint_as_float(w.y & 0xffff0000u)};
;                         a1 = (f32x4){__uint_as_float(w.z << 16), __uint_as_float(w.z & 0xffff0000u), __uint_as_float(w.w << 16), __uint_as_float(w.w & 0xffff0000u)}; }
;                     const f32x4 v0 = a0 + acc[ai][bj][m][0] * alpha, v1 = a1 + acc[ai][bj][m][1] * alpha;
;                     u32x4 w; w.x = cvtpk(v0[0], v0[1]); w.y = cvtpk(v0[2], v0[3]); w.z = cvtpk(v1[0], v1[1]); w.w = cvtpk(v1[2], v1[3]);
;                     *(u32x4*)(xb + off + bj * HALF) = w;
;                     s += (v0[0] * v0[0] + v0[1] * v0[1]) + (v0[2] * v0[2] + v0[3] * v0[3]) + (v1[0] * v1[0] + v1[1] * v1[1]) + (v1[2] * v1[2] + v1[3] * v1[3]); }
;                 s += __shfl_xor(s, 16); s += __shfl_xor(s, 32);
;                 if (fq == 0) fx_add(ssout, row, s); }
.LBB0_1989:
	s_or_b64 exec, exec, s[26:27]
	v_add_u32_e32 v64, 0x80, v146
	s_waitcnt lgkmcnt(0)
	v_ashrrev_i32_e32 v65, 31, v64
	v_lshlrev_b64 v[66:67], 11, v[64:65]
	v_lshl_add_u64 v[66:67], s[22:23], 0, v[66:67]
	v_lshl_add_u64 v[74:75], v[144:145], 1, v[66:67]
	global_load_dwordx4 v[66:69], v[74:75], off
	global_load_dwordx4 v[70:73], v[74:75], off offset:256
	s_waitcnt vmcnt(1)
	v_lshlrev_b32_e32 v76, 16, v66
	v_and_b32_e32 v77, 0xffff0000, v66
	v_lshlrev_b32_e32 v66, 16, v67
	v_and_b32_e32 v67, 0xffff0000, v67
	s_waitcnt vmcnt(0)
	v_lshlrev_b32_e32 v80, 16, v70
	v_and_b32_e32 v81, 0xffff0000, v70
	v_lshlrev_b32_e32 v70, 16, v71
	v_and_b32_e32 v71, 0xffff0000, v71
	v_lshlrev_b32_e32 v78, 16, v68
	v_and_b32_e32 v79, 0xffff0000, v68
	v_lshlrev_b32_e32 v68, 16, v69
	v_and_b32_e32 v69, 0xffff0000, v69
	v_lshlrev_b32_e32 v82, 16, v72
	v_and_b32_e32 v83, 0xffff0000, v72
	v_lshlrev_b32_e32 v72, 16, v73
	v_and_b32_e32 v73, 0xffff0000, v73
	v_fma_f32 v62, v62, 0.5, v66
	v_fma_f32 v63, v63, 0.5, v67
	v_fma_f32 v60, v60, 0.5, v76
	v_fma_f32 v61, v61, 0.5, v77
	v_fma_f32 v54, v54, 0.5, v70
	v_fma_f32 v55, v55, 0.5, v71
	v_fma_f32 v52, v52, 0.5, v80
	v_fma_f32 v53, v53, 0.5, v81
	v_fma_f32 v58, v58, 0.5, v68
	v_fma_f32 v59, v59, 0.5, v69
	v_fma_f32 v56, v56, 0.5, v78
	v_fma_f32 v57, v57, 0.5, v79
	v_fma_f32 v66, v50, 0.5, v72
	v_fma_f32 v67, v51, 0.5, v73
	v_fma_f32 v68, v48, 0.5, v82
	v_fma_f32 v69, v49, 0.5, v83
	v_mul_f32_e32 v50, v61, v61
	v_mul_f32_e32 v51, v63, v63
	v_mul_f32_e32 v70, v53, v53
	v_mul_f32_e32 v71, v55, v55
	v_cvt_pk_bf16_f32 v48, v60, v61
	v_mul_f32_e32 v61, v57, v57
	v_mul_f32_e32 v72, v69, v69
	v_fmac_f32_e32 v50, v60, v60
	v_fmac_f32_e32 v51, v62, v62
	v_fmac_f32_e32 v70, v52, v52
	v_fmac_f32_e32 v71, v54, v54
	v_cvt_pk_bf16_f32 v49, v62, v63
	v_mul_f32_e32 v63, v59, v59
	v_mul_f32_e32 v73, v67, v67
	v_fmac_f32_e32 v61, v56, v56
	v_fmac_f32_e32 v72, v68, v68
	v_add_f32_e32 v50, v50, v51
	v_add_f32_e32 v51, v70, v71
	v_fmac_f32_e32 v63, v58, v58
	v_fmac_f32_e32 v73, v66, v66
	v_add_f32_e32 v50, v61, v50
	v_add_f32_e32 v51, v72, v51
	v_add_f32_e32 v50, v63, v50
	v_add_f32_e32 v51, v73, v51
	v_add_f32_e32 v60, v50, v51
	ds_bpermute_b32 v61, v156, v60
	v_cvt_pk_bf16_f32 v50, v56, v57
	v_cvt_pk_bf16_f32 v51, v58, v59
	global_store_dwordx4 v[74:75], v[48:51], off
	s_waitcnt lgkmcnt(0)
	s_nop 0
	v_add_f32_e32 v48, v60, v61
	ds_bpermute_b32 v49, v155, v48
	v_cvt_pk_bf16_f32 v50, v52, v53
	v_cvt_pk_bf16_f32 v51, v54, v55
	v_cvt_pk_bf16_f32 v52, v68, v69
	v_cvt_pk_bf16_f32 v53, v66, v67
	global_store_dwordx4 v[74:75], v[50:53], off offset:256
	s_and_saveexec_b64 s[26:27], s[6:7]
	s_cbranch_execz .LBB0_1991
	s_waitcnt lgkmcnt(0)
	v_add_f32_e32 v48, v48, v49
	v_mul_f32_e32 v48, 0x4f800000, v48
	v_trunc_f32_e32 v48, v48
	v_mul_f32_e64 v49, |v48|, s47
	v_floor_f32_e32 v49, v49
	v_fma_f32 v50, v49, s48, |v48|
	v_cvt_u32_f32_e32 v50, v50
	v_cvt_u32_f32_e32 v49, v49
	v_ashrrev_i32_e32 v51, 31, v48
	v_xor_b32_e32 v48, v50, v51
	v_xor_b32_e32 v49, v49, v51
	v_sub_co_u32_e32 v48, vcc, v48, v51
	s_nop 1
	v_subb_co_u32_e32 v49, vcc, v49, v51, vcc
	v_lshl_add_u64 v[50:51], v[64:65], 3, s[10:11]
	global_atomic_add_x2 v[50:51], v[48:49], off
.LBB0_1991:
	s_or_b64 exec, exec, s[26:27]
	v_add_u32_e32 v48, 0x90, v146
	s_waitcnt lgkmcnt(0)
	v_ashrrev_i32_e32 v49, 31, v48
	v_lshlrev_b64 v[50:51], 11, v[48:49]
	v_lshl_add_u64 v[50:51], s[22:23], 0, v[50:51]
	v_lshl_add_u64 v[58:59], v[144:145], 1, v[50:51]
	global_load_dwordx4 v[50:53], v[58:59], off
	global_load_dwordx4 v[54:57], v[58:59], off offset:256
	s_waitcnt vmcnt(1)
	v_lshlrev_b32_e32 v60, 16, v50
	v_and_b32_e32 v61, 0xffff0000, v50
	v_lshlrev_b32_e32 v50, 16, v51
	v_and_b32_e32 v51, 0xffff0000, v51
	s_waitcnt vmcnt(0)
	v_lshlrev_b32_e32 v64, 16, v54
	v_and_b32_e32 v65, 0xffff0000, v54
	v_lshlrev_b32_e32 v54, 16, v55
	v_and_b32_e32 v55, 0xffff0000, v55
	v_lshlrev_b32_e32 v62, 16, v52
	v_and_b32_e32 v63, 0xffff0000, v52
	v_lshlrev_b32_e32 v52, 16, v53
	v_and_b32_e32 v53, 0xffff0000, v53
	v_lshlrev_b32_e32 v66, 16, v56
	v_and_b32_e32 v67, 0xffff0000, v56
	v_lshlrev_b32_e32 v56, 16, v57
	v_and_b32_e32 v57, 0xffff0000, v57
	v_fma_f32 v46, v46, 0.5, v50
	v_fma_f32 v47, v47, 0.5, v51
	v_fma_f32 v44, v44, 0.5, v60
	v_fma_f32 v45, v45, 0.5, v61
	v_fma_f32 v38, v38, 0.5, v54
	v_fma_f32 v39, v39, 0.5, v55
	v_fma_f32 v36, v36, 0.5, v64
	v_fma_f32 v37, v37, 0.5, v65
	v_fma_f32 v42, v42, 0.5, v52
	v_fma_f32 v43, v43, 0.5, v53
	v_fma_f32 v40, v40, 0.5, v62
	v_fma_f32 v41, v41, 0.5, v63
	v_fma_f32 v50, v34, 0.5, v56
	v_fma_f32 v51, v35, 0.5, v57
	v_fma_f32 v52, v32, 0.5, v66
	v_fma_f32 v53, v33, 0.5, v67
	v_mul_f32_e32 v34, v45, v45
	v_mul_f32_e32 v35, v47, v47
	v_mul_f32_e32 v54, v37, v37
	v_mul_f32_e32 v55, v39, v39
	v_cvt_pk_bf16_f32 v32, v44, v45
	v_mul_f32_e32 v45, v41, v41
	v_mul_f32_e32 v56, v53, v53
	v_fmac_f32_e32 v34, v44, v44
	v_fmac_f32_e32 v35, v46, v46
	v_fmac_f32_e32 v54, v36, v36
	v_fmac_f32_e32 v55, v38, v38
	v_cvt_pk_bf16_f32 v33, v46, v47
	v_mul_f32_e32 v47, v43, v43
	v_mul_f32_e32 v57, v51, v51
	v_fmac_f32_e32 v45, v40, v40
	v_fmac_f32_e32 v56, v52, v52
	v_add_f32_e32 v34, v34, v35
	v_add_f32_e32 v35, v54, v55
	v_fmac_f32_e32 v47, v42, v42
	v_fmac_f32_e32 v57, v50, v50
	v_add_f32_e32 v34, v45, v34
	v_add_f32_e32 v35, v56, v35
	v_add_f32_e32 v34, v47, v34
	v_add_f32_e32 v35, v57, v35
	v_add_f32_e32 v44, v34, v35
	ds_bpermute_b32 v45, v156, v44
	v_cvt_pk_bf16_f32 v34, v40, v41
	v_cvt_pk_bf16_f32 v35, v42, v43
	global_store_dwordx4 v[58:59], v[32:35], off
	s_waitcnt lgkmcnt(0)
	s_nop 0
	v_add_f32_e32 v32, v44, v45
	ds_bpermute_b32 v33, v155, v32
	v_cvt_pk_bf16_f32 v34, v36, v37
	v_cvt_pk_bf16_f32 v35, v38, v39
	v_cvt_pk_bf16_f32 v36, v52, v53
	v_cvt_pk_bf16_f32 v37, v50, v51
	global_store_dwordx4 v[58:59], v[34:37], off offset:256
	s_and_saveexec_b64 s[26:27], s[6:7]
	s_cbranch_execz .LBB0_1993
	s_waitcnt lgkmcnt(0)
	v_add_f32_e32 v32, v32, v33
	v_mul_f32_e32 v32, 0x4f800000, v32
	v_trunc_f32_e32 v32, v32
	v_mul_f32_e64 v33, |v32|, s47
	v_floor_f32_e32 v33, v33
	v_fma_f32 v34, v33, s48, |v32|
	v_cvt_u32_f32_e32 v34, v34
	v_cvt_u32_f32_e32 v33, v33
	v_ashrrev_i32_e32 v35, 31, v32
	v_xor_b32_e32 v32, v34, v35
	v_xor_b32_e32 v33, v33, v35
	v_sub_co_u32_e32 v32, vcc, v32, v35
	s_nop 1
	v_subb_co_u32_e32 v33, vcc, v33, v35, vcc
	v_lshl_add_u64 v[34:35], v[48:49], 3, s[10:11]
	global_atomic_add_x2 v[34:35], v[32:33], off
; __device__ __forceinline__ void fx_add(float* p, size_t idx, float s) { atomicAdd((unsigned long long*)p + idx, (unsigned long long)(long long)(s * 4294967296.0f)); }
; __device__ __forceinline__ unsigned cvtpk(float lo, float hi) { f32x2v_ v = {lo, hi}; bf16x2v_ b = __builtin_convertvector(v, bf16x2v_); return __builtin_bit_cast(unsigned, b); }
;     __device__ __forceinline__ void operator()(const f32x4 (&acc)[2][2][4][2], const Unit& u, int wr, int wc, int fr, int fq) const {
;     ...
;             for (int m = 0; m < 4; ++m) { const int row = row0 + ai * HALF + m * 16; const size_t off = (size_t)row * 1024 + col0; float s = 0.f;
; #pragma unroll
;                 for (int bj = 0; bj < 2; ++bj) { f32x4 a0, a1;
;                     if (xin32) { const float* p = xin32 + off + bj * HALF; a0 = *(const f32x4*)p; a1 = *(const f32x4*)(p + 4); }
;                     else { const u32x4 w = *(const u32x4*)(xb + off + bj * HALF);
;                         a0 = (f32x4){__uint_as_float(w.x << 16), __uint_as_float(w.x & 0xffff0000u), __uint_as_float(w.y << 16), __uint_as_float(w.y & 0xffff0000u)};
;                         a1 = (f32x4){__uint_as_float(w.z << 16), __uint_as_float(w.z & 0xffff0000u), __uint_as_float(w.w << 16), __uint_as_float(w.w & 0xffff0000u)}; }
;                     const f32x4 v0 = a0 + acc[ai][bj][m][0] * alpha, v1 = a1 + acc[ai][bj][m][1] * alpha;
;                     u32x4 w; w.x = cvtpk(v0[0], v0[1]); w.y = cvtpk(v0[2], v0[3]); w.z = cvtpk(v1[0], v1[1]); w.w = cvtpk(v1[2], v1[3]);
;                     *(u32x4*)(xb + off + bj * HALF) = w;
;                     s += (v0[0] * v0[0] + v0[1] * v0[1]) + (v0[2] * v0[2] + v0[3] * v0[3]) + (v1[0] * v1[0] + v1[1] * v1[1]) + (v1[2] * v1[2] + v1[3] * v1[3]); }
;                 s += __shfl_xor(s, 16); s += __shfl_xor(s, 32);
;                 if (fq == 0) fx_add(ssout, row, s); }
.LBB0_1993:
	s_or_b64 exec, exec, s[26:27]
	v_add_u32_e32 v32, 0xa0, v146
	s_waitcnt lgkmcnt(0)
	v_ashrrev_i32_e32 v33, 31, v32
	v_lshlrev_b64 v[34:35], 11, v[32:33]
	v_lshl_add_u64 v[34:35], s[22:23], 0, v[34:35]
	v_lshl_add_u64 v[42:43], v[144:145], 1, v[34:35]
	global_load_dwordx4 v[34:37], v[42:43], off
	global_load_dwordx4 v[38:41], v[42:43], off offset:256
	s_waitcnt vmcnt(1)
	v_lshlrev_b32_e32 v44, 16, v34
	v_and_b32_e32 v45, 0xffff0000, v34
	v_lshlrev_b32_e32 v34, 16, v35
	v_and_b32_e32 v35, 0xffff0000, v35
	s_waitcnt vmcnt(0)
	v_lshlrev_b32_e32 v48, 16, v38
	v_and_b32_e32 v49, 0xffff0000, v38
	v_lshlrev_b32_e32 v38, 16, v39
	v_and_b32_e32 v39, 0xffff0000, v39
	v_lshlrev_b32_e32 v46, 16, v36
	v_and_b32_e32 v47, 0xffff0000, v36
	v_lshlrev_b32_e32 v36, 16, v37
	v_and_b32_e32 v37, 0xffff0000, v37
	v_lshlrev_b32_e32 v50, 16, v40
	v_and_b32_e32 v51, 0xffff0000, v40
	v_lshlrev_b32_e32 v40, 16, v41
	v_and_b32_e32 v41, 0xffff0000, v41
	v_fma_f32 v30, v30, 0.5, v34
	v_fma_f32 v31, v31, 0.5, v35
	v_fma_f32 v28, v28, 0.5, v44
	v_fma_f32 v29, v29, 0.5, v45
	v_fma_f32 v22, v22, 0.5, v38
	v_fma_f32 v23, v23, 0.5, v39
	v_fma_f32 v20, v20, 0.5, v48
	v_fma_f32 v21, v21, 0.5, v49
	v_fma_f32 v26, v26, 0.5, v36
	v_fma_f32 v27, v27, 0.5, v37
	v_fma_f32 v24, v24, 0.5, v46
	v_fma_f32 v25, v25, 0.5, v47
	v_fma_f32 v34, v18, 0.5, v40
	v_fma_f32 v35, v19, 0.5, v41
	v_fma_f32 v36, v16, 0.5, v50
	v_fma_f32 v37, v17, 0.5, v51
	v_mul_f32_e32 v18, v29, v29
	v_mul_f32_e32 v19, v31, v31
	v_mul_f32_e32 v38, v21, v21
	v_mul_f32_e32 v39, v23, v23
	v_cvt_pk_bf16_f32 v16, v28, v29
	v_mul_f32_e32 v29, v25, v25
	v_mul_f32_e32 v40, v37, v37
	v_fmac_f32_e32 v18, v28, v28
	v_fmac_f32_e32 v19, v30, v30
	v_fmac_f32_e32 v38, v20, v20
	v_fmac_f32_e32 v39, v22, v22
	v_cvt_pk_bf16_f32 v17, v30, v31
	v_mul_f32_e32 v31, v27, v27
	v_mul_f32_e32 v41, v35, v35
	v_fmac_f32_e32 v29, v24, v24
	v_fmac_f32_e32 v40, v36, v36
	v_add_f32_e32 v18, v18, v19
	v_add_f32_e32 v19, v38, v39
	v_fmac_f32_e32 v31, v26, v26
	v_fmac_f32_e32 v41, v34, v34
	v_add_f32_e32 v18, v29, v18
	v_add_f32_e32 v19, v40, v19
	v_add_f32_e32 v18, v31, v18
	v_add_f32_e32 v19, v41, v19
	v_add_f32_e32 v28, v18, v19
	ds_bpermute_b32 v29, v156, v28
	v_cvt_pk_bf16_f32 v18, v24, v25
	v_cvt_pk_bf16_f32 v19, v26, v27
	global_store_dwordx4 v[42:43], v[16:19], off
	s_waitcnt lgkmcnt(0)
	s_nop 0
	v_add_f32_e32 v16, v28, v29
	ds_bpermute_b32 v17, v155, v16
	v_cvt_pk_bf16_f32 v18, v20, v21
	v_cvt_pk_bf16_f32 v19, v22, v23
	v_cvt_pk_bf16_f32 v20, v36, v37
	v_cvt_pk_bf16_f32 v21, v34, v35
	global_store_dwordx4 v[42:43], v[18:21], off offset:256
	s_and_saveexec_b64 s[26:27], s[6:7]
	s_cbranch_execz .LBB0_1995
	s_waitcnt lgkmcnt(0)
	v_add_f32_e32 v16, v16, v17
	v_mul_f32_e32 v16, 0x4f800000, v16
	v_trunc_f32_e32 v16, v16
	v_mul_f32_e64 v17, |v16|, s47
	v_floor_f32_e32 v17, v17
	v_fma_f32 v18, v17, s48, |v16|
	v_cvt_u32_f32_e32 v18, v18
	v_cvt_u32_f32_e32 v17, v17
	v_ashrrev_i32_e32 v19, 31, v16
	v_xor_b32_e32 v16, v18, v19
	v_xor_b32_e32 v17, v17, v19
	v_sub_co_u32_e32 v16, vcc, v16, v19
	s_nop 1
	v_subb_co_u32_e32 v17, vcc, v17, v19, vcc
	v_lshl_add_u64 v[18:19], v[32:33], 3, s[10:11]
	global_atomic_add_x2 v[18:19], v[16:17], off
.LBB0_1995:
	s_or_b64 exec, exec, s[26:27]
	v_add_u32_e32 v16, 0xb0, v146
	s_waitcnt lgkmcnt(0)
	v_ashrrev_i32_e32 v17, 31, v16
	v_lshlrev_b64 v[18:19], 11, v[16:17]
	v_lshl_add_u64 v[18:19], s[22:23], 0, v[18:19]
	v_lshl_add_u64 v[26:27], v[144:145], 1, v[18:19]
	global_load_dwordx4 v[18:21], v[26:27], off
	global_load_dwordx4 v[22:25], v[26:27], off offset:256
	s_waitcnt vmcnt(1)
	v_lshlrev_b32_e32 v28, 16, v18
	v_and_b32_e32 v29, 0xffff0000, v18
	v_lshlrev_b32_e32 v18, 16, v19
	v_and_b32_e32 v19, 0xffff0000, v19
	s_waitcnt vmcnt(0)
	v_lshlrev_b32_e32 v32, 16, v22
	v_and_b32_e32 v33, 0xffff0000, v22
	v_lshlrev_b32_e32 v22, 16, v23
	v_and_b32_e32 v23, 0xffff0000, v23
	v_lshlrev_b32_e32 v30, 16, v20
	v_and_b32_e32 v31, 0xffff0000, v20
	v_lshlrev_b32_e32 v20, 16, v21
	v_and_b32_e32 v21, 0xffff0000, v21
	v_lshlrev_b32_e32 v34, 16, v24
	v_and_b32_e32 v35, 0xffff0000, v24
	v_lshlrev_b32_e32 v24, 16, v25
	v_and_b32_e32 v25, 0xffff0000, v25
	v_fma_f32 v14, v14, 0.5, v18
	v_fma_f32 v15, v15, 0.5, v19
	v_fma_f32 v12, v12, 0.5, v28
	v_fma_f32 v13, v13, 0.5, v29
	v_fma_f32 v6, v6, 0.5, v22
	v_fma_f32 v7, v7, 0.5, v23
	v_fma_f32 v4, v4, 0.5, v32
	v_fma_f32 v5, v5, 0.5, v33
	v_fma_f32 v10, v10, 0.5, v20
	v_fma_f32 v11, v11, 0.5, v21
	v_fma_f32 v8, v8, 0.5, v30
	v_fma_f32 v9, v9, 0.5, v31
	v_fma_f32 v18, v2, 0.5, v24
	v_fma_f32 v19, v3, 0.5, v25
	v_fma_f32 v20, v0, 0.5, v34
	v_fma_f32 v21, v1, 0.5, v35
	v_mul_f32_e32 v2, v13, v13
	v_mul_f32_e32 v3, v15, v15
	v_mul_f32_e32 v22, v5, v5
	v_mul_f32_e32 v23, v7, v7
	v_cvt_pk_bf16_f32 v0, v12, v13
	v_mul_f32_e32 v13, v9, v9
	v_mul_f32_e32 v24, v21, v21
	v_fmac_f32_e32 v2, v12, v12
	v_fmac_f32_e32 v3, v14, v14
	v_fmac_f32_e32 v22, v4, v4
	v_fmac_f32_e32 v23, v6, v6
	v_cvt_pk_bf16_f32 v1, v14, v15
	v_mul_f32_e32 v15, v11, v11
	v_mul_f32_e32 v25, v19, v19
	v_fmac_f32_e32 v13, v8, v8
	v_fmac_f32_e32 v24, v20, v20
	v_add_f32_e32 v2, v2, v3
	v_add_f32_e32 v3, v22, v23
	v_fmac_f32_e32 v15, v10, v10
	v_fmac_f32_e32 v25, v18, v18
	v_add_f32_e32 v2, v13, v2
	v_add_f32_e32 v3, v24, v3
	v_add_f32_e32 v2, v15, v2
	v_add_f32_e32 v3, v25, v3
	v_add_f32_e32 v12, v2, v3
	ds_bpermute_b32 v13, v156, v12
	v_cvt_pk_bf16_f32 v2, v8, v9
	v_cvt_pk_bf16_f32 v3, v10, v11
	global_store_dwordx4 v[26:27], v[0:3], off
	s_waitcnt lgkmcnt(0)
	s_nop 0
	v_add_f32_e32 v0, v12, v13
	ds_bpermute_b32 v1, v155, v0
	v_cvt_pk_bf16_f32 v2, v4, v5
	v_cvt_pk_bf16_f32 v3, v6, v7
	v_cvt_pk_bf16_f32 v4, v20, v21
	v_cvt_pk_bf16_f32 v5, v18, v19
	global_store_dwordx4 v[26:27], v[2:5], off offset:256
	s_and_saveexec_b64 s[26:27], s[6:7]
	s_cbranch_execz .LBB0_1997
	s_waitcnt lgkmcnt(0)
	v_add_f32_e32 v0, v0, v1
	v_mul_f32_e32 v0, 0x4f800000, v0
	v_trunc_f32_e32 v0, v0
	v_mul_f32_e64 v1, |v0|, s47
	v_floor_f32_e32 v1, v1
	v_fma_f32 v2, v1, s48, |v0|
	v_cvt_u32_f32_e32 v2, v2
	v_cvt_u32_f32_e32 v1, v1
	v_ashrrev_i32_e32 v3, 31, v0
	v_xor_b32_e32 v0, v2, v3
	v_xor_b32_e32 v1, v1, v3
	v_sub_co_u32_e32 v0, vcc, v0, v3
	s_nop 1
	v_subb_co_u32_e32 v1, vcc, v1, v3, vcc
	v_lshl_add_u64 v[2:3], v[16:17], 3, s[10:11]
	global_atomic_add_x2 v[2:3], v[0:1], off

; __device__ __forceinline__ float bflo(unsigned w) { return __uint_as_float(w << 16); }
; __device__ __forceinline__ float bfhi(unsigned w) { return __uint_as_float(w & 0xffff0000u); }
; __global__ void __launch_bounds__(NWAVES * 64, 2) mk_fwd(Args args) {
;     ...
;     for (int m0 = gwf; m0 < T; m0 += 4 * NGW) {
;         const f32x4* gr = (const f32x4*)(args.in[23]) + lanef; v2u w[4][4];
; #pragma unroll
;         for (int k = 0; k < 4; ++k) { const int m = m0 + k * NGW; if (m < T) { const v2u* xr = (const v2u*)(XB + (size_t)m * D) + lanef;
; #pragma unroll
;             for (int j = 0; j < 4; ++j) w[k][j] = xr[64 * j]; } }
; #pragma unroll
;         for (int k = 0; k < 4; ++k) { const int m = m0 + k * NGW; if (m < T) { f32x4* orow = (f32x4*)(OUT + (size_t)m * D) + lanef; float s = 0.f; f32x4 v[4];
; #pragma unroll
;             for (int j = 0; j < 4; ++j) { v[j] = (f32x4){bflo(w[k][j].x), bfhi(w[k][j].x), bflo(w[k][j].y), bfhi(w[k][j].y)}; s += (v[j].x * v[j].x + v[j].y * v[j].y) + (v[j].z * v[j].z + v[j].w * v[j].w); }
;             s = wave_sum(s); const float rs = 1.0f / sqrtf(s * (1.0f / D) + 1e-6f);
; #pragma unroll
;             for (int j = 0; j < 4; ++j) { const f32x4 g = gr[64 * j]; orow[64 * j] = (f32x4){v[j].x * rs * g.x, v[j].y * rs * g.y, v[j].z * rs * g.z, v[j].w * rs * g.w}; } } }
.LBB0_2062:
	s_waitcnt vmcnt(2)
	v_and_b32_e32 v49, 0xffff0000, v37
	v_and_b32_e32 v48, 0xffff0000, v36
	s_waitcnt vmcnt(1)
	v_and_b32_e32 v53, 0xffff0000, v34
	v_lshlrev_b32_e32 v47, 16, v37
	v_lshlrev_b32_e32 v46, 16, v36
	v_pk_mul_f32 v[36:37], v[48:49], v[48:49]
	v_lshlrev_b32_e32 v52, 16, v34
	v_mul_f32_e32 v34, v53, v53
	v_and_b32_e32 v57, 0xffff0000, v35
	v_fma_f32 v36, v46, v46, v36
	v_fma_f32 v37, v47, v47, v37
	v_fma_f32 v54, v52, v52, v34
	v_fma_f32 v55, v53, v53, v34
	v_lshlrev_b32_e32 v56, 16, v35
	v_mul_f32_e32 v34, v57, v57
	v_pk_add_f32 v[50:51], v[36:37], v[36:37] op_sel:[0,1] op_sel_hi:[1,0]
	v_fma_f32 v58, v56, v56, v34
	v_fma_f32 v59, v57, v57, v34
	global_load_dwordx4 v[34:37], v[0:1], off
	v_and_b32_e32 v61, 0xffff0000, v32
	v_lshlrev_b32_e32 v60, 16, v32
	v_mul_f32_e32 v32, v61, v61
	v_fma_f32 v62, v60, v60, v32
	v_fma_f32 v63, v61, v61, v32
	v_lshlrev_b32_e32 v32, 16, v33
	v_and_b32_e32 v33, 0xffff0000, v33
	v_mul_f32_e32 v64, v33, v33
	v_fma_f32 v65, v33, v33, v64
	v_fma_f32 v64, v32, v32, v64
	s_waitcnt vmcnt(1)
	v_and_b32_e32 v69, 0xffff0000, v30
	v_and_b32_e32 v68, s0, v30
	v_lshlrev_b32_e32 v66, 16, v30
	v_pk_mul_f32 v[70:71], v[68:69], v[68:69]
	v_pk_add_f32 v[62:63], v[62:63], v[64:65]
	v_mov_b32_e32 v51, v71
	v_mul_f32_e32 v63, v66, v66
	v_pk_add_f32 v[50:51], v[62:63], v[50:51]
	v_lshlrev_b32_e32 v62, 16, v31
	v_and_b32_e32 v63, 0xffff0000, v31
	v_pk_mul_f32 v[30:31], v[62:63], v[62:63]
	v_mov_b32_e32 v67, v69
	v_mov_b32_e32 v55, v30
	v_mov_b32_e32 v59, v31
	v_pk_add_f32 v[30:31], v[54:55], v[58:59]
	s_nop 0
	v_pk_add_f32 v[30:31], v[50:51], v[30:31]
	s_nop 0
	v_add_f32_e32 v30, v30, v31
	ds_bpermute_b32 v31, v38, v30
	s_waitcnt lgkmcnt(0)
	v_add_f32_e32 v30, v30, v31
	ds_bpermute_b32 v31, v39, v30
	s_waitcnt lgkmcnt(0)
	v_add_f32_e32 v30, v30, v31
	ds_bpermute_b32 v31, v40, v30
	s_waitcnt lgkmcnt(0)
	v_add_f32_e32 v30, v30, v31
	ds_bpermute_b32 v31, v41, v30
	s_waitcnt lgkmcnt(0)
	v_add_f32_e32 v30, v30, v31
	ds_bpermute_b32 v31, v42, v30
	s_waitcnt lgkmcnt(0)
	v_add_f32_e32 v30, v30, v31
	ds_bpermute_b32 v31, v43, v30
	s_waitcnt lgkmcnt(0)
	v_add_f32_e32 v30, v30, v31
	v_fmamk_f32 v30, v30, 0x3a800000, v44
	v_mul_f32_e32 v31, 0x4f800000, v30
	v_cmp_gt_f32_e32 vcc, s17, v30
	s_nop 1
	v_cndmask_b32_e32 v30, v30, v31, vcc
	v_sqrt_f32_e32 v31, v30
	s_nop 0
	v_add_u32_e32 v50, -1, v31
	v_fma_f32 v51, -v50, v31, v30
	v_cmp_ge_f32_e64 s[0:1], 0, v51
	v_add_u32_e32 v51, 1, v31
	s_nop 0
	v_cndmask_b32_e64 v50, v31, v50, s[0:1]
	v_fma_f32 v31, -v51, v31, v30
	v_cmp_lt_f32_e64 s[0:1], 0, v31
	s_nop 1
	v_cndmask_b32_e64 v31, v50, v51, s[0:1]
	v_mul_f32_e32 v50, 0x37800000, v31
	v_cndmask_b32_e32 v31, v31, v50, vcc
	v_cmp_class_f32_e32 vcc, v30, v45
	s_nop 1
	v_cndmask_b32_e32 v30, v31, v30, vcc
	v_div_scale_f32 v31, s[0:1], v30, v30, 1.0
	v_rcp_f32_e32 v54, v31
	s_lshl_b64 s[0:1], s[2:3], 12
	v_lshl_add_u64 v[50:51], v[4:5], 0, s[0:1]
	v_fma_f32 v55, -v31, v54, 1.0
	v_fmac_f32_e32 v54, v55, v54
	v_div_scale_f32 v55, vcc, 1.0, v30, 1.0
	v_mul_f32_e32 v58, v55, v54
	v_fma_f32 v59, -v31, v58, v55
	v_fmac_f32_e32 v58, v59, v54
	v_fma_f32 v31, -v31, v58, v55
	v_div_fmas_f32 v31, v31, v54, v58
	v_div_fixup_f32 v54, v31, v30, 1.0
	v_pk_mul_f32 v[30:31], v[54:55], v[60:61] op_sel_hi:[0,1]
	v_pk_mul_f32 v[32:33], v[54:55], v[32:33] op_sel_hi:[0,1]
	s_waitcnt vmcnt(0)
	v_pk_mul_f32 v[32:33], v[32:33], v[36:37]
	v_pk_mul_f32 v[30:31], v[30:31], v[34:35]
	global_store_dwordx4 v[50:51], v[30:33], off
	global_load_dwordx4 v[30:33], v[0:1], off offset:1024
	v_mov_b32_e32 v34, v46
	v_mov_b32_e32 v35, v48
	v_mov_b32_e32 v48, v47
	v_pk_mul_f32 v[34:35], v[54:55], v[34:35] op_sel_hi:[0,1]
	v_pk_mul_f32 v[36:37], v[54:55], v[48:49] op_sel_hi:[0,1]
	s_andn2_b64 vcc, exec, s[14:15]
	s_waitcnt vmcnt(0)
	v_pk_mul_f32 v[30:31], v[34:35], v[30:31]
	v_pk_mul_f32 v[32:33], v[36:37], v[32:33]
	global_store_dwordx4 v[50:51], v[30:33], off offset:1024
	global_load_dwordx4 v[30:33], v[0:1], off offset:2048
	v_pk_mul_f32 v[34:35], v[54:55], v[56:57] op_sel_hi:[0,1]
	v_pk_mul_f32 v[36:37], v[54:55], v[52:53] op_sel_hi:[0,1]
	s_waitcnt vmcnt(0)
	v_pk_mul_f32 v[30:31], v[36:37], v[30:31]
	v_pk_mul_f32 v[32:33], v[34:35], v[32:33]
	global_store_dwordx4 v[50:51], v[30:33], off offset:2048
	global_load_dwordx4 v[30:33], v[0:1], off offset:3072
	v_pk_mul_f32 v[34:35], v[54:55], v[62:63] op_sel_hi:[0,1]
	v_pk_mul_f32 v[36:37], v[54:55], v[66:67] op_sel_hi:[0,1]
	s_waitcnt vmcnt(0)
	v_pk_mul_f32 v[30:31], v[36:37], v[30:31]
	v_pk_mul_f32 v[32:33], v[34:35], v[32:33]
	global_store_dwordx4 v[50:51], v[30:33], off offset:3072
	s_cbranch_vccz .LBB0_2065
	s_andn2_b64 vcc, exec, s[10:11]
	s_cbranch_vccz .LBB0_2066

; __device__ __forceinline__ float bflo(unsigned w) { return __uint_as_float(w << 16); }
; __device__ __forceinline__ float bfhi(unsigned w) { return __uint_as_float(w & 0xffff0000u); }
; __global__ void __launch_bounds__(NWAVES * 64, 2) mk_fwd(Args args) {
;     ...
;     for (int m0 = gwf; m0 < T; m0 += 4 * NGW) {
;         const f32x4* gr = (const f32x4*)(args.in[23]) + lanef; v2u w[4][4];
; #pragma unroll
;         for (int k = 0; k < 4; ++k) { const int m = m0 + k * NGW; if (m < T) { const v2u* xr = (const v2u*)(XB + (size_t)m * D) + lanef;
; #pragma unroll
;             for (int j = 0; j < 4; ++j) w[k][j] = xr[64 * j]; } }
; #pragma unroll
;         for (int k = 0; k < 4; ++k) { const int m = m0 + k * NGW; if (m < T) { f32x4* orow = (f32x4*)(OUT + (size_t)m * D) + lanef; float s = 0.f; f32x4 v[4];
; #pragma unroll
;             for (int j = 0; j < 4; ++j) { v[j] = (f32x4){bflo(w[k][j].x), bfhi(w[k][j].x), bflo(w[k][j].y), bfhi(w[k][j].y)}; s += (v[j].x * v[j].x + v[j].y * v[j].y) + (v[j].z * v[j].z + v[j].w * v[j].w); }
;             s = wave_sum(s); const float rs = 1.0f / sqrtf(s * (1.0f / D) + 1e-6f);
; #pragma unroll
;             for (int j = 0; j < 4; ++j) { const f32x4 g = gr[64 * j]; orow[64 * j] = (f32x4){v[j].x * rs * g.x, v[j].y * rs * g.y, v[j].z * rs * g.z, v[j].w * rs * g.w}; } } }
.LBB0_2065:
	v_and_b32_e32 v37, 0xffff0000, v27
	v_and_b32_e32 v36, 0xffff0000, v26
	v_lshlrev_b32_e32 v35, 16, v27
	v_lshlrev_b32_e32 v34, 16, v26
	v_pk_mul_f32 v[30:31], v[36:37], v[36:37]
	v_and_b32_e32 v49, 0xffff0000, v24
	v_fma_f32 v30, v34, v34, v30
	v_fma_f32 v31, v35, v35, v31
	v_lshlrev_b32_e32 v48, 16, v24
	v_pk_add_f32 v[46:47], v[30:31], v[30:31] op_sel:[0,1] op_sel_hi:[1,0]
	v_mul_f32_e32 v30, v49, v49
	v_and_b32_e32 v53, 0xffff0000, v25
	v_fma_f32 v50, v48, v48, v30
	v_fma_f32 v51, v49, v49, v30
	v_lshlrev_b32_e32 v52, 16, v25
	v_mul_f32_e32 v30, v53, v53
	v_fma_f32 v54, v52, v52, v30
	v_fma_f32 v55, v53, v53, v30
	global_load_dwordx4 v[30:33], v[0:1], off
	v_and_b32_e32 v57, 0xffff0000, v28
	v_and_b32_e32 v61, 0xffff0000, v29
	v_lshlrev_b32_e32 v56, 16, v28
	v_mul_f32_e32 v58, v57, v57
	v_lshlrev_b32_e32 v60, 16, v29
	v_mul_f32_e32 v62, v61, v61
	v_fma_f32 v59, v57, v57, v58
	v_fma_f32 v58, v56, v56, v58
	v_fma_f32 v63, v61, v61, v62
	v_fma_f32 v62, v60, v60, v62
	v_and_b32_e32 v67, 0xffff0000, v22
	v_and_b32_e32 v66, s0, v22
	v_lshlrev_b32_e32 v64, 16, v22
	v_pk_mul_f32 v[68:69], v[66:67], v[66:67]
	v_pk_add_f32 v[58:59], v[58:59], v[62:63]
	v_mov_b32_e32 v47, v69
	v_mul_f32_e32 v59, v64, v64
	v_pk_add_f32 v[46:47], v[58:59], v[46:47]
	v_lshlrev_b32_e32 v58, 16, v23
	v_and_b32_e32 v59, 0xffff0000, v23
	v_pk_mul_f32 v[62:63], v[58:59], v[58:59]
	s_ashr_i32 s13, s12, 31
	v_mov_b32_e32 v51, v62
	v_mov_b32_e32 v55, v63
	v_pk_add_f32 v[50:51], v[50:51], v[54:55]
	v_mov_b32_e32 v65, v67
	v_pk_add_f32 v[46:47], v[46:47], v[50:51]
	s_nop 0
	v_add_f32_e32 v46, v46, v47
	ds_bpermute_b32 v47, v38, v46
	s_waitcnt lgkmcnt(0)
	v_add_f32_e32 v46, v46, v47
	ds_bpermute_b32 v47, v39, v46
	s_waitcnt lgkmcnt(0)
	v_add_f32_e32 v46, v46, v47
	ds_bpermute_b32 v47, v40, v46
	s_waitcnt lgkmcnt(0)
	v_add_f32_e32 v46, v46, v47
	ds_bpermute_b32 v47, v41, v46
	s_waitcnt lgkmcnt(0)
	v_add_f32_e32 v46, v46, v47
	ds_bpermute_b32 v47, v42, v46
	s_waitcnt lgkmcnt(0)
	v_add_f32_e32 v46, v46, v47
	ds_bpermute_b32 v47, v43, v46
	s_waitcnt lgkmcnt(0)
	v_add_f32_e32 v46, v46, v47
	v_fmamk_f32 v46, v46, 0x3a800000, v44
	v_mul_f32_e32 v47, 0x4f800000, v46
	v_cmp_gt_f32_e32 vcc, s17, v46
	s_nop 1
	v_cndmask_b32_e32 v46, v46, v47, vcc
	v_sqrt_f32_e32 v47, v46
	s_nop 0
	v_add_u32_e32 v50, -1, v47
	v_fma_f32 v51, -v50, v47, v46
	v_cmp_ge_f32_e64 s[0:1], 0, v51
	v_add_u32_e32 v51, 1, v47
	s_nop 0
	v_cndmask_b32_e64 v50, v47, v50, s[0:1]
	v_fma_f32 v47, -v51, v47, v46
	v_cmp_lt_f32_e64 s[0:1], 0, v47
	s_nop 1
	v_cndmask_b32_e64 v47, v50, v51, s[0:1]
	v_mul_f32_e32 v50, 0x37800000, v47
	v_cndmask_b32_e32 v47, v47, v50, vcc
	v_cmp_class_f32_e32 vcc, v46, v45
	s_nop 1
	v_cndmask_b32_e32 v50, v47, v46, vcc
	v_div_scale_f32 v51, s[0:1], v50, v50, 1.0
	v_rcp_f32_e32 v54, v51
	s_lshl_b64 s[0:1], s[12:13], 12
	v_lshl_add_u64 v[46:47], v[4:5], 0, s[0:1]
	v_fma_f32 v55, -v51, v54, 1.0
	v_fmac_f32_e32 v54, v55, v54
	v_div_scale_f32 v55, vcc, 1.0, v50, 1.0
	v_mul_f32_e32 v62, v55, v54
	v_fma_f32 v63, -v51, v62, v55
	v_fmac_f32_e32 v62, v63, v54
	v_fma_f32 v51, -v51, v62, v55
	v_div_fmas_f32 v51, v51, v54, v62
	v_div_fixup_f32 v50, v51, v50, 1.0
	v_pk_mul_f32 v[54:55], v[50:51], v[56:57] op_sel_hi:[0,1]
	v_pk_mul_f32 v[56:57], v[50:51], v[60:61] op_sel_hi:[0,1]
	s_waitcnt vmcnt(0)
	v_pk_mul_f32 v[32:33], v[56:57], v[32:33]
	v_pk_mul_f32 v[30:31], v[54:55], v[30:31]
	global_store_dwordx4 v[46:47], v[30:33], off
	global_load_dwordx4 v[30:33], v[0:1], off offset:1024
	v_mov_b32_e32 v54, v34
	v_mov_b32_e32 v55, v36
	v_mov_b32_e32 v36, v35
	v_pk_mul_f32 v[34:35], v[50:51], v[54:55] op_sel_hi:[0,1]
	v_pk_mul_f32 v[36:37], v[50:51], v[36:37] op_sel_hi:[0,1]
	s_waitcnt vmcnt(0)
	v_pk_mul_f32 v[30:31], v[34:35], v[30:31]
	v_pk_mul_f32 v[32:33], v[36:37], v[32:33]
	global_store_dwordx4 v[46:47], v[30:33], off offset:1024
	global_load_dwordx4 v[30:33], v[0:1], off offset:2048
	v_pk_mul_f32 v[34:35], v[50:51], v[52:53] op_sel_hi:[0,1]
	v_pk_mul_f32 v[36:37], v[50:51], v[48:49] op_sel_hi:[0,1]
	s_waitcnt vmcnt(0)
	v_pk_mul_f32 v[30:31], v[36:37], v[30:31]
	v_pk_mul_f32 v[32:33], v[34:35], v[32:33]
	global_store_dwordx4 v[46:47], v[30:33], off offset:2048
	global_load_dwordx4 v[30:33], v[0:1], off offset:3072
	v_pk_mul_f32 v[34:35], v[50:51], v[58:59] op_sel_hi:[0,1]
	v_pk_mul_f32 v[36:37], v[50:51], v[64:65] op_sel_hi:[0,1]
	s_waitcnt vmcnt(0)
	v_pk_mul_f32 v[30:31], v[36:37], v[30:31]
	v_pk_mul_f32 v[32:33], v[34:35], v[32:33]
	global_store_dwordx4 v[46:47], v[30:33], off offset:3072
	s_andn2_b64 vcc, exec, s[10:11]
	s_cbranch_vccnz .LBB0_2064
; __device__ __forceinline__ float bflo(unsigned w) { return __uint_as_float(w << 16); }
; __device__ __forceinline__ float bfhi(unsigned w) { return __uint_as_float(w & 0xffff0000u); }
; __global__ void __launch_bounds__(NWAVES * 64, 2) mk_fwd(Args args) {
;     ...
;     for (int m0 = gwf; m0 < T; m0 += 4 * NGW) {
;         const f32x4* gr = (const f32x4*)(args.in[23]) + lanef; v2u w[4][4];
; #pragma unroll
;         for (int k = 0; k < 4; ++k) { const int m = m0 + k * NGW; if (m < T) { const v2u* xr = (const v2u*)(XB + (size_t)m * D) + lanef;
; #pragma unroll
;             for (int j = 0; j < 4; ++j) w[k][j] = xr[64 * j]; } }
; #pragma unroll
;         for (int k = 0; k < 4; ++k) { const int m = m0 + k * NGW; if (m < T) { f32x4* orow = (f32x4*)(OUT + (size_t)m * D) + lanef; float s = 0.f; f32x4 v[4];
; #pragma unroll
;             for (int j = 0; j < 4; ++j) { v[j] = (f32x4){bflo(w[k][j].x), bfhi(w[k][j].x), bflo(w[k][j].y), bfhi(w[k][j].y)}; s += (v[j].x * v[j].x + v[j].y * v[j].y) + (v[j].z * v[j].z + v[j].w * v[j].w); }
;             s = wave_sum(s); const float rs = 1.0f / sqrtf(s * (1.0f / D) + 1e-6f);
; #pragma unroll
;             for (int j = 0; j < 4; ++j) { const f32x4 g = gr[64 * j]; orow[64 * j] = (f32x4){v[j].x * rs * g.x, v[j].y * rs * g.y, v[j].z * rs * g.z, v[j].w * rs * g.w}; } } }
.LBB0_2066:
	v_and_b32_e32 v37, 0xffff0000, v19
	v_and_b32_e32 v36, 0xffff0000, v18
	v_lshlrev_b32_e32 v35, 16, v19
	v_lshlrev_b32_e32 v34, 16, v18
	v_pk_mul_f32 v[30:31], v[36:37], v[36:37]
	v_and_b32_e32 v49, 0xffff0000, v16
	v_fma_f32 v30, v34, v34, v30
	v_fma_f32 v31, v35, v35, v31
	v_lshlrev_b32_e32 v48, 16, v16
	v_pk_add_f32 v[46:47], v[30:31], v[30:31] op_sel:[0,1] op_sel_hi:[1,0]
	v_mul_f32_e32 v30, v49, v49
	v_and_b32_e32 v53, 0xffff0000, v17
	v_fma_f32 v50, v48, v48, v30
	v_fma_f32 v51, v49, v49, v30
	v_lshlrev_b32_e32 v52, 16, v17
	v_mul_f32_e32 v30, v53, v53
	v_fma_f32 v54, v52, v52, v30
	v_fma_f32 v55, v53, v53, v30
	global_load_dwordx4 v[30:33], v[0:1], off
	v_and_b32_e32 v57, 0xffff0000, v20
	v_and_b32_e32 v61, 0xffff0000, v21
	v_lshlrev_b32_e32 v56, 16, v20
	v_mul_f32_e32 v58, v57, v57
	v_lshlrev_b32_e32 v60, 16, v21
	v_mul_f32_e32 v62, v61, v61
	v_fma_f32 v59, v57, v57, v58
	v_fma_f32 v58, v56, v56, v58
	v_fma_f32 v63, v61, v61, v62
	v_fma_f32 v62, v60, v60, v62
	v_and_b32_e32 v67, 0xffff0000, v14
	v_and_b32_e32 v66, s0, v14
	v_lshlrev_b32_e32 v64, 16, v14
	v_pk_mul_f32 v[68:69], v[66:67], v[66:67]
	v_pk_add_f32 v[58:59], v[58:59], v[62:63]
	v_mov_b32_e32 v47, v69
	v_mul_f32_e32 v59, v64, v64
	v_pk_add_f32 v[46:47], v[58:59], v[46:47]
	v_lshlrev_b32_e32 v58, 16, v15
	v_and_b32_e32 v59, 0xffff0000, v15
	v_pk_mul_f32 v[62:63], v[58:59], v[58:59]
	s_ashr_i32 s9, s8, 31
	v_mov_b32_e32 v51, v62
	v_mov_b32_e32 v55, v63
	v_pk_add_f32 v[50:51], v[50:51], v[54:55]
	v_mov_b32_e32 v65, v67
	v_pk_add_f32 v[46:47], v[46:47], v[50:51]
	s_nop 0
	v_add_f32_e32 v46, v46, v47
	ds_bpermute_b32 v47, v38, v46
	s_waitcnt lgkmcnt(0)
	v_add_f32_e32 v46, v46, v47
	ds_bpermute_b32 v47, v39, v46
	s_waitcnt lgkmcnt(0)
	v_add_f32_e32 v46, v46, v47
	ds_bpermute_b32 v47, v40, v46
	s_waitcnt lgkmcnt(0)
	v_add_f32_e32 v46, v46, v47
	ds_bpermute_b32 v47, v41, v46
	s_waitcnt lgkmcnt(0)
	v_add_f32_e32 v46, v46, v47
	ds_bpermute_b32 v47, v42, v46
	s_waitcnt lgkmcnt(0)
	v_add_f32_e32 v46, v46, v47
	ds_bpermute_b32 v47, v43, v46
	s_waitcnt lgkmcnt(0)
	v_add_f32_e32 v46, v46, v47
	v_fmamk_f32 v46, v46, 0x3a800000, v44
	v_mul_f32_e32 v47, 0x4f800000, v46
	v_cmp_gt_f32_e32 vcc, s17, v46
	s_nop 1
	v_cndmask_b32_e32 v46, v46, v47, vcc
	v_sqrt_f32_e32 v47, v46
	s_nop 0
	v_add_u32_e32 v50, -1, v47
	v_fma_f32 v51, -v50, v47, v46
	v_cmp_ge_f32_e64 s[0:1], 0, v51
	v_add_u32_e32 v51, 1, v47
	s_nop 0
	v_cndmask_b32_e64 v50, v47, v50, s[0:1]
	v_fma_f32 v47, -v51, v47, v46
	v_cmp_lt_f32_e64 s[0:1], 0, v47
	s_nop 1
	v_cndmask_b32_e64 v47, v50, v51, s[0:1]
	v_mul_f32_e32 v50, 0x37800000, v47
	v_cndmask_b32_e32 v47, v47, v50, vcc
	v_cmp_class_f32_e32 vcc, v46, v45
	s_nop 1
	v_cndmask_b32_e32 v50, v47, v46, vcc
	v_div_scale_f32 v51, s[0:1], v50, v50, 1.0
	v_rcp_f32_e32 v54, v51
	s_lshl_b64 s[0:1], s[8:9], 12
	v_lshl_add_u64 v[46:47], v[4:5], 0, s[0:1]
	v_fma_f32 v55, -v51, v54, 1.0
	v_fmac_f32_e32 v54, v55, v54
	v_div_scale_f32 v55, vcc, 1.0, v50, 1.0
	v_mul_f32_e32 v62, v55, v54
	v_fma_f32 v63, -v51, v62, v55
	v_fmac_f32_e32 v62, v63, v54
	v_fma_f32 v51, -v51, v62, v55
	v_div_fmas_f32 v51, v51, v54, v62
	v_div_fixup_f32 v50, v51, v50, 1.0
	v_pk_mul_f32 v[54:55], v[50:51], v[56:57] op_sel_hi:[0,1]
	v_pk_mul_f32 v[56:57], v[50:51], v[60:61] op_sel_hi:[0,1]
	s_waitcnt vmcnt(0)
	v_pk_mul_f32 v[32:33], v[56:57], v[32:33]
	v_pk_mul_f32 v[30:31], v[54:55], v[30:31]
	global_store_dwordx4 v[46:47], v[30:33], off
	global_load_dwordx4 v[30:33], v[0:1], off offset:1024
	v_mov_b32_e32 v54, v34
	v_mov_b32_e32 v55, v36
	v_mov_b32_e32 v36, v35
	v_pk_mul_f32 v[34:35], v[50:51], v[54:55] op_sel_hi:[0,1]
	v_pk_mul_f32 v[36:37], v[50:51], v[36:37] op_sel_hi:[0,1]
	s_waitcnt vmcnt(0)
	v_pk_mul_f32 v[30:31], v[34:35], v[30:31]
	v_pk_mul_f32 v[32:33], v[36:37], v[32:33]
	global_store_dwordx4 v[46:47], v[30:33], off offset:1024
	global_load_dwordx4 v[30:33], v[0:1], off offset:2048
	v_pk_mul_f32 v[34:35], v[50:51], v[52:53] op_sel_hi:[0,1]
	v_pk_mul_f32 v[36:37], v[50:51], v[48:49] op_sel_hi:[0,1]
	s_waitcnt vmcnt(0)
	v_pk_mul_f32 v[30:31], v[36:37], v[30:31]
	v_pk_mul_f32 v[32:33], v[34:35], v[32:33]
	global_store_dwordx4 v[46:47], v[30:33], off offset:2048
	global_load_dwordx4 v[30:33], v[0:1], off offset:3072
	v_pk_mul_f32 v[34:35], v[50:51], v[58:59] op_sel_hi:[0,1]
	v_pk_mul_f32 v[36:37], v[50:51], v[64:65] op_sel_hi:[0,1]
	s_waitcnt vmcnt(0)
	v_pk_mul_f32 v[30:31], v[36:37], v[30:31]
	v_pk_mul_f32 v[32:33], v[34:35], v[32:33]
	global_store_dwordx4 v[46:47], v[30:33], off offset:3072
	s_andn2_b64 vcc, exec, s[6:7]
	s_cbranch_vccnz .LBB0_2055
; __device__ __forceinline__ float bflo(unsigned w) { return __uint_as_float(w << 16); }
; __device__ __forceinline__ float bfhi(unsigned w) { return __uint_as_float(w & 0xffff0000u); }
; __global__ void __launch_bounds__(NWAVES * 64, 2) mk_fwd(Args args) {
;     ...
;     for (int m0 = gwf; m0 < T; m0 += 4 * NGW) {
;         const f32x4* gr = (const f32x4*)(args.in[23]) + lanef; v2u w[4][4];
; #pragma unroll
;         for (int k = 0; k < 4; ++k) { const int m = m0 + k * NGW; if (m < T) { const v2u* xr = (const v2u*)(XB + (size_t)m * D) + lanef;
; #pragma unroll
;             for (int j = 0; j < 4; ++j) w[k][j] = xr[64 * j]; } }
; #pragma unroll
;         for (int k = 0; k < 4; ++k) { const int m = m0 + k * NGW; if (m < T) { f32x4* orow = (f32x4*)(OUT + (size_t)m * D) + lanef; float s = 0.f; f32x4 v[4];
; #pragma unroll
;             for (int j = 0; j < 4; ++j) { v[j] = (f32x4){bflo(w[k][j].x), bfhi(w[k][j].x), bflo(w[k][j].y), bfhi(w[k][j].y)}; s += (v[j].x * v[j].x + v[j].y * v[j].y) + (v[j].z * v[j].z + v[j].w * v[j].w); }
;             s = wave_sum(s); const float rs = 1.0f / sqrtf(s * (1.0f / D) + 1e-6f);
; #pragma unroll
;             for (int j = 0; j < 4; ++j) { const f32x4 g = gr[64 * j]; orow[64 * j] = (f32x4){v[j].x * rs * g.x, v[j].y * rs * g.y, v[j].z * rs * g.z, v[j].w * rs * g.w}; } } }
.LBB0_2067:
	v_and_b32_e32 v37, 0xffff0000, v11
	v_and_b32_e32 v36, 0xffff0000, v10
	v_lshlrev_b32_e32 v35, 16, v11
	v_lshlrev_b32_e32 v34, 16, v10
	v_pk_mul_f32 v[30:31], v[36:37], v[36:37]
	v_and_b32_e32 v49, 0xffff0000, v8
	v_fma_f32 v30, v34, v34, v30
	v_fma_f32 v31, v35, v35, v31
	v_lshlrev_b32_e32 v48, 16, v8
	v_pk_add_f32 v[46:47], v[30:31], v[30:31] op_sel:[0,1] op_sel_hi:[1,0]
	v_mul_f32_e32 v30, v49, v49
	v_and_b32_e32 v53, 0xffff0000, v9
	v_fma_f32 v50, v48, v48, v30
	v_fma_f32 v51, v49, v49, v30
	v_lshlrev_b32_e32 v52, 16, v9
	v_mul_f32_e32 v30, v53, v53
	v_fma_f32 v54, v52, v52, v30
	v_fma_f32 v55, v53, v53, v30
	global_load_dwordx4 v[30:33], v[0:1], off
	v_and_b32_e32 v57, 0xffff0000, v12
	v_and_b32_e32 v61, 0xffff0000, v13
	v_lshlrev_b32_e32 v56, 16, v12
	v_mul_f32_e32 v58, v57, v57
	v_lshlrev_b32_e32 v60, 16, v13
	v_mul_f32_e32 v62, v61, v61
	v_fma_f32 v59, v57, v57, v58
	v_fma_f32 v58, v56, v56, v58
	v_fma_f32 v63, v61, v61, v62
	v_fma_f32 v62, v60, v60, v62
	v_and_b32_e32 v67, 0xffff0000, v6
	v_and_b32_e32 v66, s0, v6
	v_lshlrev_b32_e32 v64, 16, v6
	v_pk_mul_f32 v[68:69], v[66:67], v[66:67]
	v_pk_add_f32 v[58:59], v[58:59], v[62:63]
	v_mov_b32_e32 v47, v69
	v_mul_f32_e32 v59, v64, v64
	v_pk_add_f32 v[46:47], v[58:59], v[46:47]
	v_lshlrev_b32_e32 v58, 16, v7
	v_and_b32_e32 v59, 0xffff0000, v7
	v_pk_mul_f32 v[62:63], v[58:59], v[58:59]
	s_ashr_i32 s5, s4, 31
	v_mov_b32_e32 v51, v62
	v_mov_b32_e32 v55, v63
	v_pk_add_f32 v[50:51], v[50:51], v[54:55]
	v_mov_b32_e32 v65, v67
	v_pk_add_f32 v[46:47], v[46:47], v[50:51]
	s_nop 0
	v_add_f32_e32 v46, v46, v47
	ds_bpermute_b32 v47, v38, v46
	s_waitcnt lgkmcnt(0)
	v_add_f32_e32 v46, v46, v47
	ds_bpermute_b32 v47, v39, v46
	s_waitcnt lgkmcnt(0)
	v_add_f32_e32 v46, v46, v47
	ds_bpermute_b32 v47, v40, v46
	s_waitcnt lgkmcnt(0)
	v_add_f32_e32 v46, v46, v47
	ds_bpermute_b32 v47, v41, v46
	s_waitcnt lgkmcnt(0)
	v_add_f32_e32 v46, v46, v47
	ds_bpermute_b32 v47, v42, v46
	s_waitcnt lgkmcnt(0)
	v_add_f32_e32 v46, v46, v47
	ds_bpermute_b32 v47, v43, v46
	s_waitcnt lgkmcnt(0)
	v_add_f32_e32 v46, v46, v47
	v_fmamk_f32 v46, v46, 0x3a800000, v44
	v_mul_f32_e32 v47, 0x4f800000, v46
	v_cmp_gt_f32_e32 vcc, s17, v46
	s_nop 1
	v_cndmask_b32_e32 v46, v46, v47, vcc
	v_sqrt_f32_e32 v47, v46
	s_nop 0
	v_add_u32_e32 v50, -1, v47
	v_fma_f32 v51, -v50, v47, v46
	v_cmp_ge_f32_e64 s[0:1], 0, v51
	v_add_u32_e32 v51, 1, v47
	s_nop 0
	v_cndmask_b32_e64 v50, v47, v50, s[0:1]
	v_fma_f32 v47, -v51, v47, v46
	v_cmp_lt_f32_e64 s[0:1], 0, v47
	s_nop 1
	v_cndmask_b32_e64 v47, v50, v51, s[0:1]
	v_mul_f32_e32 v50, 0x37800000, v47
	v_cndmask_b32_e32 v47, v47, v50, vcc
	v_cmp_class_f32_e32 vcc, v46, v45
	s_nop 1
	v_cndmask_b32_e32 v50, v47, v46, vcc
	v_div_scale_f32 v51, s[0:1], v50, v50, 1.0
	v_rcp_f32_e32 v54, v51
	s_lshl_b64 s[0:1], s[4:5], 12
	v_lshl_add_u64 v[46:47], v[4:5], 0, s[0:1]
	v_fma_f32 v55, -v51, v54, 1.0
	v_fmac_f32_e32 v54, v55, v54
	v_div_scale_f32 v55, vcc, 1.0, v50, 1.0
	v_mul_f32_e32 v62, v55, v54
	v_fma_f32 v63, -v51, v62, v55
	v_fmac_f32_e32 v62, v63, v54
	v_fma_f32 v51, -v51, v62, v55
	v_div_fmas_f32 v51, v51, v54, v62
	v_div_fixup_f32 v50, v51, v50, 1.0
	v_pk_mul_f32 v[54:55], v[50:51], v[56:57] op_sel_hi:[0,1]
	v_pk_mul_f32 v[56:57], v[50:51], v[60:61] op_sel_hi:[0,1]
	s_waitcnt vmcnt(0)
	v_pk_mul_f32 v[32:33], v[56:57], v[32:33]
	v_pk_mul_f32 v[30:31], v[54:55], v[30:31]
	global_store_dwordx4 v[46:47], v[30:33], off
	global_load_dwordx4 v[30:33], v[0:1], off offset:1024
	v_mov_b32_e32 v54, v34
	v_mov_b32_e32 v55, v36
	v_mov_b32_e32 v36, v35
	v_pk_mul_f32 v[34:35], v[50:51], v[54:55] op_sel_hi:[0,1]
	v_pk_mul_f32 v[36:37], v[50:51], v[36:37] op_sel_hi:[0,1]
	s_waitcnt vmcnt(0)
	v_pk_mul_f32 v[30:31], v[34:35], v[30:31]
	v_pk_mul_f32 v[32:33], v[36:37], v[32:33]
	global_store_dwordx4 v[46:47], v[30:33], off offset:1024
	global_load_dwordx4 v[30:33], v[0:1], off offset:2048
	v_pk_mul_f32 v[34:35], v[50:51], v[52:53] op_sel_hi:[0,1]
	v_pk_mul_f32 v[36:37], v[50:51], v[48:49] op_sel_hi:[0,1]
	s_waitcnt vmcnt(0)
	v_pk_mul_f32 v[30:31], v[36:37], v[30:31]
	v_pk_mul_f32 v[32:33], v[34:35], v[32:33]
	global_store_dwordx4 v[46:47], v[30:33], off offset:2048
	global_load_dwordx4 v[30:33], v[0:1], off offset:3072
	v_pk_mul_f32 v[34:35], v[50:51], v[58:59] op_sel_hi:[0,1]
	v_pk_mul_f32 v[36:37], v[50:51], v[64:65] op_sel_hi:[0,1]
	s_waitcnt vmcnt(0)
	v_pk_mul_f32 v[30:31], v[36:37], v[30:31]
	v_pk_mul_f32 v[32:33], v[34:35], v[32:33]
	global_store_dwordx4 v[46:47], v[30:33], off offset:3072
	s_branch .LBB0_2055
